# waitcnt placement: the 60 redundant post-barrier s_waitcnt lgkmcnt(0) at the heads of the K-loop MFMA segments deleted (the same wait already sits directly before the barrier)
# speedup vs baseline: 1.0048x; 1.0048x over previous
.LBB0_143:
	ds_read_b128 v[168:171], v163
	ds_read_b128 v[172:175], v163 offset:1024
	ds_read_b128 v[176:179], v163 offset:2048
	ds_read_b128 v[180:183], v163 offset:3072
	ds_read_b128 v[184:187], v164
	ds_read_b128 v[188:191], v164 offset:1024
	ds_read_b128 v[192:195], v164 offset:2048
	ds_read_b128 v[196:199], v164 offset:3072
	s_add_u32 s26, s24, 0xfff80080
	s_addc_u32 s27, s25, -1
	s_cmp_eq_u32 s62, 28
	s_cselect_b32 s31, s15, s27
	s_cselect_b32 s30, s23, s26
	s_cselect_b32 s27, s13, s61
	s_cselect_b32 s26, s59, s60
	v_lshl_add_u64 v[154:155], s[24:25], 0, v[144:145]
	s_add_i32 m0, s43, 0xc000
	ds_read_b128 v[200:203], v165
	ds_read_b128 v[204:207], v165 offset:1024
	ds_read_b128 v[208:211], v165 offset:2048
	ds_read_b128 v[212:215], v165 offset:3072
	ds_read_b128 v[216:219], v165 offset:4096
	ds_read_b128 v[220:223], v165 offset:5120
	ds_read_b128 v[224:227], v165 offset:6144
	ds_read_b128 v[228:231], v165 offset:7168
	global_load_lds_dwordx4 v[154:155], off
	v_lshl_add_u64 v[154:155], s[24:25], 0, v[142:143]
	s_add_i32 m0, s43, 0xe000
	s_nop 0
	global_load_lds_dwordx4 v[154:155], off
	s_waitcnt vmcnt(8)
	s_waitcnt lgkmcnt(0)
	s_barrier
	s_setprio 1
	v_mfma_f32_16x16x32_bf16 v[126:129], v[168:171], v[200:203], v[126:129]
	v_mfma_f32_16x16x32_bf16 v[122:125], v[176:179], v[200:203], v[122:125]
	v_mfma_f32_16x16x32_bf16 v[114:117], v[168:171], v[208:211], v[114:117]
	v_mfma_f32_16x16x32_bf16 v[106:109], v[176:179], v[208:211], v[106:109]
	v_mfma_f32_16x16x32_bf16 v[98:101], v[168:171], v[216:219], v[98:101]
	v_mfma_f32_16x16x32_bf16 v[90:93], v[176:179], v[216:219], v[90:93]
	v_mfma_f32_16x16x32_bf16 v[82:85], v[168:171], v[224:227], v[82:85]
	v_mfma_f32_16x16x32_bf16 v[74:77], v[176:179], v[224:227], v[74:77]
	v_mfma_f32_16x16x32_bf16 v[126:129], v[172:175], v[204:207], v[126:129]
	v_mfma_f32_16x16x32_bf16 v[122:125], v[180:183], v[204:207], v[122:125]
	v_mfma_f32_16x16x32_bf16 v[114:117], v[172:175], v[212:215], v[114:117]
	v_mfma_f32_16x16x32_bf16 v[106:109], v[180:183], v[212:215], v[106:109]
	v_mfma_f32_16x16x32_bf16 v[98:101], v[172:175], v[220:223], v[98:101]
	v_mfma_f32_16x16x32_bf16 v[90:93], v[180:183], v[220:223], v[90:93]
	v_mfma_f32_16x16x32_bf16 v[82:85], v[172:175], v[228:231], v[82:85]
	v_mfma_f32_16x16x32_bf16 v[74:77], v[180:183], v[228:231], v[74:77]
	s_setprio 0
	s_setprio 1
	v_mfma_f32_16x16x32_bf16 v[118:121], v[184:187], v[200:203], v[118:121]
	v_mfma_f32_16x16x32_bf16 v[110:113], v[192:195], v[200:203], v[110:113]
	v_mfma_f32_16x16x32_bf16 v[102:105], v[184:187], v[208:211], v[102:105]
	v_mfma_f32_16x16x32_bf16 v[94:97], v[192:195], v[208:211], v[94:97]
	v_mfma_f32_16x16x32_bf16 v[86:89], v[184:187], v[216:219], v[86:89]
	v_mfma_f32_16x16x32_bf16 v[78:81], v[192:195], v[216:219], v[78:81]
	v_mfma_f32_16x16x32_bf16 v[70:73], v[184:187], v[224:227], v[70:73]
	v_mfma_f32_16x16x32_bf16 v[66:69], v[192:195], v[224:227], v[66:69]
	v_mfma_f32_16x16x32_bf16 v[118:121], v[188:191], v[204:207], v[118:121]
	v_mfma_f32_16x16x32_bf16 v[110:113], v[196:199], v[204:207], v[110:113]
	v_mfma_f32_16x16x32_bf16 v[102:105], v[188:191], v[212:215], v[102:105]
	v_mfma_f32_16x16x32_bf16 v[94:97], v[196:199], v[212:215], v[94:97]
	v_mfma_f32_16x16x32_bf16 v[86:89], v[188:191], v[220:223], v[86:89]
	v_mfma_f32_16x16x32_bf16 v[78:81], v[196:199], v[220:223], v[78:81]
	v_mfma_f32_16x16x32_bf16 v[70:73], v[188:191], v[228:231], v[70:73]
	v_mfma_f32_16x16x32_bf16 v[66:69], v[196:199], v[228:231], v[66:69]
	s_setprio 0
	s_barrier
	s_add_i32 s63, s55, s42
	v_lshl_add_u64 v[154:155], s[26:27], 0, v[132:133]
	s_mov_b32 m0, s63
	ds_read_b128 v[200:203], v165 offset:16384
	ds_read_b128 v[204:207], v165 offset:17408
	ds_read_b128 v[208:211], v165 offset:18432
	ds_read_b128 v[212:215], v165 offset:19456
	ds_read_b128 v[216:219], v165 offset:20480
	ds_read_b128 v[220:223], v165 offset:21504
	ds_read_b128 v[224:227], v165 offset:22528
	ds_read_b128 v[228:231], v165 offset:23552
	global_load_lds_dwordx4 v[154:155], off
	s_add_i32 m0, s63, 0x2000
	s_add_u32 s64, s26, 0x80000
	v_lshl_add_u64 v[232:233], s[26:27], 0, v[136:137]
	s_addc_u32 s65, s27, 0
	s_add_i32 s63, s56, s42
	global_load_lds_dwordx4 v[232:233], off
	v_lshl_add_u64 v[234:235], s[64:65], 0, v[132:133]
	s_mov_b32 m0, s63
	v_lshl_add_u64 v[236:237], s[30:31], 0, v[134:135]
	global_load_lds_dwordx4 v[234:235], off
	v_lshl_add_u64 v[234:235], s[64:65], 0, v[136:137]
	s_add_i32 m0, s63, 0x2000
	s_nop 0
	global_load_lds_dwordx4 v[234:235], off
	v_lshl_add_u64 v[234:235], s[30:31], 0, v[130:131]
	s_mov_b32 m0, s43
	s_nop 0
	global_load_lds_dwordx4 v[234:235], off
	s_mov_b32 m0, s44
	s_nop 0
	global_load_lds_dwordx4 v[236:237], off
	s_waitcnt vmcnt(8)
	s_waitcnt lgkmcnt(0)
	s_barrier
	s_setprio 1
	v_mfma_f32_16x16x32_bf16 v[62:65], v[168:171], v[200:203], v[62:65]
	v_mfma_f32_16x16x32_bf16 v[58:61], v[176:179], v[200:203], v[58:61]
	v_mfma_f32_16x16x32_bf16 v[50:53], v[168:171], v[208:211], v[50:53]
	v_mfma_f32_16x16x32_bf16 v[42:45], v[176:179], v[208:211], v[42:45]
	v_mfma_f32_16x16x32_bf16 v[34:37], v[168:171], v[216:219], v[34:37]
	v_mfma_f32_16x16x32_bf16 v[26:29], v[176:179], v[216:219], v[26:29]
	v_mfma_f32_16x16x32_bf16 v[18:21], v[168:171], v[224:227], v[18:21]
	v_mfma_f32_16x16x32_bf16 v[10:13], v[176:179], v[224:227], v[10:13]
	v_mfma_f32_16x16x32_bf16 v[62:65], v[172:175], v[204:207], v[62:65]
	v_mfma_f32_16x16x32_bf16 v[58:61], v[180:183], v[204:207], v[58:61]
	v_mfma_f32_16x16x32_bf16 v[50:53], v[172:175], v[212:215], v[50:53]
	v_mfma_f32_16x16x32_bf16 v[42:45], v[180:183], v[212:215], v[42:45]
	v_mfma_f32_16x16x32_bf16 v[34:37], v[172:175], v[220:223], v[34:37]
	v_mfma_f32_16x16x32_bf16 v[26:29], v[180:183], v[220:223], v[26:29]
	v_mfma_f32_16x16x32_bf16 v[18:21], v[172:175], v[228:231], v[18:21]
	v_mfma_f32_16x16x32_bf16 v[10:13], v[180:183], v[228:231], v[10:13]
	s_setprio 0
	s_setprio 1
	v_mfma_f32_16x16x32_bf16 v[54:57], v[184:187], v[200:203], v[54:57]
	v_mfma_f32_16x16x32_bf16 v[46:49], v[192:195], v[200:203], v[46:49]
	v_mfma_f32_16x16x32_bf16 v[38:41], v[184:187], v[208:211], v[38:41]
	v_mfma_f32_16x16x32_bf16 v[30:33], v[192:195], v[208:211], v[30:33]
	v_mfma_f32_16x16x32_bf16 v[22:25], v[184:187], v[216:219], v[22:25]
	v_mfma_f32_16x16x32_bf16 v[14:17], v[192:195], v[216:219], v[14:17]
	v_mfma_f32_16x16x32_bf16 v[6:9], v[184:187], v[224:227], v[6:9]
	v_mfma_f32_16x16x32_bf16 v[2:5], v[192:195], v[224:227], v[2:5]
	v_mfma_f32_16x16x32_bf16 v[54:57], v[188:191], v[204:207], v[54:57]
	v_mfma_f32_16x16x32_bf16 v[46:49], v[196:199], v[204:207], v[46:49]
	v_mfma_f32_16x16x32_bf16 v[38:41], v[188:191], v[212:215], v[38:41]
	v_mfma_f32_16x16x32_bf16 v[30:33], v[196:199], v[212:215], v[30:33]
	v_mfma_f32_16x16x32_bf16 v[22:25], v[188:191], v[220:223], v[22:25]
	v_mfma_f32_16x16x32_bf16 v[14:17], v[196:199], v[220:223], v[14:17]
	v_mfma_f32_16x16x32_bf16 v[6:9], v[188:191], v[228:231], v[6:9]
	v_mfma_f32_16x16x32_bf16 v[2:5], v[196:199], v[228:231], v[2:5]
	s_setprio 0
	s_barrier
	s_add_i32 s63, 0, 0x18000
	v_add_u32_e32 v138, s63, v159
	s_add_i32 s64, 0, 0x1c000
	ds_read_b128 v[168:171], v138
	ds_read_b128 v[172:175], v138 offset:1024
	ds_read_b128 v[176:179], v138 offset:2048
	ds_read_b128 v[180:183], v138 offset:3072
	v_add_u32_e32 v138, s64, v159
	ds_read_b128 v[184:187], v138
	ds_read_b128 v[188:191], v138 offset:1024
	ds_read_b128 v[192:195], v138 offset:2048
	ds_read_b128 v[196:199], v138 offset:3072
	s_add_u32 s30, s30, 0x80000
	s_addc_u32 s31, s31, 0
	s_mov_b32 m0, s45
	v_lshl_add_u64 v[238:239], s[30:31], 0, v[130:131]
	ds_read_b128 v[200:203], v165 offset:32768
	ds_read_b128 v[204:207], v165 offset:33792
	ds_read_b128 v[208:211], v165 offset:34816
	ds_read_b128 v[212:215], v165 offset:35840
	ds_read_b128 v[216:219], v165 offset:36864
	ds_read_b128 v[220:223], v165 offset:37888
	ds_read_b128 v[224:227], v165 offset:38912
	ds_read_b128 v[228:231], v165 offset:39936
	global_load_lds_dwordx4 v[238:239], off
	v_lshl_add_u64 v[238:239], s[30:31], 0, v[134:135]
	s_mov_b32 m0, s46
	s_nop 0
	global_load_lds_dwordx4 v[238:239], off
	s_waitcnt vmcnt(8)
	s_waitcnt lgkmcnt(0)
	s_barrier
	s_setprio 1
	v_mfma_f32_16x16x32_bf16 v[126:129], v[168:171], v[200:203], v[126:129]
	v_mfma_f32_16x16x32_bf16 v[122:125], v[176:179], v[200:203], v[122:125]
	v_mfma_f32_16x16x32_bf16 v[114:117], v[168:171], v[208:211], v[114:117]
	v_mfma_f32_16x16x32_bf16 v[106:109], v[176:179], v[208:211], v[106:109]
	v_mfma_f32_16x16x32_bf16 v[98:101], v[168:171], v[216:219], v[98:101]
	v_mfma_f32_16x16x32_bf16 v[90:93], v[176:179], v[216:219], v[90:93]
	v_mfma_f32_16x16x32_bf16 v[82:85], v[168:171], v[224:227], v[82:85]
	v_mfma_f32_16x16x32_bf16 v[74:77], v[176:179], v[224:227], v[74:77]
	v_mfma_f32_16x16x32_bf16 v[126:129], v[172:175], v[204:207], v[126:129]
	v_mfma_f32_16x16x32_bf16 v[122:125], v[180:183], v[204:207], v[122:125]
	v_mfma_f32_16x16x32_bf16 v[114:117], v[172:175], v[212:215], v[114:117]
	v_mfma_f32_16x16x32_bf16 v[106:109], v[180:183], v[212:215], v[106:109]
	v_mfma_f32_16x16x32_bf16 v[98:101], v[172:175], v[220:223], v[98:101]
	v_mfma_f32_16x16x32_bf16 v[90:93], v[180:183], v[220:223], v[90:93]
	v_mfma_f32_16x16x32_bf16 v[82:85], v[172:175], v[228:231], v[82:85]
	v_mfma_f32_16x16x32_bf16 v[74:77], v[180:183], v[228:231], v[74:77]
	s_setprio 0
	s_setprio 1
	v_mfma_f32_16x16x32_bf16 v[118:121], v[184:187], v[200:203], v[118:121]
	v_mfma_f32_16x16x32_bf16 v[110:113], v[192:195], v[200:203], v[110:113]
	v_mfma_f32_16x16x32_bf16 v[102:105], v[184:187], v[208:211], v[102:105]
	v_mfma_f32_16x16x32_bf16 v[94:97], v[192:195], v[208:211], v[94:97]
	v_mfma_f32_16x16x32_bf16 v[86:89], v[184:187], v[216:219], v[86:89]
	v_mfma_f32_16x16x32_bf16 v[78:81], v[192:195], v[216:219], v[78:81]
	v_mfma_f32_16x16x32_bf16 v[70:73], v[184:187], v[224:227], v[70:73]
	v_mfma_f32_16x16x32_bf16 v[66:69], v[192:195], v[224:227], v[66:69]
	v_mfma_f32_16x16x32_bf16 v[118:121], v[188:191], v[204:207], v[118:121]
	v_mfma_f32_16x16x32_bf16 v[110:113], v[196:199], v[204:207], v[110:113]
	v_mfma_f32_16x16x32_bf16 v[102:105], v[188:191], v[212:215], v[102:105]
	v_mfma_f32_16x16x32_bf16 v[94:97], v[196:199], v[212:215], v[94:97]
	v_mfma_f32_16x16x32_bf16 v[86:89], v[188:191], v[220:223], v[86:89]
	v_mfma_f32_16x16x32_bf16 v[78:81], v[196:199], v[220:223], v[78:81]
	v_mfma_f32_16x16x32_bf16 v[70:73], v[188:191], v[228:231], v[70:73]
	v_mfma_f32_16x16x32_bf16 v[66:69], v[196:199], v[228:231], v[66:69]
	s_setprio 0
	s_barrier
	s_add_i32 s30, s63, s42
	v_lshl_add_u64 v[154:155], v[154:155], 0, s[8:9]
	s_mov_b32 m0, s30
	ds_read_b128 v[200:203], v165 offset:49152
	ds_read_b128 v[204:207], v165 offset:50176
	ds_read_b128 v[208:211], v165 offset:51200
	ds_read_b128 v[212:215], v165 offset:52224
	ds_read_b128 v[216:219], v165 offset:53248
	ds_read_b128 v[220:223], v165 offset:54272
	ds_read_b128 v[224:227], v165 offset:55296
	ds_read_b128 v[228:231], v165 offset:56320
	global_load_lds_dwordx4 v[154:155], off
	s_add_i32 m0, s30, 0x2000
	s_add_u32 s26, s26, 0x80080
	v_lshl_add_u64 v[154:155], v[232:233], 0, s[8:9]
	s_addc_u32 s27, s27, 0
	s_add_i32 s30, s64, s42
	global_load_lds_dwordx4 v[154:155], off
	v_lshl_add_u64 v[154:155], s[26:27], 0, v[132:133]
	s_mov_b32 m0, s30
	s_nop 0
	global_load_lds_dwordx4 v[154:155], off
	v_lshl_add_u64 v[154:155], s[26:27], 0, v[136:137]
	s_add_i32 m0, s30, 0x2000
	s_nop 0
	global_load_lds_dwordx4 v[154:155], off
	v_lshl_add_u64 v[154:155], v[234:235], 0, s[8:9]
	s_mov_b32 m0, s51
	s_nop 0
	global_load_lds_dwordx4 v[154:155], off
	v_lshl_add_u64 v[154:155], v[236:237], 0, s[8:9]
	s_mov_b32 m0, s53
	s_nop 0
	global_load_lds_dwordx4 v[154:155], off
	s_waitcnt vmcnt(8)
	s_waitcnt lgkmcnt(0)
	s_barrier
	s_setprio 1
	v_mfma_f32_16x16x32_bf16 v[62:65], v[168:171], v[200:203], v[62:65]
	v_mfma_f32_16x16x32_bf16 v[58:61], v[176:179], v[200:203], v[58:61]
	v_mfma_f32_16x16x32_bf16 v[50:53], v[168:171], v[208:211], v[50:53]
	v_mfma_f32_16x16x32_bf16 v[42:45], v[176:179], v[208:211], v[42:45]
	v_mfma_f32_16x16x32_bf16 v[34:37], v[168:171], v[216:219], v[34:37]
	v_mfma_f32_16x16x32_bf16 v[26:29], v[176:179], v[216:219], v[26:29]
	v_mfma_f32_16x16x32_bf16 v[18:21], v[168:171], v[224:227], v[18:21]
	v_mfma_f32_16x16x32_bf16 v[10:13], v[176:179], v[224:227], v[10:13]
	v_mfma_f32_16x16x32_bf16 v[62:65], v[172:175], v[204:207], v[62:65]
	v_mfma_f32_16x16x32_bf16 v[58:61], v[180:183], v[204:207], v[58:61]
	v_mfma_f32_16x16x32_bf16 v[50:53], v[172:175], v[212:215], v[50:53]
	v_mfma_f32_16x16x32_bf16 v[42:45], v[180:183], v[212:215], v[42:45]
	v_mfma_f32_16x16x32_bf16 v[34:37], v[172:175], v[220:223], v[34:37]
	v_mfma_f32_16x16x32_bf16 v[26:29], v[180:183], v[220:223], v[26:29]
	v_mfma_f32_16x16x32_bf16 v[18:21], v[172:175], v[228:231], v[18:21]
	v_mfma_f32_16x16x32_bf16 v[10:13], v[180:183], v[228:231], v[10:13]
	s_setprio 0
	s_setprio 1
	v_mfma_f32_16x16x32_bf16 v[54:57], v[184:187], v[200:203], v[54:57]
	v_mfma_f32_16x16x32_bf16 v[46:49], v[192:195], v[200:203], v[46:49]
	v_mfma_f32_16x16x32_bf16 v[38:41], v[184:187], v[208:211], v[38:41]
	v_mfma_f32_16x16x32_bf16 v[30:33], v[192:195], v[208:211], v[30:33]
	v_mfma_f32_16x16x32_bf16 v[22:25], v[184:187], v[216:219], v[22:25]
	v_mfma_f32_16x16x32_bf16 v[14:17], v[192:195], v[216:219], v[14:17]
	v_mfma_f32_16x16x32_bf16 v[6:9], v[184:187], v[224:227], v[6:9]
	v_mfma_f32_16x16x32_bf16 v[2:5], v[192:195], v[224:227], v[2:5]
	v_mfma_f32_16x16x32_bf16 v[54:57], v[188:191], v[204:207], v[54:57]
	v_mfma_f32_16x16x32_bf16 v[46:49], v[196:199], v[204:207], v[46:49]
	v_mfma_f32_16x16x32_bf16 v[38:41], v[188:191], v[212:215], v[38:41]
	v_mfma_f32_16x16x32_bf16 v[30:33], v[196:199], v[212:215], v[30:33]
	v_mfma_f32_16x16x32_bf16 v[22:25], v[188:191], v[220:223], v[22:25]
	v_mfma_f32_16x16x32_bf16 v[14:17], v[196:199], v[220:223], v[14:17]
	v_mfma_f32_16x16x32_bf16 v[6:9], v[188:191], v[228:231], v[6:9]
	v_mfma_f32_16x16x32_bf16 v[2:5], v[196:199], v[228:231], v[2:5]
	s_setprio 0
	s_barrier
	s_add_i32 s62, s62, 2
	s_add_u32 s60, s60, 0x100
	s_addc_u32 s61, s61, 0
	s_add_u32 s24, s24, 0x100
	s_addc_u32 s25, s25, 0
	s_cmp_gt_u32 s62, 29
	s_cbranch_scc0 .LBB0_143
	s_and_b64 vcc, exec, s[10:11]
	s_cbranch_vccz .LBB0_146
	s_barrier

.LBB0_268:
	ds_read_b128 v[150:153], v139
	ds_read_b128 v[154:157], v139 offset:1024
	ds_read_b128 v[158:161], v139 offset:2048
	ds_read_b128 v[162:165], v139 offset:3072
	ds_read_b128 v[166:169], v146
	ds_read_b128 v[170:173], v146 offset:1024
	ds_read_b128 v[174:177], v146 offset:2048
	ds_read_b128 v[178:181], v146 offset:3072
	s_add_u32 s18, s14, s16
	s_addc_u32 s19, s15, s17
	s_add_u32 s18, s18, 0x28300100
	s_addc_u32 s19, s19, 0
	s_add_u32 s55, s41, s16
	s_addc_u32 s56, s42, s17
	s_cmpk_eq_i32 s16, 0x300
	s_cselect_b32 s23, s11, s19
	s_cselect_b32 s22, s10, s18
	s_cselect_b32 s19, s9, s56
	s_cselect_b32 s18, s8, s55
	s_mov_b32 m0, s44
	v_lshl_add_u64 v[214:215], v[142:143], 0, s[16:17]
	ds_read_b128 v[182:185], v147
	ds_read_b128 v[186:189], v147 offset:1024
	ds_read_b128 v[190:193], v147 offset:2048
	ds_read_b128 v[194:197], v147 offset:3072
	ds_read_b128 v[198:201], v147 offset:4096
	ds_read_b128 v[202:205], v147 offset:5120
	ds_read_b128 v[206:209], v147 offset:6144
	ds_read_b128 v[210:213], v147 offset:7168
	global_load_lds_dwordx4 v[214:215], off
	v_lshl_add_u64 v[214:215], v[140:141], 0, s[16:17]
	s_mov_b32 m0, s45
	s_nop 0
	global_load_lds_dwordx4 v[214:215], off
	s_waitcnt vmcnt(8)
	s_waitcnt lgkmcnt(0)
	s_barrier
	s_setprio 1
	v_mfma_f32_16x16x32_bf16 v[126:129], v[150:153], v[182:185], v[126:129]
	v_mfma_f32_16x16x32_bf16 v[122:125], v[158:161], v[182:185], v[122:125]
	v_mfma_f32_16x16x32_bf16 v[118:121], v[150:153], v[190:193], v[118:121]
	v_mfma_f32_16x16x32_bf16 v[110:113], v[158:161], v[190:193], v[110:113]
	v_mfma_f32_16x16x32_bf16 v[102:105], v[150:153], v[198:201], v[102:105]
	v_mfma_f32_16x16x32_bf16 v[94:97], v[158:161], v[198:201], v[94:97]
	v_mfma_f32_16x16x32_bf16 v[86:89], v[150:153], v[206:209], v[86:89]
	v_mfma_f32_16x16x32_bf16 v[78:81], v[158:161], v[206:209], v[78:81]
	v_mfma_f32_16x16x32_bf16 v[126:129], v[154:157], v[186:189], v[126:129]
	v_mfma_f32_16x16x32_bf16 v[122:125], v[162:165], v[186:189], v[122:125]
	v_mfma_f32_16x16x32_bf16 v[118:121], v[154:157], v[194:197], v[118:121]
	v_mfma_f32_16x16x32_bf16 v[110:113], v[162:165], v[194:197], v[110:113]
	v_mfma_f32_16x16x32_bf16 v[102:105], v[154:157], v[202:205], v[102:105]
	v_mfma_f32_16x16x32_bf16 v[94:97], v[162:165], v[202:205], v[94:97]
	v_mfma_f32_16x16x32_bf16 v[86:89], v[154:157], v[210:213], v[86:89]
	v_mfma_f32_16x16x32_bf16 v[78:81], v[162:165], v[210:213], v[78:81]
	s_setprio 0
	s_setprio 1
	v_mfma_f32_16x16x32_bf16 v[114:117], v[166:169], v[182:185], v[114:117]
	v_mfma_f32_16x16x32_bf16 v[106:109], v[174:177], v[182:185], v[106:109]
	v_mfma_f32_16x16x32_bf16 v[98:101], v[166:169], v[190:193], v[98:101]
	v_mfma_f32_16x16x32_bf16 v[90:93], v[174:177], v[190:193], v[90:93]
	v_mfma_f32_16x16x32_bf16 v[82:85], v[166:169], v[198:201], v[82:85]
	v_mfma_f32_16x16x32_bf16 v[74:77], v[174:177], v[198:201], v[74:77]
	v_mfma_f32_16x16x32_bf16 v[70:73], v[166:169], v[206:209], v[70:73]
	v_mfma_f32_16x16x32_bf16 v[66:69], v[174:177], v[206:209], v[66:69]
	v_mfma_f32_16x16x32_bf16 v[114:117], v[170:173], v[186:189], v[114:117]
	v_mfma_f32_16x16x32_bf16 v[106:109], v[178:181], v[186:189], v[106:109]
	v_mfma_f32_16x16x32_bf16 v[98:101], v[170:173], v[194:197], v[98:101]
	v_mfma_f32_16x16x32_bf16 v[90:93], v[178:181], v[194:197], v[90:93]
	v_mfma_f32_16x16x32_bf16 v[82:85], v[170:173], v[202:205], v[82:85]
	v_mfma_f32_16x16x32_bf16 v[74:77], v[178:181], v[202:205], v[74:77]
	v_mfma_f32_16x16x32_bf16 v[70:73], v[170:173], v[210:213], v[70:73]
	v_mfma_f32_16x16x32_bf16 v[66:69], v[178:181], v[210:213], v[66:69]
	s_setprio 0
	s_barrier
	s_mov_b32 m0, s46
	v_lshl_add_u64 v[214:215], s[18:19], 0, v[132:133]
	s_add_u32 s56, s18, 0x20000
	ds_read_b128 v[182:185], v147 offset:16384
	ds_read_b128 v[186:189], v147 offset:17408
	ds_read_b128 v[190:193], v147 offset:18432
	ds_read_b128 v[194:197], v147 offset:19456
	ds_read_b128 v[198:201], v147 offset:20480
	ds_read_b128 v[202:205], v147 offset:21504
	ds_read_b128 v[206:209], v147 offset:22528
	ds_read_b128 v[210:213], v147 offset:23552
	global_load_lds_dwordx4 v[214:215], off
	v_lshl_add_u64 v[216:217], s[18:19], 0, v[136:137]
	s_mov_b32 m0, s47
	s_addc_u32 s57, s19, 0
	global_load_lds_dwordx4 v[216:217], off
	v_lshl_add_u64 v[218:219], s[56:57], 0, v[132:133]
	s_mov_b32 m0, s48
	v_lshl_add_u64 v[220:221], s[22:23], 0, v[134:135]
	global_load_lds_dwordx4 v[218:219], off
	v_lshl_add_u64 v[218:219], s[56:57], 0, v[136:137]
	s_mov_b32 m0, s49
	s_nop 0
	global_load_lds_dwordx4 v[218:219], off
	v_lshl_add_u64 v[218:219], s[22:23], 0, v[130:131]
	s_mov_b32 m0, s7
	s_nop 0
	global_load_lds_dwordx4 v[218:219], off
	s_mov_b32 m0, s36
	s_nop 0
	global_load_lds_dwordx4 v[220:221], off
	s_waitcnt vmcnt(8)
	s_waitcnt lgkmcnt(0)
	s_barrier
	s_setprio 1
	v_mfma_f32_16x16x32_bf16 v[62:65], v[150:153], v[182:185], v[62:65]
	v_mfma_f32_16x16x32_bf16 v[58:61], v[158:161], v[182:185], v[58:61]
	v_mfma_f32_16x16x32_bf16 v[54:57], v[150:153], v[190:193], v[54:57]
	v_mfma_f32_16x16x32_bf16 v[46:49], v[158:161], v[190:193], v[46:49]
	v_mfma_f32_16x16x32_bf16 v[38:41], v[150:153], v[198:201], v[38:41]
	v_mfma_f32_16x16x32_bf16 v[30:33], v[158:161], v[198:201], v[30:33]
	v_mfma_f32_16x16x32_bf16 v[22:25], v[150:153], v[206:209], v[22:25]
	v_mfma_f32_16x16x32_bf16 v[14:17], v[158:161], v[206:209], v[14:17]
	v_mfma_f32_16x16x32_bf16 v[62:65], v[154:157], v[186:189], v[62:65]
	v_mfma_f32_16x16x32_bf16 v[58:61], v[162:165], v[186:189], v[58:61]
	v_mfma_f32_16x16x32_bf16 v[54:57], v[154:157], v[194:197], v[54:57]
	v_mfma_f32_16x16x32_bf16 v[46:49], v[162:165], v[194:197], v[46:49]
	v_mfma_f32_16x16x32_bf16 v[38:41], v[154:157], v[202:205], v[38:41]
	v_mfma_f32_16x16x32_bf16 v[30:33], v[162:165], v[202:205], v[30:33]
	v_mfma_f32_16x16x32_bf16 v[22:25], v[154:157], v[210:213], v[22:25]
	v_mfma_f32_16x16x32_bf16 v[14:17], v[162:165], v[210:213], v[14:17]
	s_setprio 0
	s_setprio 1
	v_mfma_f32_16x16x32_bf16 v[50:53], v[166:169], v[182:185], v[50:53]
	v_mfma_f32_16x16x32_bf16 v[42:45], v[174:177], v[182:185], v[42:45]
	v_mfma_f32_16x16x32_bf16 v[34:37], v[166:169], v[190:193], v[34:37]
	v_mfma_f32_16x16x32_bf16 v[26:29], v[174:177], v[190:193], v[26:29]
	v_mfma_f32_16x16x32_bf16 v[18:21], v[166:169], v[198:201], v[18:21]
	v_mfma_f32_16x16x32_bf16 v[10:13], v[174:177], v[198:201], v[10:13]
	v_mfma_f32_16x16x32_bf16 v[6:9], v[166:169], v[206:209], v[6:9]
	v_mfma_f32_16x16x32_bf16 v[2:5], v[174:177], v[206:209], v[2:5]
	v_mfma_f32_16x16x32_bf16 v[50:53], v[170:173], v[186:189], v[50:53]
	v_mfma_f32_16x16x32_bf16 v[42:45], v[178:181], v[186:189], v[42:45]
	v_mfma_f32_16x16x32_bf16 v[34:37], v[170:173], v[194:197], v[34:37]
	v_mfma_f32_16x16x32_bf16 v[26:29], v[178:181], v[194:197], v[26:29]
	v_mfma_f32_16x16x32_bf16 v[18:21], v[170:173], v[202:205], v[18:21]
	v_mfma_f32_16x16x32_bf16 v[10:13], v[178:181], v[202:205], v[10:13]
	v_mfma_f32_16x16x32_bf16 v[6:9], v[170:173], v[210:213], v[6:9]
	v_mfma_f32_16x16x32_bf16 v[2:5], v[178:181], v[210:213], v[2:5]
	s_setprio 0
	s_barrier
	ds_read_b128 v[150:153], v148
	ds_read_b128 v[154:157], v148 offset:1024
	ds_read_b128 v[158:161], v148 offset:2048
	ds_read_b128 v[162:165], v148 offset:3072
	ds_read_b128 v[166:169], v149
	ds_read_b128 v[170:173], v149 offset:1024
	ds_read_b128 v[174:177], v149 offset:2048
	ds_read_b128 v[178:181], v149 offset:3072
	s_add_u32 s22, s22, 0x20000
	s_addc_u32 s23, s23, 0
	s_mov_b32 m0, s37
	v_lshl_add_u64 v[222:223], s[22:23], 0, v[130:131]
	ds_read_b128 v[182:185], v147 offset:32768
	ds_read_b128 v[186:189], v147 offset:33792
	ds_read_b128 v[190:193], v147 offset:34816
	ds_read_b128 v[194:197], v147 offset:35840
	ds_read_b128 v[198:201], v147 offset:36864
	ds_read_b128 v[202:205], v147 offset:37888
	ds_read_b128 v[206:209], v147 offset:38912
	ds_read_b128 v[210:213], v147 offset:39936
	global_load_lds_dwordx4 v[222:223], off
	v_lshl_add_u64 v[222:223], s[22:23], 0, v[134:135]
	s_mov_b32 m0, s38
	s_nop 0
	global_load_lds_dwordx4 v[222:223], off
	s_waitcnt vmcnt(8)
	s_waitcnt lgkmcnt(0)
	s_barrier
	s_setprio 1
	v_mfma_f32_16x16x32_bf16 v[126:129], v[150:153], v[182:185], v[126:129]
	v_mfma_f32_16x16x32_bf16 v[122:125], v[158:161], v[182:185], v[122:125]
	v_mfma_f32_16x16x32_bf16 v[118:121], v[150:153], v[190:193], v[118:121]
	v_mfma_f32_16x16x32_bf16 v[110:113], v[158:161], v[190:193], v[110:113]
	v_mfma_f32_16x16x32_bf16 v[102:105], v[150:153], v[198:201], v[102:105]
	v_mfma_f32_16x16x32_bf16 v[94:97], v[158:161], v[198:201], v[94:97]
	v_mfma_f32_16x16x32_bf16 v[86:89], v[150:153], v[206:209], v[86:89]
	v_mfma_f32_16x16x32_bf16 v[78:81], v[158:161], v[206:209], v[78:81]
	v_mfma_f32_16x16x32_bf16 v[126:129], v[154:157], v[186:189], v[126:129]
	v_mfma_f32_16x16x32_bf16 v[122:125], v[162:165], v[186:189], v[122:125]
	v_mfma_f32_16x16x32_bf16 v[118:121], v[154:157], v[194:197], v[118:121]
	v_mfma_f32_16x16x32_bf16 v[110:113], v[162:165], v[194:197], v[110:113]
	v_mfma_f32_16x16x32_bf16 v[102:105], v[154:157], v[202:205], v[102:105]
	v_mfma_f32_16x16x32_bf16 v[94:97], v[162:165], v[202:205], v[94:97]
	v_mfma_f32_16x16x32_bf16 v[86:89], v[154:157], v[210:213], v[86:89]
	v_mfma_f32_16x16x32_bf16 v[78:81], v[162:165], v[210:213], v[78:81]
	s_setprio 0
	s_setprio 1
	v_mfma_f32_16x16x32_bf16 v[114:117], v[166:169], v[182:185], v[114:117]
	v_mfma_f32_16x16x32_bf16 v[106:109], v[174:177], v[182:185], v[106:109]
	v_mfma_f32_16x16x32_bf16 v[98:101], v[166:169], v[190:193], v[98:101]
	v_mfma_f32_16x16x32_bf16 v[90:93], v[174:177], v[190:193], v[90:93]
	v_mfma_f32_16x16x32_bf16 v[82:85], v[166:169], v[198:201], v[82:85]
	v_mfma_f32_16x16x32_bf16 v[74:77], v[174:177], v[198:201], v[74:77]
	v_mfma_f32_16x16x32_bf16 v[70:73], v[166:169], v[206:209], v[70:73]
	v_mfma_f32_16x16x32_bf16 v[66:69], v[174:177], v[206:209], v[66:69]
	v_mfma_f32_16x16x32_bf16 v[114:117], v[170:173], v[186:189], v[114:117]
	v_mfma_f32_16x16x32_bf16 v[106:109], v[178:181], v[186:189], v[106:109]
	v_mfma_f32_16x16x32_bf16 v[98:101], v[170:173], v[194:197], v[98:101]
	v_mfma_f32_16x16x32_bf16 v[90:93], v[178:181], v[194:197], v[90:93]
	v_mfma_f32_16x16x32_bf16 v[82:85], v[170:173], v[202:205], v[82:85]
	v_mfma_f32_16x16x32_bf16 v[74:77], v[178:181], v[202:205], v[74:77]
	v_mfma_f32_16x16x32_bf16 v[70:73], v[170:173], v[210:213], v[70:73]
	v_mfma_f32_16x16x32_bf16 v[66:69], v[178:181], v[210:213], v[66:69]
	s_setprio 0
	s_barrier
	s_mov_b32 m0, s50
	v_lshl_add_u64 v[214:215], v[214:215], 0, s[12:13]
	s_add_u32 s18, s18, 0x20080
	ds_read_b128 v[182:185], v147 offset:49152
	ds_read_b128 v[186:189], v147 offset:50176
	ds_read_b128 v[190:193], v147 offset:51200
	ds_read_b128 v[194:197], v147 offset:52224
	ds_read_b128 v[198:201], v147 offset:53248
	ds_read_b128 v[202:205], v147 offset:54272
	ds_read_b128 v[206:209], v147 offset:55296
	ds_read_b128 v[210:213], v147 offset:56320
	global_load_lds_dwordx4 v[214:215], off
	v_lshl_add_u64 v[214:215], v[216:217], 0, s[12:13]
	s_mov_b32 m0, s51
	s_addc_u32 s19, s19, 0
	global_load_lds_dwordx4 v[214:215], off
	v_lshl_add_u64 v[214:215], s[18:19], 0, v[132:133]
	s_mov_b32 m0, s53
	s_nop 0
	global_load_lds_dwordx4 v[214:215], off
	v_lshl_add_u64 v[214:215], s[18:19], 0, v[136:137]
	s_mov_b32 m0, s54
	s_nop 0
	global_load_lds_dwordx4 v[214:215], off
	v_lshl_add_u64 v[214:215], v[218:219], 0, s[12:13]
	s_mov_b32 m0, s39
	s_nop 0
	global_load_lds_dwordx4 v[214:215], off
	v_lshl_add_u64 v[214:215], v[220:221], 0, s[12:13]
	s_mov_b32 m0, s40
	s_nop 0
	global_load_lds_dwordx4 v[214:215], off
	s_waitcnt vmcnt(8)
	s_waitcnt lgkmcnt(0)
	s_barrier
	s_setprio 1
	v_mfma_f32_16x16x32_bf16 v[62:65], v[150:153], v[182:185], v[62:65]
	v_mfma_f32_16x16x32_bf16 v[58:61], v[158:161], v[182:185], v[58:61]
	v_mfma_f32_16x16x32_bf16 v[54:57], v[150:153], v[190:193], v[54:57]
	v_mfma_f32_16x16x32_bf16 v[46:49], v[158:161], v[190:193], v[46:49]
	v_mfma_f32_16x16x32_bf16 v[38:41], v[150:153], v[198:201], v[38:41]
	v_mfma_f32_16x16x32_bf16 v[30:33], v[158:161], v[198:201], v[30:33]
	v_mfma_f32_16x16x32_bf16 v[22:25], v[150:153], v[206:209], v[22:25]
	v_mfma_f32_16x16x32_bf16 v[14:17], v[158:161], v[206:209], v[14:17]
	v_mfma_f32_16x16x32_bf16 v[62:65], v[154:157], v[186:189], v[62:65]
	v_mfma_f32_16x16x32_bf16 v[58:61], v[162:165], v[186:189], v[58:61]
	v_mfma_f32_16x16x32_bf16 v[54:57], v[154:157], v[194:197], v[54:57]
	v_mfma_f32_16x16x32_bf16 v[46:49], v[162:165], v[194:197], v[46:49]
	v_mfma_f32_16x16x32_bf16 v[38:41], v[154:157], v[202:205], v[38:41]
	v_mfma_f32_16x16x32_bf16 v[30:33], v[162:165], v[202:205], v[30:33]
	v_mfma_f32_16x16x32_bf16 v[22:25], v[154:157], v[210:213], v[22:25]
	v_mfma_f32_16x16x32_bf16 v[14:17], v[162:165], v[210:213], v[14:17]
	s_setprio 0
	s_setprio 1
	v_mfma_f32_16x16x32_bf16 v[50:53], v[166:169], v[182:185], v[50:53]
	v_mfma_f32_16x16x32_bf16 v[42:45], v[174:177], v[182:185], v[42:45]
	v_mfma_f32_16x16x32_bf16 v[34:37], v[166:169], v[190:193], v[34:37]
	v_mfma_f32_16x16x32_bf16 v[26:29], v[174:177], v[190:193], v[26:29]
	v_mfma_f32_16x16x32_bf16 v[18:21], v[166:169], v[198:201], v[18:21]
	v_mfma_f32_16x16x32_bf16 v[10:13], v[174:177], v[198:201], v[10:13]
	v_mfma_f32_16x16x32_bf16 v[6:9], v[166:169], v[206:209], v[6:9]
	v_mfma_f32_16x16x32_bf16 v[2:5], v[174:177], v[206:209], v[2:5]
	v_mfma_f32_16x16x32_bf16 v[50:53], v[170:173], v[186:189], v[50:53]
	v_mfma_f32_16x16x32_bf16 v[42:45], v[178:181], v[186:189], v[42:45]
	v_mfma_f32_16x16x32_bf16 v[34:37], v[170:173], v[194:197], v[34:37]
	v_mfma_f32_16x16x32_bf16 v[26:29], v[178:181], v[194:197], v[26:29]
	v_mfma_f32_16x16x32_bf16 v[18:21], v[170:173], v[202:205], v[18:21]
	v_mfma_f32_16x16x32_bf16 v[10:13], v[178:181], v[202:205], v[10:13]
	v_mfma_f32_16x16x32_bf16 v[6:9], v[170:173], v[210:213], v[6:9]
	v_mfma_f32_16x16x32_bf16 v[2:5], v[178:181], v[210:213], v[2:5]
	s_setprio 0
	s_barrier
	s_add_i32 s43, s43, 2
	s_add_u32 s16, s16, 0x100
	s_addc_u32 s17, s17, 0
	s_cmp_gt_u32 s43, 5
	s_cbranch_scc0 .LBB0_268
	s_cmpk_lt_u32 s33, 0x100
	s_cbranch_scc0 .LBB0_271
	s_barrier

.LBB0_274:
	ds_read_b128 v[150:153], v144
	ds_read_b128 v[154:157], v144 offset:1024
	ds_read_b128 v[158:161], v144 offset:2048
	ds_read_b128 v[162:165], v144 offset:3072
	ds_read_b128 v[166:169], v145
	ds_read_b128 v[170:173], v145 offset:1024
	ds_read_b128 v[174:177], v145 offset:2048
	ds_read_b128 v[178:181], v145 offset:3072
	s_add_u32 s18, s14, s16
	s_addc_u32 s19, s15, s17
	s_add_u32 s18, s18, 0xf900100
	s_addc_u32 s19, s19, 0
	s_add_u32 s49, s40, s16
	s_addc_u32 s50, s41, s17
	s_cmpk_eq_i32 s16, 0x300
	s_cselect_b32 s23, s11, s19
	s_cselect_b32 s22, s10, s18
	s_cselect_b32 s19, s9, s50
	s_cselect_b32 s18, s8, s49
	s_mov_b32 m0, s43
	v_lshl_add_u64 v[214:215], v[140:141], 0, s[16:17]
	ds_read_b128 v[182:185], v146
	ds_read_b128 v[186:189], v146 offset:1024
	ds_read_b128 v[190:193], v146 offset:2048
	ds_read_b128 v[194:197], v146 offset:3072
	ds_read_b128 v[198:201], v146 offset:4096
	ds_read_b128 v[202:205], v146 offset:5120
	ds_read_b128 v[206:209], v146 offset:6144
	ds_read_b128 v[210:213], v146 offset:7168
	global_load_lds_dwordx4 v[214:215], off
	v_lshl_add_u64 v[214:215], v[138:139], 0, s[16:17]
	s_mov_b32 m0, s44
	s_nop 0
	global_load_lds_dwordx4 v[214:215], off
	s_waitcnt vmcnt(8)
	s_waitcnt lgkmcnt(0)
	s_barrier
	s_setprio 1
	v_mfma_f32_16x16x32_bf16 v[126:129], v[150:153], v[182:185], v[126:129]
	v_mfma_f32_16x16x32_bf16 v[122:125], v[158:161], v[182:185], v[122:125]
	v_mfma_f32_16x16x32_bf16 v[118:121], v[150:153], v[190:193], v[118:121]
	v_mfma_f32_16x16x32_bf16 v[110:113], v[158:161], v[190:193], v[110:113]
	v_mfma_f32_16x16x32_bf16 v[102:105], v[150:153], v[198:201], v[102:105]
	v_mfma_f32_16x16x32_bf16 v[94:97], v[158:161], v[198:201], v[94:97]
	v_mfma_f32_16x16x32_bf16 v[86:89], v[150:153], v[206:209], v[86:89]
	v_mfma_f32_16x16x32_bf16 v[78:81], v[158:161], v[206:209], v[78:81]
	v_mfma_f32_16x16x32_bf16 v[126:129], v[154:157], v[186:189], v[126:129]
	v_mfma_f32_16x16x32_bf16 v[122:125], v[162:165], v[186:189], v[122:125]
	v_mfma_f32_16x16x32_bf16 v[118:121], v[154:157], v[194:197], v[118:121]
	v_mfma_f32_16x16x32_bf16 v[110:113], v[162:165], v[194:197], v[110:113]
	v_mfma_f32_16x16x32_bf16 v[102:105], v[154:157], v[202:205], v[102:105]
	v_mfma_f32_16x16x32_bf16 v[94:97], v[162:165], v[202:205], v[94:97]
	v_mfma_f32_16x16x32_bf16 v[86:89], v[154:157], v[210:213], v[86:89]
	v_mfma_f32_16x16x32_bf16 v[78:81], v[162:165], v[210:213], v[78:81]
	s_setprio 0
	s_setprio 1
	v_mfma_f32_16x16x32_bf16 v[114:117], v[166:169], v[182:185], v[114:117]
	v_mfma_f32_16x16x32_bf16 v[106:109], v[174:177], v[182:185], v[106:109]
	v_mfma_f32_16x16x32_bf16 v[98:101], v[166:169], v[190:193], v[98:101]
	v_mfma_f32_16x16x32_bf16 v[90:93], v[174:177], v[190:193], v[90:93]
	v_mfma_f32_16x16x32_bf16 v[82:85], v[166:169], v[198:201], v[82:85]
	v_mfma_f32_16x16x32_bf16 v[74:77], v[174:177], v[198:201], v[74:77]
	v_mfma_f32_16x16x32_bf16 v[70:73], v[166:169], v[206:209], v[70:73]
	v_mfma_f32_16x16x32_bf16 v[66:69], v[174:177], v[206:209], v[66:69]
	v_mfma_f32_16x16x32_bf16 v[114:117], v[170:173], v[186:189], v[114:117]
	v_mfma_f32_16x16x32_bf16 v[106:109], v[178:181], v[186:189], v[106:109]
	v_mfma_f32_16x16x32_bf16 v[98:101], v[170:173], v[194:197], v[98:101]
	v_mfma_f32_16x16x32_bf16 v[90:93], v[178:181], v[194:197], v[90:93]
	v_mfma_f32_16x16x32_bf16 v[82:85], v[170:173], v[202:205], v[82:85]
	v_mfma_f32_16x16x32_bf16 v[74:77], v[178:181], v[202:205], v[74:77]
	v_mfma_f32_16x16x32_bf16 v[70:73], v[170:173], v[210:213], v[70:73]
	v_mfma_f32_16x16x32_bf16 v[66:69], v[178:181], v[210:213], v[66:69]
	s_setprio 0
	s_barrier
	s_mov_b32 m0, s25
	v_lshl_add_u64 v[214:215], s[18:19], 0, v[130:131]
	s_add_u32 s50, s18, 0x20000
	ds_read_b128 v[182:185], v146 offset:16384
	ds_read_b128 v[186:189], v146 offset:17408
	ds_read_b128 v[190:193], v146 offset:18432
	ds_read_b128 v[194:197], v146 offset:19456
	ds_read_b128 v[198:201], v146 offset:20480
	ds_read_b128 v[202:205], v146 offset:21504
	ds_read_b128 v[206:209], v146 offset:22528
	ds_read_b128 v[210:213], v146 offset:23552
	global_load_lds_dwordx4 v[214:215], off
	v_lshl_add_u64 v[216:217], s[18:19], 0, v[136:137]
	s_mov_b32 m0, s45
	s_addc_u32 s51, s19, 0
	global_load_lds_dwordx4 v[216:217], off
	v_lshl_add_u64 v[218:219], s[50:51], 0, v[130:131]
	s_mov_b32 m0, s26
	v_lshl_add_u64 v[220:221], s[22:23], 0, v[134:135]
	global_load_lds_dwordx4 v[218:219], off
	v_lshl_add_u64 v[218:219], s[50:51], 0, v[136:137]
	s_mov_b32 m0, s46
	s_nop 0
	global_load_lds_dwordx4 v[218:219], off
	v_lshl_add_u64 v[218:219], s[22:23], 0, v[132:133]
	s_mov_b32 m0, s7
	s_nop 0
	global_load_lds_dwordx4 v[218:219], off
	s_mov_b32 m0, s34
	s_nop 0
	global_load_lds_dwordx4 v[220:221], off
	s_waitcnt vmcnt(8)
	s_waitcnt lgkmcnt(0)
	s_barrier
	s_setprio 1
	v_mfma_f32_16x16x32_bf16 v[62:65], v[150:153], v[182:185], v[62:65]
	v_mfma_f32_16x16x32_bf16 v[58:61], v[158:161], v[182:185], v[58:61]
	v_mfma_f32_16x16x32_bf16 v[54:57], v[150:153], v[190:193], v[54:57]
	v_mfma_f32_16x16x32_bf16 v[46:49], v[158:161], v[190:193], v[46:49]
	v_mfma_f32_16x16x32_bf16 v[38:41], v[150:153], v[198:201], v[38:41]
	v_mfma_f32_16x16x32_bf16 v[30:33], v[158:161], v[198:201], v[30:33]
	v_mfma_f32_16x16x32_bf16 v[22:25], v[150:153], v[206:209], v[22:25]
	v_mfma_f32_16x16x32_bf16 v[14:17], v[158:161], v[206:209], v[14:17]
	v_mfma_f32_16x16x32_bf16 v[62:65], v[154:157], v[186:189], v[62:65]
	v_mfma_f32_16x16x32_bf16 v[58:61], v[162:165], v[186:189], v[58:61]
	v_mfma_f32_16x16x32_bf16 v[54:57], v[154:157], v[194:197], v[54:57]
	v_mfma_f32_16x16x32_bf16 v[46:49], v[162:165], v[194:197], v[46:49]
	v_mfma_f32_16x16x32_bf16 v[38:41], v[154:157], v[202:205], v[38:41]
	v_mfma_f32_16x16x32_bf16 v[30:33], v[162:165], v[202:205], v[30:33]
	v_mfma_f32_16x16x32_bf16 v[22:25], v[154:157], v[210:213], v[22:25]
	v_mfma_f32_16x16x32_bf16 v[14:17], v[162:165], v[210:213], v[14:17]
	s_setprio 0
	s_setprio 1
	v_mfma_f32_16x16x32_bf16 v[50:53], v[166:169], v[182:185], v[50:53]
	v_mfma_f32_16x16x32_bf16 v[42:45], v[174:177], v[182:185], v[42:45]
	v_mfma_f32_16x16x32_bf16 v[34:37], v[166:169], v[190:193], v[34:37]
	v_mfma_f32_16x16x32_bf16 v[26:29], v[174:177], v[190:193], v[26:29]
	v_mfma_f32_16x16x32_bf16 v[18:21], v[166:169], v[198:201], v[18:21]
	v_mfma_f32_16x16x32_bf16 v[10:13], v[174:177], v[198:201], v[10:13]
	v_mfma_f32_16x16x32_bf16 v[6:9], v[166:169], v[206:209], v[6:9]
	v_mfma_f32_16x16x32_bf16 v[2:5], v[174:177], v[206:209], v[2:5]
	v_mfma_f32_16x16x32_bf16 v[50:53], v[170:173], v[186:189], v[50:53]
	v_mfma_f32_16x16x32_bf16 v[42:45], v[178:181], v[186:189], v[42:45]
	v_mfma_f32_16x16x32_bf16 v[34:37], v[170:173], v[194:197], v[34:37]
	v_mfma_f32_16x16x32_bf16 v[26:29], v[178:181], v[194:197], v[26:29]
	v_mfma_f32_16x16x32_bf16 v[18:21], v[170:173], v[202:205], v[18:21]
	v_mfma_f32_16x16x32_bf16 v[10:13], v[178:181], v[202:205], v[10:13]
	v_mfma_f32_16x16x32_bf16 v[6:9], v[170:173], v[210:213], v[6:9]
	v_mfma_f32_16x16x32_bf16 v[2:5], v[178:181], v[210:213], v[2:5]
	s_setprio 0
	s_barrier
	ds_read_b128 v[150:153], v147
	ds_read_b128 v[154:157], v147 offset:1024
	ds_read_b128 v[158:161], v147 offset:2048
	ds_read_b128 v[162:165], v147 offset:3072
	ds_read_b128 v[166:169], v148
	ds_read_b128 v[170:173], v148 offset:1024
	ds_read_b128 v[174:177], v148 offset:2048
	ds_read_b128 v[178:181], v148 offset:3072
	s_add_u32 s22, s22, 0x20000
	s_addc_u32 s23, s23, 0
	s_mov_b32 m0, s35
	v_lshl_add_u64 v[222:223], s[22:23], 0, v[132:133]
	ds_read_b128 v[182:185], v146 offset:32768
	ds_read_b128 v[186:189], v146 offset:33792
	ds_read_b128 v[190:193], v146 offset:34816
	ds_read_b128 v[194:197], v146 offset:35840
	ds_read_b128 v[198:201], v146 offset:36864
	ds_read_b128 v[202:205], v146 offset:37888
	ds_read_b128 v[206:209], v146 offset:38912
	ds_read_b128 v[210:213], v146 offset:39936
	global_load_lds_dwordx4 v[222:223], off
	v_lshl_add_u64 v[222:223], s[22:23], 0, v[134:135]
	s_mov_b32 m0, s36
	s_nop 0
	global_load_lds_dwordx4 v[222:223], off
	s_waitcnt vmcnt(8)
	s_waitcnt lgkmcnt(0)
	s_barrier
	s_setprio 1
	v_mfma_f32_16x16x32_bf16 v[126:129], v[150:153], v[182:185], v[126:129]
	v_mfma_f32_16x16x32_bf16 v[122:125], v[158:161], v[182:185], v[122:125]
	v_mfma_f32_16x16x32_bf16 v[118:121], v[150:153], v[190:193], v[118:121]
	v_mfma_f32_16x16x32_bf16 v[110:113], v[158:161], v[190:193], v[110:113]
	v_mfma_f32_16x16x32_bf16 v[102:105], v[150:153], v[198:201], v[102:105]
	v_mfma_f32_16x16x32_bf16 v[94:97], v[158:161], v[198:201], v[94:97]
	v_mfma_f32_16x16x32_bf16 v[86:89], v[150:153], v[206:209], v[86:89]
	v_mfma_f32_16x16x32_bf16 v[78:81], v[158:161], v[206:209], v[78:81]
	v_mfma_f32_16x16x32_bf16 v[126:129], v[154:157], v[186:189], v[126:129]
	v_mfma_f32_16x16x32_bf16 v[122:125], v[162:165], v[186:189], v[122:125]
	v_mfma_f32_16x16x32_bf16 v[118:121], v[154:157], v[194:197], v[118:121]
	v_mfma_f32_16x16x32_bf16 v[110:113], v[162:165], v[194:197], v[110:113]
	v_mfma_f32_16x16x32_bf16 v[102:105], v[154:157], v[202:205], v[102:105]
	v_mfma_f32_16x16x32_bf16 v[94:97], v[162:165], v[202:205], v[94:97]
	v_mfma_f32_16x16x32_bf16 v[86:89], v[154:157], v[210:213], v[86:89]
	v_mfma_f32_16x16x32_bf16 v[78:81], v[162:165], v[210:213], v[78:81]
	s_setprio 0
	s_setprio 1
	v_mfma_f32_16x16x32_bf16 v[114:117], v[166:169], v[182:185], v[114:117]
	v_mfma_f32_16x16x32_bf16 v[106:109], v[174:177], v[182:185], v[106:109]
	v_mfma_f32_16x16x32_bf16 v[98:101], v[166:169], v[190:193], v[98:101]
	v_mfma_f32_16x16x32_bf16 v[90:93], v[174:177], v[190:193], v[90:93]
	v_mfma_f32_16x16x32_bf16 v[82:85], v[166:169], v[198:201], v[82:85]
	v_mfma_f32_16x16x32_bf16 v[74:77], v[174:177], v[198:201], v[74:77]
	v_mfma_f32_16x16x32_bf16 v[70:73], v[166:169], v[206:209], v[70:73]
	v_mfma_f32_16x16x32_bf16 v[66:69], v[174:177], v[206:209], v[66:69]
	v_mfma_f32_16x16x32_bf16 v[114:117], v[170:173], v[186:189], v[114:117]
	v_mfma_f32_16x16x32_bf16 v[106:109], v[178:181], v[186:189], v[106:109]
	v_mfma_f32_16x16x32_bf16 v[98:101], v[170:173], v[194:197], v[98:101]
	v_mfma_f32_16x16x32_bf16 v[90:93], v[178:181], v[194:197], v[90:93]
	v_mfma_f32_16x16x32_bf16 v[82:85], v[170:173], v[202:205], v[82:85]
	v_mfma_f32_16x16x32_bf16 v[74:77], v[178:181], v[202:205], v[74:77]
	v_mfma_f32_16x16x32_bf16 v[70:73], v[170:173], v[210:213], v[70:73]
	v_mfma_f32_16x16x32_bf16 v[66:69], v[178:181], v[210:213], v[66:69]
	s_setprio 0
	s_barrier
	s_mov_b32 m0, s27
	v_lshl_add_u64 v[214:215], v[214:215], 0, s[12:13]
	s_add_u32 s18, s18, 0x20080
	ds_read_b128 v[182:185], v146 offset:49152
	ds_read_b128 v[186:189], v146 offset:50176
	ds_read_b128 v[190:193], v146 offset:51200
	ds_read_b128 v[194:197], v146 offset:52224
	ds_read_b128 v[198:201], v146 offset:53248
	ds_read_b128 v[202:205], v146 offset:54272
	ds_read_b128 v[206:209], v146 offset:55296
	ds_read_b128 v[210:213], v146 offset:56320
	global_load_lds_dwordx4 v[214:215], off
	v_lshl_add_u64 v[214:215], v[216:217], 0, s[12:13]
	s_mov_b32 m0, s47
	s_addc_u32 s19, s19, 0
	global_load_lds_dwordx4 v[214:215], off
	v_lshl_add_u64 v[214:215], s[18:19], 0, v[130:131]
	s_mov_b32 m0, s30
	s_nop 0
	global_load_lds_dwordx4 v[214:215], off
	v_lshl_add_u64 v[214:215], s[18:19], 0, v[136:137]
	s_mov_b32 m0, s48
	s_nop 0
	global_load_lds_dwordx4 v[214:215], off
	v_lshl_add_u64 v[214:215], v[218:219], 0, s[12:13]
	s_mov_b32 m0, s38
	s_nop 0
	global_load_lds_dwordx4 v[214:215], off
	v_lshl_add_u64 v[214:215], v[220:221], 0, s[12:13]
	s_mov_b32 m0, s39
	s_nop 0
	global_load_lds_dwordx4 v[214:215], off
	s_waitcnt vmcnt(8)
	s_waitcnt lgkmcnt(0)
	s_barrier
	s_setprio 1
	v_mfma_f32_16x16x32_bf16 v[62:65], v[150:153], v[182:185], v[62:65]
	v_mfma_f32_16x16x32_bf16 v[58:61], v[158:161], v[182:185], v[58:61]
	v_mfma_f32_16x16x32_bf16 v[54:57], v[150:153], v[190:193], v[54:57]
	v_mfma_f32_16x16x32_bf16 v[46:49], v[158:161], v[190:193], v[46:49]
	v_mfma_f32_16x16x32_bf16 v[38:41], v[150:153], v[198:201], v[38:41]
	v_mfma_f32_16x16x32_bf16 v[30:33], v[158:161], v[198:201], v[30:33]
	v_mfma_f32_16x16x32_bf16 v[22:25], v[150:153], v[206:209], v[22:25]
	v_mfma_f32_16x16x32_bf16 v[14:17], v[158:161], v[206:209], v[14:17]
	v_mfma_f32_16x16x32_bf16 v[62:65], v[154:157], v[186:189], v[62:65]
	v_mfma_f32_16x16x32_bf16 v[58:61], v[162:165], v[186:189], v[58:61]
	v_mfma_f32_16x16x32_bf16 v[54:57], v[154:157], v[194:197], v[54:57]
	v_mfma_f32_16x16x32_bf16 v[46:49], v[162:165], v[194:197], v[46:49]
	v_mfma_f32_16x16x32_bf16 v[38:41], v[154:157], v[202:205], v[38:41]
	v_mfma_f32_16x16x32_bf16 v[30:33], v[162:165], v[202:205], v[30:33]
	v_mfma_f32_16x16x32_bf16 v[22:25], v[154:157], v[210:213], v[22:25]
	v_mfma_f32_16x16x32_bf16 v[14:17], v[162:165], v[210:213], v[14:17]
	s_setprio 0
	s_setprio 1
	v_mfma_f32_16x16x32_bf16 v[50:53], v[166:169], v[182:185], v[50:53]
	v_mfma_f32_16x16x32_bf16 v[42:45], v[174:177], v[182:185], v[42:45]
	v_mfma_f32_16x16x32_bf16 v[34:37], v[166:169], v[190:193], v[34:37]
	v_mfma_f32_16x16x32_bf16 v[26:29], v[174:177], v[190:193], v[26:29]
	v_mfma_f32_16x16x32_bf16 v[18:21], v[166:169], v[198:201], v[18:21]
	v_mfma_f32_16x16x32_bf16 v[10:13], v[174:177], v[198:201], v[10:13]
	v_mfma_f32_16x16x32_bf16 v[6:9], v[166:169], v[206:209], v[6:9]
	v_mfma_f32_16x16x32_bf16 v[2:5], v[174:177], v[206:209], v[2:5]
	v_mfma_f32_16x16x32_bf16 v[50:53], v[170:173], v[186:189], v[50:53]
	v_mfma_f32_16x16x32_bf16 v[42:45], v[178:181], v[186:189], v[42:45]
	v_mfma_f32_16x16x32_bf16 v[34:37], v[170:173], v[194:197], v[34:37]
	v_mfma_f32_16x16x32_bf16 v[26:29], v[178:181], v[194:197], v[26:29]
	v_mfma_f32_16x16x32_bf16 v[18:21], v[170:173], v[202:205], v[18:21]
	v_mfma_f32_16x16x32_bf16 v[10:13], v[178:181], v[202:205], v[10:13]
	v_mfma_f32_16x16x32_bf16 v[6:9], v[170:173], v[210:213], v[6:9]
	v_mfma_f32_16x16x32_bf16 v[2:5], v[178:181], v[210:213], v[2:5]
	s_setprio 0
	s_barrier
	s_add_i32 s42, s42, 2
	s_add_u32 s16, s16, 0x100
	s_addc_u32 s17, s17, 0
	s_cmp_gt_u32 s42, 5
	s_cbranch_scc0 .LBB0_274
	s_cmpk_lt_u32 s31, 0x100
	s_cbranch_scc0 .LBB0_277
	s_barrier

.Lpj_skip1_p:
	s_waitcnt lgkmcnt(0)
	s_barrier
	s_setprio 1
	v_mfma_f32_16x16x32_bf16 v[128:131], v[154:157], v[196:199], 0
	v_mfma_f32_16x16x32_bf16 v[124:127], v[172:175], v[196:199], 0
	v_mfma_f32_16x16x32_bf16 v[116:119], v[154:157], v[204:207], 0
	v_mfma_f32_16x16x32_bf16 v[108:111], v[172:175], v[204:207], 0
	v_mfma_f32_16x16x32_bf16 v[100:103], v[154:157], v[212:215], 0
	v_mfma_f32_16x16x32_bf16 v[92:95], v[172:175], v[212:215], 0
	v_mfma_f32_16x16x32_bf16 v[84:87], v[154:157], v[220:223], 0
	v_mfma_f32_16x16x32_bf16 v[76:79], v[172:175], v[220:223], 0
	v_mfma_f32_16x16x32_bf16 v[128:131], v[168:171], v[200:203], v[128:131]
	v_mfma_f32_16x16x32_bf16 v[124:127], v[176:179], v[200:203], v[124:127]
	v_mfma_f32_16x16x32_bf16 v[116:119], v[168:171], v[208:211], v[116:119]
	v_mfma_f32_16x16x32_bf16 v[108:111], v[176:179], v[208:211], v[108:111]
	v_mfma_f32_16x16x32_bf16 v[100:103], v[168:171], v[216:219], v[100:103]
	v_mfma_f32_16x16x32_bf16 v[92:95], v[176:179], v[216:219], v[92:95]
	v_mfma_f32_16x16x32_bf16 v[84:87], v[168:171], v[224:227], v[84:87]
	v_mfma_f32_16x16x32_bf16 v[76:79], v[176:179], v[224:227], v[76:79]
	v_mfma_f32_16x16x32_bf16 v[120:123], v[180:183], v[196:199], 0
	v_mfma_f32_16x16x32_bf16 v[112:115], v[188:191], v[196:199], 0
	v_mfma_f32_16x16x32_bf16 v[104:107], v[180:183], v[204:207], 0
	v_mfma_f32_16x16x32_bf16 v[96:99], v[188:191], v[204:207], 0
	v_mfma_f32_16x16x32_bf16 v[88:91], v[180:183], v[212:215], 0
	v_mfma_f32_16x16x32_bf16 v[80:83], v[188:191], v[212:215], 0
	v_mfma_f32_16x16x32_bf16 v[72:75], v[180:183], v[220:223], 0
	v_mfma_f32_16x16x32_bf16 v[68:71], v[188:191], v[220:223], 0
	v_mfma_f32_16x16x32_bf16 v[120:123], v[184:187], v[200:203], v[120:123]
	v_mfma_f32_16x16x32_bf16 v[112:115], v[192:195], v[200:203], v[112:115]
	v_mfma_f32_16x16x32_bf16 v[104:107], v[184:187], v[208:211], v[104:107]
	v_mfma_f32_16x16x32_bf16 v[96:99], v[192:195], v[208:211], v[96:99]
	v_mfma_f32_16x16x32_bf16 v[88:91], v[184:187], v[216:219], v[88:91]
	v_mfma_f32_16x16x32_bf16 v[80:83], v[192:195], v[216:219], v[80:83]
	v_mfma_f32_16x16x32_bf16 v[72:75], v[184:187], v[224:227], v[72:75]
	v_mfma_f32_16x16x32_bf16 v[68:71], v[192:195], v[224:227], v[68:71]
	s_setprio 0
	s_barrier
	s_add_i32 s43, s50, s10
	s_mov_b32 m0, s43
	ds_read_b128 v[196:199], v167 offset:16384
	ds_read_b128 v[200:203], v167 offset:17408
	ds_read_b128 v[204:207], v167 offset:18432
	ds_read_b128 v[208:211], v167 offset:19456
	ds_read_b128 v[212:215], v167 offset:20480
	ds_read_b128 v[216:219], v167 offset:21504
	ds_read_b128 v[220:223], v167 offset:22528
	ds_read_b128 v[224:227], v167 offset:23552
	global_load_lds_dwordx4 v2, s[46:47]
	s_add_i32 m0, s43, 0x2000
	s_add_u32 s50, s46, 0x80000
	s_addc_u32 s51, s47, 0
	s_add_i32 s33, s33, s10
	global_load_lds_dwordx4 v0, s[46:47]
	s_mov_b32 m0, s33
	s_nop 0
	global_load_lds_dwordx4 v2, s[50:51]
	s_add_i32 m0, s33, 0x2000
	s_nop 0
	global_load_lds_dwordx4 v0, s[50:51]
	s_mov_b32 m0, s12
	s_nop 0
	global_load_lds_dwordx4 v134, s[48:49]
	s_mov_b32 m0, s13
	s_nop 0
	global_load_lds_dwordx4 v132, s[48:49]
	s_cmp_lg_u32 s32, 0
	s_cbranch_scc1 .Lpj_skip2_p
	s_waitcnt vmcnt(8)
.Lpj_skip2_p:
	s_mov_b32 s32, 0
	s_waitcnt lgkmcnt(0)
	s_barrier
	s_setprio 1
	v_mfma_f32_16x16x32_bf16 v[64:67], v[154:157], v[196:199], 0
	v_mfma_f32_16x16x32_bf16 v[60:63], v[172:175], v[196:199], 0
	v_mfma_f32_16x16x32_bf16 v[52:55], v[154:157], v[204:207], 0
	v_mfma_f32_16x16x32_bf16 v[44:47], v[172:175], v[204:207], 0
	v_mfma_f32_16x16x32_bf16 v[36:39], v[154:157], v[212:215], 0
	v_mfma_f32_16x16x32_bf16 v[28:31], v[172:175], v[212:215], 0
	v_mfma_f32_16x16x32_bf16 v[20:23], v[154:157], v[220:223], 0
	v_mfma_f32_16x16x32_bf16 v[12:15], v[172:175], v[220:223], 0
	v_mfma_f32_16x16x32_bf16 v[64:67], v[168:171], v[200:203], v[64:67]
	v_mfma_f32_16x16x32_bf16 v[60:63], v[176:179], v[200:203], v[60:63]
	v_mfma_f32_16x16x32_bf16 v[52:55], v[168:171], v[208:211], v[52:55]
	v_mfma_f32_16x16x32_bf16 v[44:47], v[176:179], v[208:211], v[44:47]
	v_mfma_f32_16x16x32_bf16 v[36:39], v[168:171], v[216:219], v[36:39]
	v_mfma_f32_16x16x32_bf16 v[28:31], v[176:179], v[216:219], v[28:31]
	v_mfma_f32_16x16x32_bf16 v[20:23], v[168:171], v[224:227], v[20:23]
	v_mfma_f32_16x16x32_bf16 v[12:15], v[176:179], v[224:227], v[12:15]
	v_mfma_f32_16x16x32_bf16 v[56:59], v[180:183], v[196:199], 0
	v_mfma_f32_16x16x32_bf16 v[48:51], v[188:191], v[196:199], 0
	v_mfma_f32_16x16x32_bf16 v[40:43], v[180:183], v[204:207], 0
	v_mfma_f32_16x16x32_bf16 v[32:35], v[188:191], v[204:207], 0
	v_mfma_f32_16x16x32_bf16 v[24:27], v[180:183], v[212:215], 0
	v_mfma_f32_16x16x32_bf16 v[16:19], v[188:191], v[212:215], 0
	v_mfma_f32_16x16x32_bf16 v[8:11], v[180:183], v[220:223], 0
	v_mfma_f32_16x16x32_bf16 v[4:7], v[188:191], v[220:223], 0
	v_mfma_f32_16x16x32_bf16 v[56:59], v[184:187], v[200:203], v[56:59]
	v_mfma_f32_16x16x32_bf16 v[48:51], v[192:195], v[200:203], v[48:51]
	v_mfma_f32_16x16x32_bf16 v[40:43], v[184:187], v[208:211], v[40:43]
	v_mfma_f32_16x16x32_bf16 v[32:35], v[192:195], v[208:211], v[32:35]
	v_mfma_f32_16x16x32_bf16 v[24:27], v[184:187], v[216:219], v[24:27]
	v_mfma_f32_16x16x32_bf16 v[16:19], v[192:195], v[216:219], v[16:19]
	v_mfma_f32_16x16x32_bf16 v[8:11], v[184:187], v[224:227], v[8:11]
	v_mfma_f32_16x16x32_bf16 v[4:7], v[192:195], v[224:227], v[4:7]
	s_setprio 0
	s_barrier
	s_add_i32 s33, 0, 0x18000
	v_add_u32_e32 v144, s33, v149
	s_add_i32 s43, 0, 0x1c000
	ds_read_b128 v[154:157], v144
	ds_read_b128 v[168:171], v144 offset:1024
	ds_read_b128 v[172:175], v144 offset:2048
	ds_read_b128 v[176:179], v144 offset:3072
	v_add_u32_e32 v144, s43, v149
	ds_read_b128 v[180:183], v144
	ds_read_b128 v[184:187], v144 offset:1024
	ds_read_b128 v[188:191], v144 offset:2048
	ds_read_b128 v[192:195], v144 offset:3072
	s_add_u32 s48, s48, 0x80000
	s_addc_u32 s49, s49, 0
	s_mov_b32 m0, s14
	ds_read_b128 v[196:199], v167 offset:32768
	ds_read_b128 v[200:203], v167 offset:33792
	ds_read_b128 v[204:207], v167 offset:34816
	ds_read_b128 v[208:211], v167 offset:35840
	ds_read_b128 v[212:215], v167 offset:36864
	ds_read_b128 v[216:219], v167 offset:37888
	ds_read_b128 v[220:223], v167 offset:38912
	ds_read_b128 v[224:227], v167 offset:39936
	global_load_lds_dwordx4 v134, s[48:49]
	s_mov_b32 m0, s15
	s_nop 0
	global_load_lds_dwordx4 v132, s[48:49]
	s_waitcnt vmcnt(8)
	s_waitcnt lgkmcnt(0)
	s_barrier
	s_setprio 1
	v_mfma_f32_16x16x32_bf16 v[128:131], v[154:157], v[196:199], v[128:131]
	v_mfma_f32_16x16x32_bf16 v[124:127], v[172:175], v[196:199], v[124:127]
	v_mfma_f32_16x16x32_bf16 v[116:119], v[154:157], v[204:207], v[116:119]
	v_mfma_f32_16x16x32_bf16 v[108:111], v[172:175], v[204:207], v[108:111]
	v_mfma_f32_16x16x32_bf16 v[100:103], v[154:157], v[212:215], v[100:103]
	v_mfma_f32_16x16x32_bf16 v[92:95], v[172:175], v[212:215], v[92:95]
	v_mfma_f32_16x16x32_bf16 v[84:87], v[154:157], v[220:223], v[84:87]
	v_mfma_f32_16x16x32_bf16 v[76:79], v[172:175], v[220:223], v[76:79]
	v_mfma_f32_16x16x32_bf16 v[128:131], v[168:171], v[200:203], v[128:131]
	v_mfma_f32_16x16x32_bf16 v[124:127], v[176:179], v[200:203], v[124:127]
	v_mfma_f32_16x16x32_bf16 v[116:119], v[168:171], v[208:211], v[116:119]
	v_mfma_f32_16x16x32_bf16 v[108:111], v[176:179], v[208:211], v[108:111]
	v_mfma_f32_16x16x32_bf16 v[100:103], v[168:171], v[216:219], v[100:103]
	v_mfma_f32_16x16x32_bf16 v[92:95], v[176:179], v[216:219], v[92:95]
	v_mfma_f32_16x16x32_bf16 v[84:87], v[168:171], v[224:227], v[84:87]
	v_mfma_f32_16x16x32_bf16 v[76:79], v[176:179], v[224:227], v[76:79]
	v_mfma_f32_16x16x32_bf16 v[120:123], v[180:183], v[196:199], v[120:123]
	v_mfma_f32_16x16x32_bf16 v[112:115], v[188:191], v[196:199], v[112:115]
	v_mfma_f32_16x16x32_bf16 v[104:107], v[180:183], v[204:207], v[104:107]
	v_mfma_f32_16x16x32_bf16 v[96:99], v[188:191], v[204:207], v[96:99]
	v_mfma_f32_16x16x32_bf16 v[88:91], v[180:183], v[212:215], v[88:91]
	v_mfma_f32_16x16x32_bf16 v[80:83], v[188:191], v[212:215], v[80:83]
	v_mfma_f32_16x16x32_bf16 v[72:75], v[180:183], v[220:223], v[72:75]
	v_mfma_f32_16x16x32_bf16 v[68:71], v[188:191], v[220:223], v[68:71]
	v_mfma_f32_16x16x32_bf16 v[120:123], v[184:187], v[200:203], v[120:123]
	v_mfma_f32_16x16x32_bf16 v[112:115], v[192:195], v[200:203], v[112:115]
	v_mfma_f32_16x16x32_bf16 v[104:107], v[184:187], v[208:211], v[104:107]
	v_mfma_f32_16x16x32_bf16 v[96:99], v[192:195], v[208:211], v[96:99]
	v_mfma_f32_16x16x32_bf16 v[88:91], v[184:187], v[216:219], v[88:91]
	v_mfma_f32_16x16x32_bf16 v[80:83], v[192:195], v[216:219], v[80:83]
	v_mfma_f32_16x16x32_bf16 v[72:75], v[184:187], v[224:227], v[72:75]
	v_mfma_f32_16x16x32_bf16 v[68:71], v[192:195], v[224:227], v[68:71]
	s_setprio 0
	s_barrier
	s_add_i32 s33, s33, s10
	s_mov_b32 m0, s33
	ds_read_b128 v[196:199], v167 offset:49152
	ds_read_b128 v[200:203], v167 offset:50176
	ds_read_b128 v[204:207], v167 offset:51200
	ds_read_b128 v[208:211], v167 offset:52224
	ds_read_b128 v[212:215], v167 offset:53248
	ds_read_b128 v[216:219], v167 offset:54272
	ds_read_b128 v[220:223], v167 offset:55296
	ds_read_b128 v[224:227], v167 offset:56320
	s_add_u32 s100, s46, 0x80
	s_addc_u32 s101, s47, 0
	global_load_lds_dwordx4 v2, s[100:101]
	s_add_i32 m0, s33, 0x2000
	s_add_u32 s46, s46, 0x80080
	s_addc_u32 s47, s47, 0
	s_add_i32 s33, s43, s10
	s_add_u32 s100, s46, 0xfff80000
	s_addc_u32 s101, s47, -1
	global_load_lds_dwordx4 v0, s[100:101]
	s_mov_b32 m0, s33
	s_nop 0
	global_load_lds_dwordx4 v2, s[46:47]
	s_add_i32 m0, s33, 0x2000
	s_nop 0
	global_load_lds_dwordx4 v0, s[46:47]
	s_mov_b32 m0, s16
	s_nop 0
	s_add_u32 s100, s48, 0xfff80080
	s_addc_u32 s101, s49, -1
	global_load_lds_dwordx4 v134, s[100:101]
	s_mov_b32 m0, s17
	s_nop 0
	s_add_u32 s100, s48, 0xfff80080
	s_addc_u32 s101, s49, -1
	global_load_lds_dwordx4 v132, s[100:101]
	s_waitcnt vmcnt(8)
	s_waitcnt lgkmcnt(0)
	s_barrier
	s_setprio 1
	v_mfma_f32_16x16x32_bf16 v[64:67], v[154:157], v[196:199], v[64:67]
	v_mfma_f32_16x16x32_bf16 v[60:63], v[172:175], v[196:199], v[60:63]
	v_mfma_f32_16x16x32_bf16 v[52:55], v[154:157], v[204:207], v[52:55]
	v_mfma_f32_16x16x32_bf16 v[44:47], v[172:175], v[204:207], v[44:47]
	v_mfma_f32_16x16x32_bf16 v[36:39], v[154:157], v[212:215], v[36:39]
	v_mfma_f32_16x16x32_bf16 v[28:31], v[172:175], v[212:215], v[28:31]
	v_mfma_f32_16x16x32_bf16 v[20:23], v[154:157], v[220:223], v[20:23]
	v_mfma_f32_16x16x32_bf16 v[12:15], v[172:175], v[220:223], v[12:15]
	v_mfma_f32_16x16x32_bf16 v[64:67], v[168:171], v[200:203], v[64:67]
	v_mfma_f32_16x16x32_bf16 v[60:63], v[176:179], v[200:203], v[60:63]
	v_mfma_f32_16x16x32_bf16 v[52:55], v[168:171], v[208:211], v[52:55]
	v_mfma_f32_16x16x32_bf16 v[44:47], v[176:179], v[208:211], v[44:47]
	v_mfma_f32_16x16x32_bf16 v[36:39], v[168:171], v[216:219], v[36:39]
	v_mfma_f32_16x16x32_bf16 v[28:31], v[176:179], v[216:219], v[28:31]
	v_mfma_f32_16x16x32_bf16 v[20:23], v[168:171], v[224:227], v[20:23]
	v_mfma_f32_16x16x32_bf16 v[12:15], v[176:179], v[224:227], v[12:15]
	v_mfma_f32_16x16x32_bf16 v[56:59], v[180:183], v[196:199], v[56:59]
	v_mfma_f32_16x16x32_bf16 v[48:51], v[188:191], v[196:199], v[48:51]
	v_mfma_f32_16x16x32_bf16 v[40:43], v[180:183], v[204:207], v[40:43]
	v_mfma_f32_16x16x32_bf16 v[32:35], v[188:191], v[204:207], v[32:35]
	v_mfma_f32_16x16x32_bf16 v[24:27], v[180:183], v[212:215], v[24:27]
	v_mfma_f32_16x16x32_bf16 v[16:19], v[188:191], v[212:215], v[16:19]
	v_mfma_f32_16x16x32_bf16 v[8:11], v[180:183], v[220:223], v[8:11]
	v_mfma_f32_16x16x32_bf16 v[4:7], v[188:191], v[220:223], v[4:7]
	v_mfma_f32_16x16x32_bf16 v[56:59], v[184:187], v[200:203], v[56:59]
	v_mfma_f32_16x16x32_bf16 v[48:51], v[192:195], v[200:203], v[48:51]
	v_mfma_f32_16x16x32_bf16 v[40:43], v[184:187], v[208:211], v[40:43]
	v_mfma_f32_16x16x32_bf16 v[32:35], v[192:195], v[208:211], v[32:35]
	v_mfma_f32_16x16x32_bf16 v[24:27], v[184:187], v[216:219], v[24:27]
	v_mfma_f32_16x16x32_bf16 v[16:19], v[192:195], v[216:219], v[16:19]
	v_mfma_f32_16x16x32_bf16 v[8:11], v[184:187], v[224:227], v[8:11]
	v_mfma_f32_16x16x32_bf16 v[4:7], v[192:195], v[224:227], v[4:7]
	s_setprio 0
	s_barrier
	s_add_i32 s35, s35, 2
	s_add_u32 s31, s31, 0x100
	s_addc_u32 s34, s34, 0
	s_add_u32 s44, s44, 0x100
	s_addc_u32 s45, s45, 0
	s_cmp_gt_u32 s35, 29
.LBB0_342:
	s_add_u32 s33, s44, 0xfff80080
	s_addc_u32 s43, s45, -1
	s_add_i32 s50, 0, 0x10000
	s_cmp_eq_u32 s35, 28
	s_cselect_b32 s49, s27, s43
	s_cselect_b32 s48, s28, s33
	v_add_u32_e32 v142, s50, v149
	s_cselect_b32 s47, s25, s34
	s_cselect_b32 s46, s29, s31
	s_add_i32 s33, 0, 0x14000
	ds_read_b128 v[154:157], v142
	ds_read_b128 v[168:171], v142 offset:1024
	ds_read_b128 v[172:175], v142 offset:2048
	ds_read_b128 v[176:179], v142 offset:3072
	v_add_u32_e32 v142, s33, v149
	ds_read_b128 v[180:183], v142
	ds_read_b128 v[184:187], v142 offset:1024
	ds_read_b128 v[188:191], v142 offset:2048
	ds_read_b128 v[192:195], v142 offset:3072
	s_add_i32 m0, s12, 0xc000
	ds_read_b128 v[196:199], v167
	ds_read_b128 v[200:203], v167 offset:1024
	ds_read_b128 v[204:207], v167 offset:2048
	ds_read_b128 v[208:211], v167 offset:3072
	ds_read_b128 v[212:215], v167 offset:4096
	ds_read_b128 v[216:219], v167 offset:5120
	ds_read_b128 v[220:223], v167 offset:6144
	ds_read_b128 v[224:227], v167 offset:7168
	global_load_lds_dwordx4 v140, s[44:45]
	s_add_i32 m0, s12, 0xe000
	s_nop 0
	global_load_lds_dwordx4 v138, s[44:45]
	s_waitcnt vmcnt(8)
	s_waitcnt lgkmcnt(0)
	s_barrier
	s_setprio 1
	v_mfma_f32_16x16x32_bf16 v[128:131], v[154:157], v[196:199], v[128:131]
	v_mfma_f32_16x16x32_bf16 v[124:127], v[172:175], v[196:199], v[124:127]
	v_mfma_f32_16x16x32_bf16 v[116:119], v[154:157], v[204:207], v[116:119]
	v_mfma_f32_16x16x32_bf16 v[108:111], v[172:175], v[204:207], v[108:111]
	v_mfma_f32_16x16x32_bf16 v[100:103], v[154:157], v[212:215], v[100:103]
	v_mfma_f32_16x16x32_bf16 v[92:95], v[172:175], v[212:215], v[92:95]
	v_mfma_f32_16x16x32_bf16 v[84:87], v[154:157], v[220:223], v[84:87]
	v_mfma_f32_16x16x32_bf16 v[76:79], v[172:175], v[220:223], v[76:79]
	v_mfma_f32_16x16x32_bf16 v[128:131], v[168:171], v[200:203], v[128:131]
	v_mfma_f32_16x16x32_bf16 v[124:127], v[176:179], v[200:203], v[124:127]
	v_mfma_f32_16x16x32_bf16 v[116:119], v[168:171], v[208:211], v[116:119]
	v_mfma_f32_16x16x32_bf16 v[108:111], v[176:179], v[208:211], v[108:111]
	v_mfma_f32_16x16x32_bf16 v[100:103], v[168:171], v[216:219], v[100:103]
	v_mfma_f32_16x16x32_bf16 v[92:95], v[176:179], v[216:219], v[92:95]
	v_mfma_f32_16x16x32_bf16 v[84:87], v[168:171], v[224:227], v[84:87]
	v_mfma_f32_16x16x32_bf16 v[76:79], v[176:179], v[224:227], v[76:79]
	v_mfma_f32_16x16x32_bf16 v[120:123], v[180:183], v[196:199], v[120:123]
	v_mfma_f32_16x16x32_bf16 v[112:115], v[188:191], v[196:199], v[112:115]
	v_mfma_f32_16x16x32_bf16 v[104:107], v[180:183], v[204:207], v[104:107]
	v_mfma_f32_16x16x32_bf16 v[96:99], v[188:191], v[204:207], v[96:99]
	v_mfma_f32_16x16x32_bf16 v[88:91], v[180:183], v[212:215], v[88:91]
	v_mfma_f32_16x16x32_bf16 v[80:83], v[188:191], v[212:215], v[80:83]
	v_mfma_f32_16x16x32_bf16 v[72:75], v[180:183], v[220:223], v[72:75]
	v_mfma_f32_16x16x32_bf16 v[68:71], v[188:191], v[220:223], v[68:71]
	v_mfma_f32_16x16x32_bf16 v[120:123], v[184:187], v[200:203], v[120:123]
	v_mfma_f32_16x16x32_bf16 v[112:115], v[192:195], v[200:203], v[112:115]
	v_mfma_f32_16x16x32_bf16 v[104:107], v[184:187], v[208:211], v[104:107]
	v_mfma_f32_16x16x32_bf16 v[96:99], v[192:195], v[208:211], v[96:99]
	v_mfma_f32_16x16x32_bf16 v[88:91], v[184:187], v[216:219], v[88:91]
	v_mfma_f32_16x16x32_bf16 v[80:83], v[192:195], v[216:219], v[80:83]
	v_mfma_f32_16x16x32_bf16 v[72:75], v[184:187], v[224:227], v[72:75]
	v_mfma_f32_16x16x32_bf16 v[68:71], v[192:195], v[224:227], v[68:71]
	s_setprio 0
	s_barrier
	s_add_i32 s43, s50, s10
	s_mov_b32 m0, s43
	ds_read_b128 v[196:199], v167 offset:16384
	ds_read_b128 v[200:203], v167 offset:17408
	ds_read_b128 v[204:207], v167 offset:18432
	ds_read_b128 v[208:211], v167 offset:19456
	ds_read_b128 v[212:215], v167 offset:20480
	ds_read_b128 v[216:219], v167 offset:21504
	ds_read_b128 v[220:223], v167 offset:22528
	ds_read_b128 v[224:227], v167 offset:23552
	global_load_lds_dwordx4 v2, s[46:47]
	s_add_i32 m0, s43, 0x2000
	s_add_u32 s50, s46, 0x80000
	s_addc_u32 s51, s47, 0
	s_add_i32 s33, s33, s10
	global_load_lds_dwordx4 v0, s[46:47]
	s_mov_b32 m0, s33
	s_nop 0
	global_load_lds_dwordx4 v2, s[50:51]
	s_add_i32 m0, s33, 0x2000
	s_nop 0
	global_load_lds_dwordx4 v0, s[50:51]
	s_mov_b32 m0, s12
	s_nop 0
	global_load_lds_dwordx4 v134, s[48:49]
	s_mov_b32 m0, s13
	s_nop 0
	global_load_lds_dwordx4 v132, s[48:49]
	s_waitcnt vmcnt(8)
	s_waitcnt lgkmcnt(0)
	s_barrier
	s_setprio 1
	v_mfma_f32_16x16x32_bf16 v[64:67], v[154:157], v[196:199], v[64:67]
	v_mfma_f32_16x16x32_bf16 v[60:63], v[172:175], v[196:199], v[60:63]
	v_mfma_f32_16x16x32_bf16 v[52:55], v[154:157], v[204:207], v[52:55]
	v_mfma_f32_16x16x32_bf16 v[44:47], v[172:175], v[204:207], v[44:47]
	v_mfma_f32_16x16x32_bf16 v[36:39], v[154:157], v[212:215], v[36:39]
	v_mfma_f32_16x16x32_bf16 v[28:31], v[172:175], v[212:215], v[28:31]
	v_mfma_f32_16x16x32_bf16 v[20:23], v[154:157], v[220:223], v[20:23]
	v_mfma_f32_16x16x32_bf16 v[12:15], v[172:175], v[220:223], v[12:15]
	v_mfma_f32_16x16x32_bf16 v[64:67], v[168:171], v[200:203], v[64:67]
	v_mfma_f32_16x16x32_bf16 v[60:63], v[176:179], v[200:203], v[60:63]
	v_mfma_f32_16x16x32_bf16 v[52:55], v[168:171], v[208:211], v[52:55]
	v_mfma_f32_16x16x32_bf16 v[44:47], v[176:179], v[208:211], v[44:47]
	v_mfma_f32_16x16x32_bf16 v[36:39], v[168:171], v[216:219], v[36:39]
	v_mfma_f32_16x16x32_bf16 v[28:31], v[176:179], v[216:219], v[28:31]
	v_mfma_f32_16x16x32_bf16 v[20:23], v[168:171], v[224:227], v[20:23]
	v_mfma_f32_16x16x32_bf16 v[12:15], v[176:179], v[224:227], v[12:15]
	v_mfma_f32_16x16x32_bf16 v[56:59], v[180:183], v[196:199], v[56:59]
	v_mfma_f32_16x16x32_bf16 v[48:51], v[188:191], v[196:199], v[48:51]
	v_mfma_f32_16x16x32_bf16 v[40:43], v[180:183], v[204:207], v[40:43]
	v_mfma_f32_16x16x32_bf16 v[32:35], v[188:191], v[204:207], v[32:35]
	v_mfma_f32_16x16x32_bf16 v[24:27], v[180:183], v[212:215], v[24:27]
	v_mfma_f32_16x16x32_bf16 v[16:19], v[188:191], v[212:215], v[16:19]
	v_mfma_f32_16x16x32_bf16 v[8:11], v[180:183], v[220:223], v[8:11]
	v_mfma_f32_16x16x32_bf16 v[4:7], v[188:191], v[220:223], v[4:7]
	v_mfma_f32_16x16x32_bf16 v[56:59], v[184:187], v[200:203], v[56:59]
	v_mfma_f32_16x16x32_bf16 v[48:51], v[192:195], v[200:203], v[48:51]
	v_mfma_f32_16x16x32_bf16 v[40:43], v[184:187], v[208:211], v[40:43]
	v_mfma_f32_16x16x32_bf16 v[32:35], v[192:195], v[208:211], v[32:35]
	v_mfma_f32_16x16x32_bf16 v[24:27], v[184:187], v[216:219], v[24:27]
	v_mfma_f32_16x16x32_bf16 v[16:19], v[192:195], v[216:219], v[16:19]
	v_mfma_f32_16x16x32_bf16 v[8:11], v[184:187], v[224:227], v[8:11]
	v_mfma_f32_16x16x32_bf16 v[4:7], v[192:195], v[224:227], v[4:7]
	s_setprio 0
	s_barrier
	s_add_i32 s33, 0, 0x18000
	v_add_u32_e32 v144, s33, v149
	s_add_i32 s43, 0, 0x1c000
	ds_read_b128 v[154:157], v144
	ds_read_b128 v[168:171], v144 offset:1024
	ds_read_b128 v[172:175], v144 offset:2048
	ds_read_b128 v[176:179], v144 offset:3072
	v_add_u32_e32 v144, s43, v149
	ds_read_b128 v[180:183], v144
	ds_read_b128 v[184:187], v144 offset:1024
	ds_read_b128 v[188:191], v144 offset:2048
	ds_read_b128 v[192:195], v144 offset:3072
	s_add_u32 s48, s48, 0x80000
	s_addc_u32 s49, s49, 0
	s_mov_b32 m0, s14
	ds_read_b128 v[196:199], v167 offset:32768
	ds_read_b128 v[200:203], v167 offset:33792
	ds_read_b128 v[204:207], v167 offset:34816
	ds_read_b128 v[208:211], v167 offset:35840
	ds_read_b128 v[212:215], v167 offset:36864
	ds_read_b128 v[216:219], v167 offset:37888
	ds_read_b128 v[220:223], v167 offset:38912
	ds_read_b128 v[224:227], v167 offset:39936
	global_load_lds_dwordx4 v134, s[48:49]
	s_mov_b32 m0, s15
	s_nop 0
	global_load_lds_dwordx4 v132, s[48:49]
	s_waitcnt vmcnt(8)
	s_waitcnt lgkmcnt(0)
	s_barrier
	s_setprio 1
	v_mfma_f32_16x16x32_bf16 v[128:131], v[154:157], v[196:199], v[128:131]
	v_mfma_f32_16x16x32_bf16 v[124:127], v[172:175], v[196:199], v[124:127]
	v_mfma_f32_16x16x32_bf16 v[116:119], v[154:157], v[204:207], v[116:119]
	v_mfma_f32_16x16x32_bf16 v[108:111], v[172:175], v[204:207], v[108:111]
	v_mfma_f32_16x16x32_bf16 v[100:103], v[154:157], v[212:215], v[100:103]
	v_mfma_f32_16x16x32_bf16 v[92:95], v[172:175], v[212:215], v[92:95]
	v_mfma_f32_16x16x32_bf16 v[84:87], v[154:157], v[220:223], v[84:87]
	v_mfma_f32_16x16x32_bf16 v[76:79], v[172:175], v[220:223], v[76:79]
	v_mfma_f32_16x16x32_bf16 v[128:131], v[168:171], v[200:203], v[128:131]
	v_mfma_f32_16x16x32_bf16 v[124:127], v[176:179], v[200:203], v[124:127]
	v_mfma_f32_16x16x32_bf16 v[116:119], v[168:171], v[208:211], v[116:119]
	v_mfma_f32_16x16x32_bf16 v[108:111], v[176:179], v[208:211], v[108:111]
	v_mfma_f32_16x16x32_bf16 v[100:103], v[168:171], v[216:219], v[100:103]
	v_mfma_f32_16x16x32_bf16 v[92:95], v[176:179], v[216:219], v[92:95]
	v_mfma_f32_16x16x32_bf16 v[84:87], v[168:171], v[224:227], v[84:87]
	v_mfma_f32_16x16x32_bf16 v[76:79], v[176:179], v[224:227], v[76:79]
	v_mfma_f32_16x16x32_bf16 v[120:123], v[180:183], v[196:199], v[120:123]
	v_mfma_f32_16x16x32_bf16 v[112:115], v[188:191], v[196:199], v[112:115]
	v_mfma_f32_16x16x32_bf16 v[104:107], v[180:183], v[204:207], v[104:107]
	v_mfma_f32_16x16x32_bf16 v[96:99], v[188:191], v[204:207], v[96:99]
	v_mfma_f32_16x16x32_bf16 v[88:91], v[180:183], v[212:215], v[88:91]
	v_mfma_f32_16x16x32_bf16 v[80:83], v[188:191], v[212:215], v[80:83]
	v_mfma_f32_16x16x32_bf16 v[72:75], v[180:183], v[220:223], v[72:75]
	v_mfma_f32_16x16x32_bf16 v[68:71], v[188:191], v[220:223], v[68:71]
	v_mfma_f32_16x16x32_bf16 v[120:123], v[184:187], v[200:203], v[120:123]
	v_mfma_f32_16x16x32_bf16 v[112:115], v[192:195], v[200:203], v[112:115]
	v_mfma_f32_16x16x32_bf16 v[104:107], v[184:187], v[208:211], v[104:107]
	v_mfma_f32_16x16x32_bf16 v[96:99], v[192:195], v[208:211], v[96:99]
	v_mfma_f32_16x16x32_bf16 v[88:91], v[184:187], v[216:219], v[88:91]
	v_mfma_f32_16x16x32_bf16 v[80:83], v[192:195], v[216:219], v[80:83]
	v_mfma_f32_16x16x32_bf16 v[72:75], v[184:187], v[224:227], v[72:75]
	v_mfma_f32_16x16x32_bf16 v[68:71], v[192:195], v[224:227], v[68:71]
	s_setprio 0
	s_barrier
	s_add_i32 s33, s33, s10
	s_mov_b32 m0, s33
	ds_read_b128 v[196:199], v167 offset:49152
	ds_read_b128 v[200:203], v167 offset:50176
	ds_read_b128 v[204:207], v167 offset:51200
	ds_read_b128 v[208:211], v167 offset:52224
	ds_read_b128 v[212:215], v167 offset:53248
	ds_read_b128 v[216:219], v167 offset:54272
	ds_read_b128 v[220:223], v167 offset:55296
	ds_read_b128 v[224:227], v167 offset:56320
	s_add_u32 s100, s46, 0x80
	s_addc_u32 s101, s47, 0
	global_load_lds_dwordx4 v2, s[100:101]
	s_add_i32 m0, s33, 0x2000
	s_add_u32 s46, s46, 0x80080
	s_addc_u32 s47, s47, 0
	s_add_i32 s33, s43, s10
	s_add_u32 s100, s46, 0xfff80000
	s_addc_u32 s101, s47, -1
	global_load_lds_dwordx4 v0, s[100:101]
	s_mov_b32 m0, s33
	s_nop 0
	global_load_lds_dwordx4 v2, s[46:47]
	s_add_i32 m0, s33, 0x2000
	s_nop 0
	global_load_lds_dwordx4 v0, s[46:47]
	s_mov_b32 m0, s16
	s_nop 0
	s_add_u32 s100, s48, 0xfff80080
	s_addc_u32 s101, s49, -1
	global_load_lds_dwordx4 v134, s[100:101]
	s_mov_b32 m0, s17
	s_nop 0
	s_add_u32 s100, s48, 0xfff80080
	s_addc_u32 s101, s49, -1
	global_load_lds_dwordx4 v132, s[100:101]
	s_waitcnt vmcnt(8)
	s_waitcnt lgkmcnt(0)
	s_barrier
	s_setprio 1
	v_mfma_f32_16x16x32_bf16 v[64:67], v[154:157], v[196:199], v[64:67]
	v_mfma_f32_16x16x32_bf16 v[60:63], v[172:175], v[196:199], v[60:63]
	v_mfma_f32_16x16x32_bf16 v[52:55], v[154:157], v[204:207], v[52:55]
	v_mfma_f32_16x16x32_bf16 v[44:47], v[172:175], v[204:207], v[44:47]
	v_mfma_f32_16x16x32_bf16 v[36:39], v[154:157], v[212:215], v[36:39]
	v_mfma_f32_16x16x32_bf16 v[28:31], v[172:175], v[212:215], v[28:31]
	v_mfma_f32_16x16x32_bf16 v[20:23], v[154:157], v[220:223], v[20:23]
	v_mfma_f32_16x16x32_bf16 v[12:15], v[172:175], v[220:223], v[12:15]
	v_mfma_f32_16x16x32_bf16 v[64:67], v[168:171], v[200:203], v[64:67]
	v_mfma_f32_16x16x32_bf16 v[60:63], v[176:179], v[200:203], v[60:63]
	v_mfma_f32_16x16x32_bf16 v[52:55], v[168:171], v[208:211], v[52:55]
	v_mfma_f32_16x16x32_bf16 v[44:47], v[176:179], v[208:211], v[44:47]
	v_mfma_f32_16x16x32_bf16 v[36:39], v[168:171], v[216:219], v[36:39]
	v_mfma_f32_16x16x32_bf16 v[28:31], v[176:179], v[216:219], v[28:31]
	v_mfma_f32_16x16x32_bf16 v[20:23], v[168:171], v[224:227], v[20:23]
	v_mfma_f32_16x16x32_bf16 v[12:15], v[176:179], v[224:227], v[12:15]
	v_mfma_f32_16x16x32_bf16 v[56:59], v[180:183], v[196:199], v[56:59]
	v_mfma_f32_16x16x32_bf16 v[48:51], v[188:191], v[196:199], v[48:51]
	v_mfma_f32_16x16x32_bf16 v[40:43], v[180:183], v[204:207], v[40:43]
	v_mfma_f32_16x16x32_bf16 v[32:35], v[188:191], v[204:207], v[32:35]
	v_mfma_f32_16x16x32_bf16 v[24:27], v[180:183], v[212:215], v[24:27]
	v_mfma_f32_16x16x32_bf16 v[16:19], v[188:191], v[212:215], v[16:19]
	v_mfma_f32_16x16x32_bf16 v[8:11], v[180:183], v[220:223], v[8:11]
	v_mfma_f32_16x16x32_bf16 v[4:7], v[188:191], v[220:223], v[4:7]
	v_mfma_f32_16x16x32_bf16 v[56:59], v[184:187], v[200:203], v[56:59]
	v_mfma_f32_16x16x32_bf16 v[48:51], v[192:195], v[200:203], v[48:51]
	v_mfma_f32_16x16x32_bf16 v[40:43], v[184:187], v[208:211], v[40:43]
	v_mfma_f32_16x16x32_bf16 v[32:35], v[192:195], v[208:211], v[32:35]
	v_mfma_f32_16x16x32_bf16 v[24:27], v[184:187], v[216:219], v[24:27]
	v_mfma_f32_16x16x32_bf16 v[16:19], v[192:195], v[216:219], v[16:19]
	v_mfma_f32_16x16x32_bf16 v[8:11], v[184:187], v[224:227], v[8:11]
	v_mfma_f32_16x16x32_bf16 v[4:7], v[192:195], v[224:227], v[4:7]
	s_setprio 0
	s_barrier
	s_add_i32 s35, s35, 2
	s_add_u32 s31, s31, 0x100
	s_addc_u32 s34, s34, 0
	s_add_u32 s44, s44, 0x100
	s_addc_u32 s45, s45, 0
	s_cmp_gt_u32 s35, 29
	s_cbranch_scc0 .LBB0_342
	s_and_b64 vcc, exec, s[22:23]
	s_cbranch_vccz .LBB0_345
	s_nop 0

.LBB0_740:
	s_mov_b32 s48, s6
	s_ashr_i32 s49, s6, 31
	s_mov_b32 s94, s7
	s_lshl_b64 s[6:7], s[48:49], 20
	s_add_u32 s56, s70, s6
	s_addc_u32 s57, s71, s7
	s_and_b64 s[6:7], exec, s[52:53]
	s_mov_b32 s50, s5
	s_cselect_b32 s5, s57, s39
	s_cselect_b32 s6, s56, s38
	s_add_u32 s60, s80, s60
	s_addc_u32 s61, s81, s61
	s_mov_b32 s67, s8
	s_and_b64 s[8:9], exec, s[52:53]
	s_cselect_b32 s7, s61, s37
	s_cselect_b32 s8, s60, s36
	s_add_u32 s9, s36, 0x100
	s_addc_u32 s10, s37, 0
	s_add_u32 s36, s38, 0x80080
	s_addc_u32 s37, s39, 0
	s_mov_b32 s11, -2
	s_waitcnt lgkmcnt(0)
	s_add_u32 s12, s36, 0xfff80080
	s_addc_u32 s13, s37, -1
	s_add_i32 s14, 0, 0x10000
	s_cmp_eq_u32 s11, 28
	s_cselect_b32 s63, s5, s13
	s_cselect_b32 s62, s6, s12
	s_cselect_b32 s39, s7, s10
	s_cselect_b32 s38, s8, s9
	s_add_i32 s15, 0, 0x14000
	v_add_u32_e32 v144, s14, v230
	v_add_u32_e32 v160, s15, v230
	ds_read_b128 v[124:127], v144
	ds_read_b128 v[128:131], v144 offset:1024
	ds_read_b128 v[136:139], v144 offset:2048
	ds_read_b128 v[144:147], v144 offset:3072
	ds_read_b128 v[148:151], v160
	ds_read_b128 v[152:155], v160 offset:1024
	ds_read_b128 v[156:159], v160 offset:2048
	ds_read_b128 v[160:163], v160 offset:3072
	v_lshl_add_u64 v[196:197], s[36:37], 0, v[222:223]
	s_add_i32 m0, s21, 0xc000
	ds_read_b128 v[164:167], v243
	ds_read_b128 v[168:171], v243 offset:1024
	ds_read_b128 v[172:175], v243 offset:2048
	ds_read_b128 v[176:179], v243 offset:3072
	ds_read_b128 v[180:183], v243 offset:4096
	ds_read_b128 v[184:187], v243 offset:5120
	ds_read_b128 v[188:191], v243 offset:6144
	ds_read_b128 v[192:195], v243 offset:7168
	global_load_lds_dwordx4 v[196:197], off
	v_lshl_add_u64 v[196:197], s[36:37], 0, v[220:221]
	s_add_i32 m0, s21, 0xe000
	s_nop 0
	global_load_lds_dwordx4 v[196:197], off
	s_waitcnt vmcnt(8)
	s_waitcnt lgkmcnt(0)
	s_barrier
	s_setprio 1
	v_mfma_f32_16x16x32_bf16 v[140:143], v[124:127], v[164:167], 0
	v_mfma_f32_16x16x32_bf16 v[132:135], v[136:139], v[164:167], 0
	v_mfma_f32_16x16x32_bf16 v[112:115], v[124:127], v[172:175], 0
	v_mfma_f32_16x16x32_bf16 v[108:111], v[136:139], v[172:175], 0
	v_mfma_f32_16x16x32_bf16 v[96:99], v[124:127], v[180:183], 0
	v_mfma_f32_16x16x32_bf16 v[92:95], v[136:139], v[180:183], 0
	v_mfma_f32_16x16x32_bf16 v[80:83], v[124:127], v[188:191], 0
	v_mfma_f32_16x16x32_bf16 v[76:79], v[136:139], v[188:191], 0
	v_mfma_f32_16x16x32_bf16 v[140:143], v[128:131], v[168:171], v[140:143]
	v_mfma_f32_16x16x32_bf16 v[132:135], v[144:147], v[168:171], v[132:135]
	v_mfma_f32_16x16x32_bf16 v[112:115], v[128:131], v[176:179], v[112:115]
	v_mfma_f32_16x16x32_bf16 v[108:111], v[144:147], v[176:179], v[108:111]
	v_mfma_f32_16x16x32_bf16 v[96:99], v[128:131], v[184:187], v[96:99]
	v_mfma_f32_16x16x32_bf16 v[92:95], v[144:147], v[184:187], v[92:95]
	v_mfma_f32_16x16x32_bf16 v[80:83], v[128:131], v[192:195], v[80:83]
	v_mfma_f32_16x16x32_bf16 v[76:79], v[144:147], v[192:195], v[76:79]
	s_setprio 0
	s_setprio 1
	v_mfma_f32_16x16x32_bf16 v[120:123], v[148:151], v[164:167], 0
	v_mfma_f32_16x16x32_bf16 v[116:119], v[156:159], v[164:167], 0
	v_mfma_f32_16x16x32_bf16 v[104:107], v[148:151], v[172:175], 0
	v_mfma_f32_16x16x32_bf16 v[100:103], v[156:159], v[172:175], 0
	v_mfma_f32_16x16x32_bf16 v[88:91], v[148:151], v[180:183], 0
	v_mfma_f32_16x16x32_bf16 v[84:87], v[156:159], v[180:183], 0
	v_mfma_f32_16x16x32_bf16 v[72:75], v[148:151], v[188:191], 0
	v_mfma_f32_16x16x32_bf16 v[68:71], v[156:159], v[188:191], 0
	v_mfma_f32_16x16x32_bf16 v[120:123], v[152:155], v[168:171], v[120:123]
	v_mfma_f32_16x16x32_bf16 v[116:119], v[160:163], v[168:171], v[116:119]
	v_mfma_f32_16x16x32_bf16 v[104:107], v[152:155], v[176:179], v[104:107]
	v_mfma_f32_16x16x32_bf16 v[100:103], v[160:163], v[176:179], v[100:103]
	v_mfma_f32_16x16x32_bf16 v[88:91], v[152:155], v[184:187], v[88:91]
	v_mfma_f32_16x16x32_bf16 v[84:87], v[160:163], v[184:187], v[84:87]
	v_mfma_f32_16x16x32_bf16 v[72:75], v[152:155], v[192:195], v[72:75]
	v_mfma_f32_16x16x32_bf16 v[68:71], v[160:163], v[192:195], v[68:71]
	s_setprio 0
	s_barrier
	s_add_i32 s12, s14, s82
	v_lshl_add_u64 v[196:197], s[38:39], 0, v[2:3]
	s_mov_b32 m0, s12
	ds_read_b128 v[164:167], v243 offset:16384
	ds_read_b128 v[168:171], v243 offset:17408
	ds_read_b128 v[172:175], v243 offset:18432
	ds_read_b128 v[176:179], v243 offset:19456
	ds_read_b128 v[180:183], v243 offset:20480
	ds_read_b128 v[184:187], v243 offset:21504
	ds_read_b128 v[188:191], v243 offset:22528
	ds_read_b128 v[192:195], v243 offset:23552
	global_load_lds_dwordx4 v[196:197], off
	s_add_i32 m0, s12, 0x2000
	s_add_u32 s12, s38, 0x80000
	v_lshl_add_u64 v[198:199], s[38:39], 0, v[218:219]
	s_addc_u32 s13, s39, 0
	s_add_i32 s14, s15, s82
	global_load_lds_dwordx4 v[198:199], off
	v_lshl_add_u64 v[200:201], s[12:13], 0, v[2:3]
	s_mov_b32 m0, s14
	v_lshl_add_u64 v[202:203], s[62:63], 0, v[216:217]
	global_load_lds_dwordx4 v[200:201], off
	v_lshl_add_u64 v[200:201], s[12:13], 0, v[218:219]
	s_add_i32 m0, s14, 0x2000
	s_nop 0
	global_load_lds_dwordx4 v[200:201], off
	v_lshl_add_u64 v[200:201], s[62:63], 0, v[0:1]
	s_mov_b32 m0, s21
	s_nop 0
	global_load_lds_dwordx4 v[200:201], off
	s_mov_b32 m0, s83
	s_nop 0
	global_load_lds_dwordx4 v[202:203], off
	s_waitcnt vmcnt(8)
	s_waitcnt lgkmcnt(0)
	s_barrier
	s_setprio 1
	v_mfma_f32_16x16x32_bf16 v[64:67], v[124:127], v[164:167], 0
	v_mfma_f32_16x16x32_bf16 v[60:63], v[136:139], v[164:167], 0
	v_mfma_f32_16x16x32_bf16 v[48:51], v[124:127], v[172:175], 0
	v_mfma_f32_16x16x32_bf16 v[44:47], v[136:139], v[172:175], 0
	v_mfma_f32_16x16x32_bf16 v[32:35], v[124:127], v[180:183], 0
	v_mfma_f32_16x16x32_bf16 v[28:31], v[136:139], v[180:183], 0
	v_mfma_f32_16x16x32_bf16 v[16:19], v[124:127], v[188:191], 0
	v_mfma_f32_16x16x32_bf16 v[12:15], v[136:139], v[188:191], 0
	v_mfma_f32_16x16x32_bf16 v[64:67], v[128:131], v[168:171], v[64:67]
	v_mfma_f32_16x16x32_bf16 v[60:63], v[144:147], v[168:171], v[60:63]
	v_mfma_f32_16x16x32_bf16 v[48:51], v[128:131], v[176:179], v[48:51]
	v_mfma_f32_16x16x32_bf16 v[44:47], v[144:147], v[176:179], v[44:47]
	v_mfma_f32_16x16x32_bf16 v[32:35], v[128:131], v[184:187], v[32:35]
	v_mfma_f32_16x16x32_bf16 v[28:31], v[144:147], v[184:187], v[28:31]
	v_mfma_f32_16x16x32_bf16 v[16:19], v[128:131], v[192:195], v[16:19]
	v_mfma_f32_16x16x32_bf16 v[12:15], v[144:147], v[192:195], v[12:15]
	s_setprio 0
	s_setprio 1
	v_mfma_f32_16x16x32_bf16 v[56:59], v[148:151], v[164:167], 0
	v_mfma_f32_16x16x32_bf16 v[52:55], v[156:159], v[164:167], 0
	v_mfma_f32_16x16x32_bf16 v[40:43], v[148:151], v[172:175], 0
	v_mfma_f32_16x16x32_bf16 v[36:39], v[156:159], v[172:175], 0
	v_mfma_f32_16x16x32_bf16 v[24:27], v[148:151], v[180:183], 0
	v_mfma_f32_16x16x32_bf16 v[20:23], v[156:159], v[180:183], 0
	v_mfma_f32_16x16x32_bf16 v[8:11], v[148:151], v[188:191], 0
	v_mfma_f32_16x16x32_bf16 v[4:7], v[156:159], v[188:191], 0
	v_mfma_f32_16x16x32_bf16 v[56:59], v[152:155], v[168:171], v[56:59]
	v_mfma_f32_16x16x32_bf16 v[52:55], v[160:163], v[168:171], v[52:55]
	v_mfma_f32_16x16x32_bf16 v[40:43], v[152:155], v[176:179], v[40:43]
	v_mfma_f32_16x16x32_bf16 v[36:39], v[160:163], v[176:179], v[36:39]
	v_mfma_f32_16x16x32_bf16 v[24:27], v[152:155], v[184:187], v[24:27]
	v_mfma_f32_16x16x32_bf16 v[20:23], v[160:163], v[184:187], v[20:23]
	v_mfma_f32_16x16x32_bf16 v[8:11], v[152:155], v[192:195], v[8:11]
	v_mfma_f32_16x16x32_bf16 v[4:7], v[160:163], v[192:195], v[4:7]
	s_setprio 0
	s_barrier
	s_add_i32 s14, 0, 0x18000
	s_add_i32 s15, 0, 0x1c000
	v_add_u32_e32 v144, s14, v230
	v_add_u32_e32 v160, s15, v230
	ds_read_b128 v[124:127], v144
	ds_read_b128 v[128:131], v144 offset:1024
	ds_read_b128 v[136:139], v144 offset:2048
	ds_read_b128 v[144:147], v144 offset:3072
	ds_read_b128 v[148:151], v160
	ds_read_b128 v[152:155], v160 offset:1024
	ds_read_b128 v[156:159], v160 offset:2048
	ds_read_b128 v[160:163], v160 offset:3072
	s_add_u32 s12, s62, 0x80000
	s_addc_u32 s13, s63, 0
	s_mov_b32 m0, s84
	v_lshl_add_u64 v[204:205], s[12:13], 0, v[0:1]
	ds_read_b128 v[164:167], v243 offset:32768
	ds_read_b128 v[168:171], v243 offset:33792
	ds_read_b128 v[172:175], v243 offset:34816
	ds_read_b128 v[176:179], v243 offset:35840
	ds_read_b128 v[180:183], v243 offset:36864
	ds_read_b128 v[184:187], v243 offset:37888
	ds_read_b128 v[188:191], v243 offset:38912
	ds_read_b128 v[192:195], v243 offset:39936
	global_load_lds_dwordx4 v[204:205], off
	v_lshl_add_u64 v[204:205], s[12:13], 0, v[216:217]
	s_mov_b32 m0, s85
	s_nop 0
	global_load_lds_dwordx4 v[204:205], off
	s_waitcnt vmcnt(8)
	s_waitcnt lgkmcnt(0)
	s_barrier
	s_setprio 1
	v_mfma_f32_16x16x32_bf16 v[140:143], v[124:127], v[164:167], v[140:143]
	v_mfma_f32_16x16x32_bf16 v[132:135], v[136:139], v[164:167], v[132:135]
	v_mfma_f32_16x16x32_bf16 v[112:115], v[124:127], v[172:175], v[112:115]
	v_mfma_f32_16x16x32_bf16 v[108:111], v[136:139], v[172:175], v[108:111]
	v_mfma_f32_16x16x32_bf16 v[96:99], v[124:127], v[180:183], v[96:99]
	v_mfma_f32_16x16x32_bf16 v[92:95], v[136:139], v[180:183], v[92:95]
	v_mfma_f32_16x16x32_bf16 v[80:83], v[124:127], v[188:191], v[80:83]
	v_mfma_f32_16x16x32_bf16 v[76:79], v[136:139], v[188:191], v[76:79]
	v_mfma_f32_16x16x32_bf16 v[140:143], v[128:131], v[168:171], v[140:143]
	v_mfma_f32_16x16x32_bf16 v[132:135], v[144:147], v[168:171], v[132:135]
	v_mfma_f32_16x16x32_bf16 v[112:115], v[128:131], v[176:179], v[112:115]
	v_mfma_f32_16x16x32_bf16 v[108:111], v[144:147], v[176:179], v[108:111]
	v_mfma_f32_16x16x32_bf16 v[96:99], v[128:131], v[184:187], v[96:99]
	v_mfma_f32_16x16x32_bf16 v[92:95], v[144:147], v[184:187], v[92:95]
	v_mfma_f32_16x16x32_bf16 v[80:83], v[128:131], v[192:195], v[80:83]
	v_mfma_f32_16x16x32_bf16 v[76:79], v[144:147], v[192:195], v[76:79]
	s_setprio 0
	s_setprio 1
	v_mfma_f32_16x16x32_bf16 v[120:123], v[148:151], v[164:167], v[120:123]
	v_mfma_f32_16x16x32_bf16 v[116:119], v[156:159], v[164:167], v[116:119]
	v_mfma_f32_16x16x32_bf16 v[104:107], v[148:151], v[172:175], v[104:107]
	v_mfma_f32_16x16x32_bf16 v[100:103], v[156:159], v[172:175], v[100:103]
	v_mfma_f32_16x16x32_bf16 v[88:91], v[148:151], v[180:183], v[88:91]
	v_mfma_f32_16x16x32_bf16 v[84:87], v[156:159], v[180:183], v[84:87]
	v_mfma_f32_16x16x32_bf16 v[72:75], v[148:151], v[188:191], v[72:75]
	v_mfma_f32_16x16x32_bf16 v[68:71], v[156:159], v[188:191], v[68:71]
	v_mfma_f32_16x16x32_bf16 v[120:123], v[152:155], v[168:171], v[120:123]
	v_mfma_f32_16x16x32_bf16 v[116:119], v[160:163], v[168:171], v[116:119]
	v_mfma_f32_16x16x32_bf16 v[104:107], v[152:155], v[176:179], v[104:107]
	v_mfma_f32_16x16x32_bf16 v[100:103], v[160:163], v[176:179], v[100:103]
	v_mfma_f32_16x16x32_bf16 v[88:91], v[152:155], v[184:187], v[88:91]
	v_mfma_f32_16x16x32_bf16 v[84:87], v[160:163], v[184:187], v[84:87]
	v_mfma_f32_16x16x32_bf16 v[72:75], v[152:155], v[192:195], v[72:75]
	v_mfma_f32_16x16x32_bf16 v[68:71], v[160:163], v[192:195], v[68:71]
	s_setprio 0
	s_barrier
	s_add_i32 s12, s14, s82
	v_lshl_add_u64 v[196:197], v[196:197], 0, s[68:69]
	s_mov_b32 m0, s12
	ds_read_b128 v[164:167], v243 offset:49152
	ds_read_b128 v[168:171], v243 offset:50176
	ds_read_b128 v[172:175], v243 offset:51200
	ds_read_b128 v[176:179], v243 offset:52224
	ds_read_b128 v[180:183], v243 offset:53248
	ds_read_b128 v[184:187], v243 offset:54272
	ds_read_b128 v[188:191], v243 offset:55296
	ds_read_b128 v[192:195], v243 offset:56320
	global_load_lds_dwordx4 v[196:197], off
	s_add_i32 m0, s12, 0x2000
	s_add_u32 s12, s38, 0x80080
	v_lshl_add_u64 v[196:197], v[198:199], 0, s[68:69]
	s_addc_u32 s13, s39, 0
	s_add_i32 s14, s15, s82
	global_load_lds_dwordx4 v[196:197], off
	v_lshl_add_u64 v[196:197], s[12:13], 0, v[2:3]
	s_mov_b32 m0, s14
	s_nop 0
	global_load_lds_dwordx4 v[196:197], off
	v_lshl_add_u64 v[196:197], s[12:13], 0, v[218:219]
	s_add_i32 m0, s14, 0x2000
	s_nop 0
	global_load_lds_dwordx4 v[196:197], off
	v_lshl_add_u64 v[196:197], v[200:201], 0, s[68:69]
	s_mov_b32 m0, s89
	s_nop 0
	global_load_lds_dwordx4 v[196:197], off
	v_lshl_add_u64 v[196:197], v[202:203], 0, s[68:69]
	s_mov_b32 m0, s90
	s_nop 0
	global_load_lds_dwordx4 v[196:197], off
	s_waitcnt vmcnt(8)
	s_waitcnt lgkmcnt(0)
	s_barrier
	s_setprio 1
	v_mfma_f32_16x16x32_bf16 v[64:67], v[124:127], v[164:167], v[64:67]
	v_mfma_f32_16x16x32_bf16 v[60:63], v[136:139], v[164:167], v[60:63]
	v_mfma_f32_16x16x32_bf16 v[48:51], v[124:127], v[172:175], v[48:51]
	v_mfma_f32_16x16x32_bf16 v[44:47], v[136:139], v[172:175], v[44:47]
	v_mfma_f32_16x16x32_bf16 v[32:35], v[124:127], v[180:183], v[32:35]
	v_mfma_f32_16x16x32_bf16 v[28:31], v[136:139], v[180:183], v[28:31]
	v_mfma_f32_16x16x32_bf16 v[16:19], v[124:127], v[188:191], v[16:19]
	v_mfma_f32_16x16x32_bf16 v[12:15], v[136:139], v[188:191], v[12:15]
	v_mfma_f32_16x16x32_bf16 v[64:67], v[128:131], v[168:171], v[64:67]
	v_mfma_f32_16x16x32_bf16 v[60:63], v[144:147], v[168:171], v[60:63]
	v_mfma_f32_16x16x32_bf16 v[48:51], v[128:131], v[176:179], v[48:51]
	v_mfma_f32_16x16x32_bf16 v[44:47], v[144:147], v[176:179], v[44:47]
	v_mfma_f32_16x16x32_bf16 v[32:35], v[128:131], v[184:187], v[32:35]
	v_mfma_f32_16x16x32_bf16 v[28:31], v[144:147], v[184:187], v[28:31]
	v_mfma_f32_16x16x32_bf16 v[16:19], v[128:131], v[192:195], v[16:19]
	v_mfma_f32_16x16x32_bf16 v[12:15], v[144:147], v[192:195], v[12:15]
	s_setprio 0
	s_setprio 1
	v_mfma_f32_16x16x32_bf16 v[56:59], v[148:151], v[164:167], v[56:59]
	v_mfma_f32_16x16x32_bf16 v[52:55], v[156:159], v[164:167], v[52:55]
	v_mfma_f32_16x16x32_bf16 v[40:43], v[148:151], v[172:175], v[40:43]
	v_mfma_f32_16x16x32_bf16 v[36:39], v[156:159], v[172:175], v[36:39]
	v_mfma_f32_16x16x32_bf16 v[24:27], v[148:151], v[180:183], v[24:27]
	v_mfma_f32_16x16x32_bf16 v[20:23], v[156:159], v[180:183], v[20:23]
	v_mfma_f32_16x16x32_bf16 v[8:11], v[148:151], v[188:191], v[8:11]
	v_mfma_f32_16x16x32_bf16 v[4:7], v[156:159], v[188:191], v[4:7]
	v_mfma_f32_16x16x32_bf16 v[56:59], v[152:155], v[168:171], v[56:59]
	v_mfma_f32_16x16x32_bf16 v[52:55], v[160:163], v[168:171], v[52:55]
	v_mfma_f32_16x16x32_bf16 v[40:43], v[152:155], v[176:179], v[40:43]
	v_mfma_f32_16x16x32_bf16 v[36:39], v[160:163], v[176:179], v[36:39]
	v_mfma_f32_16x16x32_bf16 v[24:27], v[152:155], v[184:187], v[24:27]
	v_mfma_f32_16x16x32_bf16 v[20:23], v[160:163], v[184:187], v[20:23]
	v_mfma_f32_16x16x32_bf16 v[8:11], v[152:155], v[192:195], v[8:11]
	v_mfma_f32_16x16x32_bf16 v[4:7], v[160:163], v[192:195], v[4:7]
	s_setprio 0
	s_barrier
	s_add_i32 s11, s11, 2
	s_add_u32 s9, s9, 0x100
	s_addc_u32 s10, s10, 0
	s_add_u32 s36, s36, 0x100
	s_addc_u32 s37, s37, 0
	s_cmp_gt_u32 s11, 29
.LBB0_741:
	s_add_u32 s12, s36, 0xfff80080
	s_addc_u32 s13, s37, -1
	s_add_i32 s14, 0, 0x10000
	s_cmp_eq_u32 s11, 28
	s_cselect_b32 s63, s5, s13
	s_cselect_b32 s62, s6, s12
	s_cselect_b32 s39, s7, s10
	s_cselect_b32 s38, s8, s9
	s_add_i32 s15, 0, 0x14000
	v_add_u32_e32 v144, s14, v230
	v_add_u32_e32 v160, s15, v230
	ds_read_b128 v[124:127], v144
	ds_read_b128 v[128:131], v144 offset:1024
	ds_read_b128 v[136:139], v144 offset:2048
	ds_read_b128 v[144:147], v144 offset:3072
	ds_read_b128 v[148:151], v160
	ds_read_b128 v[152:155], v160 offset:1024
	ds_read_b128 v[156:159], v160 offset:2048
	ds_read_b128 v[160:163], v160 offset:3072
	v_lshl_add_u64 v[196:197], s[36:37], 0, v[222:223]
	s_add_i32 m0, s21, 0xc000
	ds_read_b128 v[164:167], v243
	ds_read_b128 v[168:171], v243 offset:1024
	ds_read_b128 v[172:175], v243 offset:2048
	ds_read_b128 v[176:179], v243 offset:3072
	ds_read_b128 v[180:183], v243 offset:4096
	ds_read_b128 v[184:187], v243 offset:5120
	ds_read_b128 v[188:191], v243 offset:6144
	ds_read_b128 v[192:195], v243 offset:7168
	global_load_lds_dwordx4 v[196:197], off
	v_lshl_add_u64 v[196:197], s[36:37], 0, v[220:221]
	s_add_i32 m0, s21, 0xe000
	s_nop 0
	global_load_lds_dwordx4 v[196:197], off
	s_waitcnt vmcnt(8)
	s_waitcnt lgkmcnt(0)
	s_barrier
	s_setprio 1
	v_mfma_f32_16x16x32_bf16 v[140:143], v[124:127], v[164:167], v[140:143]
	v_mfma_f32_16x16x32_bf16 v[132:135], v[136:139], v[164:167], v[132:135]
	v_mfma_f32_16x16x32_bf16 v[112:115], v[124:127], v[172:175], v[112:115]
	v_mfma_f32_16x16x32_bf16 v[108:111], v[136:139], v[172:175], v[108:111]
	v_mfma_f32_16x16x32_bf16 v[96:99], v[124:127], v[180:183], v[96:99]
	v_mfma_f32_16x16x32_bf16 v[92:95], v[136:139], v[180:183], v[92:95]
	v_mfma_f32_16x16x32_bf16 v[80:83], v[124:127], v[188:191], v[80:83]
	v_mfma_f32_16x16x32_bf16 v[76:79], v[136:139], v[188:191], v[76:79]
	v_mfma_f32_16x16x32_bf16 v[140:143], v[128:131], v[168:171], v[140:143]
	v_mfma_f32_16x16x32_bf16 v[132:135], v[144:147], v[168:171], v[132:135]
	v_mfma_f32_16x16x32_bf16 v[112:115], v[128:131], v[176:179], v[112:115]
	v_mfma_f32_16x16x32_bf16 v[108:111], v[144:147], v[176:179], v[108:111]
	v_mfma_f32_16x16x32_bf16 v[96:99], v[128:131], v[184:187], v[96:99]
	v_mfma_f32_16x16x32_bf16 v[92:95], v[144:147], v[184:187], v[92:95]
	v_mfma_f32_16x16x32_bf16 v[80:83], v[128:131], v[192:195], v[80:83]
	v_mfma_f32_16x16x32_bf16 v[76:79], v[144:147], v[192:195], v[76:79]
	s_setprio 0
	s_setprio 1
	v_mfma_f32_16x16x32_bf16 v[120:123], v[148:151], v[164:167], v[120:123]
	v_mfma_f32_16x16x32_bf16 v[116:119], v[156:159], v[164:167], v[116:119]
	v_mfma_f32_16x16x32_bf16 v[104:107], v[148:151], v[172:175], v[104:107]
	v_mfma_f32_16x16x32_bf16 v[100:103], v[156:159], v[172:175], v[100:103]
	v_mfma_f32_16x16x32_bf16 v[88:91], v[148:151], v[180:183], v[88:91]
	v_mfma_f32_16x16x32_bf16 v[84:87], v[156:159], v[180:183], v[84:87]
	v_mfma_f32_16x16x32_bf16 v[72:75], v[148:151], v[188:191], v[72:75]
	v_mfma_f32_16x16x32_bf16 v[68:71], v[156:159], v[188:191], v[68:71]
	v_mfma_f32_16x16x32_bf16 v[120:123], v[152:155], v[168:171], v[120:123]
	v_mfma_f32_16x16x32_bf16 v[116:119], v[160:163], v[168:171], v[116:119]
	v_mfma_f32_16x16x32_bf16 v[104:107], v[152:155], v[176:179], v[104:107]
	v_mfma_f32_16x16x32_bf16 v[100:103], v[160:163], v[176:179], v[100:103]
	v_mfma_f32_16x16x32_bf16 v[88:91], v[152:155], v[184:187], v[88:91]
	v_mfma_f32_16x16x32_bf16 v[84:87], v[160:163], v[184:187], v[84:87]
	v_mfma_f32_16x16x32_bf16 v[72:75], v[152:155], v[192:195], v[72:75]
	v_mfma_f32_16x16x32_bf16 v[68:71], v[160:163], v[192:195], v[68:71]
	s_setprio 0
	s_barrier
	s_add_i32 s12, s14, s82
	v_lshl_add_u64 v[196:197], s[38:39], 0, v[2:3]
	s_mov_b32 m0, s12
	ds_read_b128 v[164:167], v243 offset:16384
	ds_read_b128 v[168:171], v243 offset:17408
	ds_read_b128 v[172:175], v243 offset:18432
	ds_read_b128 v[176:179], v243 offset:19456
	ds_read_b128 v[180:183], v243 offset:20480
	ds_read_b128 v[184:187], v243 offset:21504
	ds_read_b128 v[188:191], v243 offset:22528
	ds_read_b128 v[192:195], v243 offset:23552
	global_load_lds_dwordx4 v[196:197], off
	s_add_i32 m0, s12, 0x2000
	s_add_u32 s12, s38, 0x80000
	v_lshl_add_u64 v[198:199], s[38:39], 0, v[218:219]
	s_addc_u32 s13, s39, 0
	s_add_i32 s14, s15, s82
	global_load_lds_dwordx4 v[198:199], off
	v_lshl_add_u64 v[200:201], s[12:13], 0, v[2:3]
	s_mov_b32 m0, s14
	v_lshl_add_u64 v[202:203], s[62:63], 0, v[216:217]
	global_load_lds_dwordx4 v[200:201], off
	v_lshl_add_u64 v[200:201], s[12:13], 0, v[218:219]
	s_add_i32 m0, s14, 0x2000
	s_nop 0
	global_load_lds_dwordx4 v[200:201], off
	v_lshl_add_u64 v[200:201], s[62:63], 0, v[0:1]
	s_mov_b32 m0, s21
	s_nop 0
	global_load_lds_dwordx4 v[200:201], off
	s_mov_b32 m0, s83
	s_nop 0
	global_load_lds_dwordx4 v[202:203], off
	s_waitcnt vmcnt(8)
	s_waitcnt lgkmcnt(0)
	s_barrier
	s_setprio 1
	v_mfma_f32_16x16x32_bf16 v[64:67], v[124:127], v[164:167], v[64:67]
	v_mfma_f32_16x16x32_bf16 v[60:63], v[136:139], v[164:167], v[60:63]
	v_mfma_f32_16x16x32_bf16 v[48:51], v[124:127], v[172:175], v[48:51]
	v_mfma_f32_16x16x32_bf16 v[44:47], v[136:139], v[172:175], v[44:47]
	v_mfma_f32_16x16x32_bf16 v[32:35], v[124:127], v[180:183], v[32:35]
	v_mfma_f32_16x16x32_bf16 v[28:31], v[136:139], v[180:183], v[28:31]
	v_mfma_f32_16x16x32_bf16 v[16:19], v[124:127], v[188:191], v[16:19]
	v_mfma_f32_16x16x32_bf16 v[12:15], v[136:139], v[188:191], v[12:15]
	v_mfma_f32_16x16x32_bf16 v[64:67], v[128:131], v[168:171], v[64:67]
	v_mfma_f32_16x16x32_bf16 v[60:63], v[144:147], v[168:171], v[60:63]
	v_mfma_f32_16x16x32_bf16 v[48:51], v[128:131], v[176:179], v[48:51]
	v_mfma_f32_16x16x32_bf16 v[44:47], v[144:147], v[176:179], v[44:47]
	v_mfma_f32_16x16x32_bf16 v[32:35], v[128:131], v[184:187], v[32:35]
	v_mfma_f32_16x16x32_bf16 v[28:31], v[144:147], v[184:187], v[28:31]
	v_mfma_f32_16x16x32_bf16 v[16:19], v[128:131], v[192:195], v[16:19]
	v_mfma_f32_16x16x32_bf16 v[12:15], v[144:147], v[192:195], v[12:15]
	s_setprio 0
	s_setprio 1
	v_mfma_f32_16x16x32_bf16 v[56:59], v[148:151], v[164:167], v[56:59]
	v_mfma_f32_16x16x32_bf16 v[52:55], v[156:159], v[164:167], v[52:55]
	v_mfma_f32_16x16x32_bf16 v[40:43], v[148:151], v[172:175], v[40:43]
	v_mfma_f32_16x16x32_bf16 v[36:39], v[156:159], v[172:175], v[36:39]
	v_mfma_f32_16x16x32_bf16 v[24:27], v[148:151], v[180:183], v[24:27]
	v_mfma_f32_16x16x32_bf16 v[20:23], v[156:159], v[180:183], v[20:23]
	v_mfma_f32_16x16x32_bf16 v[8:11], v[148:151], v[188:191], v[8:11]
	v_mfma_f32_16x16x32_bf16 v[4:7], v[156:159], v[188:191], v[4:7]
	v_mfma_f32_16x16x32_bf16 v[56:59], v[152:155], v[168:171], v[56:59]
	v_mfma_f32_16x16x32_bf16 v[52:55], v[160:163], v[168:171], v[52:55]
	v_mfma_f32_16x16x32_bf16 v[40:43], v[152:155], v[176:179], v[40:43]
	v_mfma_f32_16x16x32_bf16 v[36:39], v[160:163], v[176:179], v[36:39]
	v_mfma_f32_16x16x32_bf16 v[24:27], v[152:155], v[184:187], v[24:27]
	v_mfma_f32_16x16x32_bf16 v[20:23], v[160:163], v[184:187], v[20:23]
	v_mfma_f32_16x16x32_bf16 v[8:11], v[152:155], v[192:195], v[8:11]
	v_mfma_f32_16x16x32_bf16 v[4:7], v[160:163], v[192:195], v[4:7]
	s_setprio 0
	s_barrier
	s_add_i32 s14, 0, 0x18000
	s_add_i32 s15, 0, 0x1c000
	v_add_u32_e32 v144, s14, v230
	v_add_u32_e32 v160, s15, v230
	ds_read_b128 v[124:127], v144
	ds_read_b128 v[128:131], v144 offset:1024
	ds_read_b128 v[136:139], v144 offset:2048
	ds_read_b128 v[144:147], v144 offset:3072
	ds_read_b128 v[148:151], v160
	ds_read_b128 v[152:155], v160 offset:1024
	ds_read_b128 v[156:159], v160 offset:2048
	ds_read_b128 v[160:163], v160 offset:3072
	s_add_u32 s12, s62, 0x80000
	s_addc_u32 s13, s63, 0
	s_mov_b32 m0, s84
	v_lshl_add_u64 v[204:205], s[12:13], 0, v[0:1]
	ds_read_b128 v[164:167], v243 offset:32768
	ds_read_b128 v[168:171], v243 offset:33792
	ds_read_b128 v[172:175], v243 offset:34816
	ds_read_b128 v[176:179], v243 offset:35840
	ds_read_b128 v[180:183], v243 offset:36864
	ds_read_b128 v[184:187], v243 offset:37888
	ds_read_b128 v[188:191], v243 offset:38912
	ds_read_b128 v[192:195], v243 offset:39936
	global_load_lds_dwordx4 v[204:205], off
	v_lshl_add_u64 v[204:205], s[12:13], 0, v[216:217]
	s_mov_b32 m0, s85
	s_nop 0
	global_load_lds_dwordx4 v[204:205], off
	s_waitcnt vmcnt(8)
	s_waitcnt lgkmcnt(0)
	s_barrier
	s_setprio 1
	v_mfma_f32_16x16x32_bf16 v[140:143], v[124:127], v[164:167], v[140:143]
	v_mfma_f32_16x16x32_bf16 v[132:135], v[136:139], v[164:167], v[132:135]
	v_mfma_f32_16x16x32_bf16 v[112:115], v[124:127], v[172:175], v[112:115]
	v_mfma_f32_16x16x32_bf16 v[108:111], v[136:139], v[172:175], v[108:111]
	v_mfma_f32_16x16x32_bf16 v[96:99], v[124:127], v[180:183], v[96:99]
	v_mfma_f32_16x16x32_bf16 v[92:95], v[136:139], v[180:183], v[92:95]
	v_mfma_f32_16x16x32_bf16 v[80:83], v[124:127], v[188:191], v[80:83]
	v_mfma_f32_16x16x32_bf16 v[76:79], v[136:139], v[188:191], v[76:79]
	v_mfma_f32_16x16x32_bf16 v[140:143], v[128:131], v[168:171], v[140:143]
	v_mfma_f32_16x16x32_bf16 v[132:135], v[144:147], v[168:171], v[132:135]
	v_mfma_f32_16x16x32_bf16 v[112:115], v[128:131], v[176:179], v[112:115]
	v_mfma_f32_16x16x32_bf16 v[108:111], v[144:147], v[176:179], v[108:111]
	v_mfma_f32_16x16x32_bf16 v[96:99], v[128:131], v[184:187], v[96:99]
	v_mfma_f32_16x16x32_bf16 v[92:95], v[144:147], v[184:187], v[92:95]
	v_mfma_f32_16x16x32_bf16 v[80:83], v[128:131], v[192:195], v[80:83]
	v_mfma_f32_16x16x32_bf16 v[76:79], v[144:147], v[192:195], v[76:79]
	s_setprio 0
	s_setprio 1
	v_mfma_f32_16x16x32_bf16 v[120:123], v[148:151], v[164:167], v[120:123]
	v_mfma_f32_16x16x32_bf16 v[116:119], v[156:159], v[164:167], v[116:119]
	v_mfma_f32_16x16x32_bf16 v[104:107], v[148:151], v[172:175], v[104:107]
	v_mfma_f32_16x16x32_bf16 v[100:103], v[156:159], v[172:175], v[100:103]
	v_mfma_f32_16x16x32_bf16 v[88:91], v[148:151], v[180:183], v[88:91]
	v_mfma_f32_16x16x32_bf16 v[84:87], v[156:159], v[180:183], v[84:87]
	v_mfma_f32_16x16x32_bf16 v[72:75], v[148:151], v[188:191], v[72:75]
	v_mfma_f32_16x16x32_bf16 v[68:71], v[156:159], v[188:191], v[68:71]
	v_mfma_f32_16x16x32_bf16 v[120:123], v[152:155], v[168:171], v[120:123]
	v_mfma_f32_16x16x32_bf16 v[116:119], v[160:163], v[168:171], v[116:119]
	v_mfma_f32_16x16x32_bf16 v[104:107], v[152:155], v[176:179], v[104:107]
	v_mfma_f32_16x16x32_bf16 v[100:103], v[160:163], v[176:179], v[100:103]
	v_mfma_f32_16x16x32_bf16 v[88:91], v[152:155], v[184:187], v[88:91]
	v_mfma_f32_16x16x32_bf16 v[84:87], v[160:163], v[184:187], v[84:87]
	v_mfma_f32_16x16x32_bf16 v[72:75], v[152:155], v[192:195], v[72:75]
	v_mfma_f32_16x16x32_bf16 v[68:71], v[160:163], v[192:195], v[68:71]
	s_setprio 0
	s_barrier
	s_add_i32 s12, s14, s82
	v_lshl_add_u64 v[196:197], v[196:197], 0, s[68:69]
	s_mov_b32 m0, s12
	ds_read_b128 v[164:167], v243 offset:49152
	ds_read_b128 v[168:171], v243 offset:50176
	ds_read_b128 v[172:175], v243 offset:51200
	ds_read_b128 v[176:179], v243 offset:52224
	ds_read_b128 v[180:183], v243 offset:53248
	ds_read_b128 v[184:187], v243 offset:54272
	ds_read_b128 v[188:191], v243 offset:55296
	ds_read_b128 v[192:195], v243 offset:56320
	global_load_lds_dwordx4 v[196:197], off
	s_add_i32 m0, s12, 0x2000
	s_add_u32 s12, s38, 0x80080
	v_lshl_add_u64 v[196:197], v[198:199], 0, s[68:69]
	s_addc_u32 s13, s39, 0
	s_add_i32 s14, s15, s82
	global_load_lds_dwordx4 v[196:197], off
	v_lshl_add_u64 v[196:197], s[12:13], 0, v[2:3]
	s_mov_b32 m0, s14
	s_nop 0
	global_load_lds_dwordx4 v[196:197], off
	v_lshl_add_u64 v[196:197], s[12:13], 0, v[218:219]
	s_add_i32 m0, s14, 0x2000
	s_nop 0
	global_load_lds_dwordx4 v[196:197], off
	v_lshl_add_u64 v[196:197], v[200:201], 0, s[68:69]
	s_mov_b32 m0, s89
	s_nop 0
	global_load_lds_dwordx4 v[196:197], off
	v_lshl_add_u64 v[196:197], v[202:203], 0, s[68:69]
	s_mov_b32 m0, s90
	s_nop 0
	global_load_lds_dwordx4 v[196:197], off
	s_waitcnt vmcnt(8)
	s_waitcnt lgkmcnt(0)
	s_barrier
	s_setprio 1
	v_mfma_f32_16x16x32_bf16 v[64:67], v[124:127], v[164:167], v[64:67]
	v_mfma_f32_16x16x32_bf16 v[60:63], v[136:139], v[164:167], v[60:63]
	v_mfma_f32_16x16x32_bf16 v[48:51], v[124:127], v[172:175], v[48:51]
	v_mfma_f32_16x16x32_bf16 v[44:47], v[136:139], v[172:175], v[44:47]
	v_mfma_f32_16x16x32_bf16 v[32:35], v[124:127], v[180:183], v[32:35]
	v_mfma_f32_16x16x32_bf16 v[28:31], v[136:139], v[180:183], v[28:31]
	v_mfma_f32_16x16x32_bf16 v[16:19], v[124:127], v[188:191], v[16:19]
	v_mfma_f32_16x16x32_bf16 v[12:15], v[136:139], v[188:191], v[12:15]
	v_mfma_f32_16x16x32_bf16 v[64:67], v[128:131], v[168:171], v[64:67]
	v_mfma_f32_16x16x32_bf16 v[60:63], v[144:147], v[168:171], v[60:63]
	v_mfma_f32_16x16x32_bf16 v[48:51], v[128:131], v[176:179], v[48:51]
	v_mfma_f32_16x16x32_bf16 v[44:47], v[144:147], v[176:179], v[44:47]
	v_mfma_f32_16x16x32_bf16 v[32:35], v[128:131], v[184:187], v[32:35]
	v_mfma_f32_16x16x32_bf16 v[28:31], v[144:147], v[184:187], v[28:31]
	v_mfma_f32_16x16x32_bf16 v[16:19], v[128:131], v[192:195], v[16:19]
	v_mfma_f32_16x16x32_bf16 v[12:15], v[144:147], v[192:195], v[12:15]
	s_setprio 0
	s_setprio 1
	v_mfma_f32_16x16x32_bf16 v[56:59], v[148:151], v[164:167], v[56:59]
	v_mfma_f32_16x16x32_bf16 v[52:55], v[156:159], v[164:167], v[52:55]
	v_mfma_f32_16x16x32_bf16 v[40:43], v[148:151], v[172:175], v[40:43]
	v_mfma_f32_16x16x32_bf16 v[36:39], v[156:159], v[172:175], v[36:39]
	v_mfma_f32_16x16x32_bf16 v[24:27], v[148:151], v[180:183], v[24:27]
	v_mfma_f32_16x16x32_bf16 v[20:23], v[156:159], v[180:183], v[20:23]
	v_mfma_f32_16x16x32_bf16 v[8:11], v[148:151], v[188:191], v[8:11]
	v_mfma_f32_16x16x32_bf16 v[4:7], v[156:159], v[188:191], v[4:7]
	v_mfma_f32_16x16x32_bf16 v[56:59], v[152:155], v[168:171], v[56:59]
	v_mfma_f32_16x16x32_bf16 v[52:55], v[160:163], v[168:171], v[52:55]
	v_mfma_f32_16x16x32_bf16 v[40:43], v[152:155], v[176:179], v[40:43]
	v_mfma_f32_16x16x32_bf16 v[36:39], v[160:163], v[176:179], v[36:39]
	v_mfma_f32_16x16x32_bf16 v[24:27], v[152:155], v[184:187], v[24:27]
	v_mfma_f32_16x16x32_bf16 v[20:23], v[160:163], v[184:187], v[20:23]
	v_mfma_f32_16x16x32_bf16 v[8:11], v[152:155], v[192:195], v[8:11]
	v_mfma_f32_16x16x32_bf16 v[4:7], v[160:163], v[192:195], v[4:7]
	s_setprio 0
	s_barrier
	s_add_i32 s11, s11, 2
	s_add_u32 s9, s9, 0x100
	s_addc_u32 s10, s10, 0
	s_add_u32 s36, s36, 0x100
	s_addc_u32 s37, s37, 0
	s_cmp_gt_u32 s11, 29
	s_cbranch_scc0 .LBB0_741
	s_and_b64 vcc, exec, s[46:47]
	s_cbranch_vccz .LBB0_744
	s_barrier

.LBB0_853:
	v_and_b32_e32 v203, 15, v16
	v_bfe_u32 v201, v16, 4, 2
	s_and_b32 s5, s5, 3
	v_lshlrev_b32_e32 v16, 4, v201
	v_lshlrev_b32_e32 v202, 2, v203
	v_lshl_or_b32 v16, v203, 6, v16
	v_and_b32_e32 v19, 32, v202
	s_lshl_b32 s14, s8, 13
	s_lshl_b32 s15, s5, 12
	s_add_i32 m0, s10, 0x18000
	v_lshl_add_u64 v[10:11], v[10:11], 0, s[68:69]
	v_bitop3_b32 v140, v16, s15, v19 bitop3:0xde
	v_bitop3_b32 v16, v16, s14, v19 bitop3:0xde
	s_nop 0
	global_load_lds_dwordx4 v[10:11], off
	v_lshl_add_u64 v[8:9], v[8:9], 0, s[68:69]
	s_add_i32 m0, s10, 0x1a000
	s_add_i32 s14, s10, 0x8000
	s_add_i32 s15, s10, 0xa000
	global_load_lds_dwordx4 v[8:9], off
	v_lshl_add_u64 v[6:7], v[6:7], 0, s[68:69]
	s_mov_b32 m0, s14
	s_add_u32 s16, s20, 0x80080
	global_load_lds_dwordx4 v[6:7], off
	v_lshl_add_u64 v[4:5], v[4:5], 0, s[68:69]
	s_mov_b32 m0, s15
	s_addc_u32 s17, s21, 0
	global_load_lds_dwordx4 v[4:5], off
	s_add_i32 m0, s10, 0x1c000
	v_lshl_add_u64 v[4:5], s[16:17], 0, v[2:3]
	global_load_lds_dwordx4 v[4:5], off
	v_lshl_add_u64 v[4:5], s[16:17], 0, v[134:135]
	s_add_i32 m0, s10, 0x1e000
	v_readlane_b32 s16, v254, 25
	global_load_lds_dwordx4 v[4:5], off
	v_readlane_b32 s17, v254, 26
	s_add_u32 s16, s16, s24
	s_addc_u32 s17, s17, s25
	s_add_u32 s16, s2, s16
	s_addc_u32 s17, s3, s17
	s_and_b32 s18, s18, 7
	s_lshl_b32 s18, s18, 23
	s_lshl_b32 s19, s19, 20
	v_lshlrev_b32_e32 v4, 15, v15
	s_or_b32 s18, s18, s19
	v_and_b32_e32 v4, 0xffff0000, v4
	s_add_u32 s18, s2, s18
	v_lshl_add_u32 v4, v17, 12, v4
	v_and_b32_e32 v5, 1, v15
	s_addc_u32 s19, s3, 0
	v_lshl_or_b32 v4, v5, 6, v4
	s_add_u32 s24, s18, 0x22180080
	v_lshl_add_u32 v4, v18, 1, v4
	v_mov_b32_e32 v5, v3
	s_addc_u32 s25, s19, 0
	v_lshl_add_u64 v[136:137], s[24:25], 0, v[4:5]
	v_lshlrev_b32_e32 v4, 15, v12
	v_and_b32_e32 v4, 0xffff0000, v4
	v_lshl_add_u32 v4, v13, 12, v4
	v_and_b32_e32 v5, 1, v12
	v_lshl_or_b32 v4, v5, 6, v4
	s_waitcnt vmcnt(8)
	s_barrier
	s_waitcnt vmcnt(6)
	v_lshl_add_u32 v4, v14, 1, v4
	v_mov_b32_e32 v5, v3
	v_lshl_add_u64 v[138:139], s[24:25], 0, v[4:5]
	v_lshl_or_b32 v200, s8, 6, v203
	s_mov_b32 s28, -2
	s_mov_b64 s[24:25], 0
	v_add_u32_e32 v141, 0, v16
	s_barrier
	s_add_u32 s26, s18, s24
	s_addc_u32 s27, s19, s25
	s_add_u32 s26, s26, 0x22100100
	s_addc_u32 s27, s27, 0
	s_add_u32 s29, s16, s24
	s_addc_u32 s30, s17, s25
	s_add_i32 s31, 0, 0x10000
	s_cmpk_eq_i32 s24, 0xf00
	s_cselect_b32 s37, s23, s27
	s_cselect_b32 s36, s22, s26
	s_cselect_b32 s27, s21, s30
	s_cselect_b32 s26, s20, s29
	s_add_i32 s29, 0, 0x14000
	v_add_u32_e32 v154, s31, v140
	v_add_u32_e32 v170, s29, v140
	ds_read_b128 v[142:145], v154
	ds_read_b128 v[146:149], v154 offset:1024
	ds_read_b128 v[150:153], v154 offset:2048
	ds_read_b128 v[154:157], v154 offset:3072
	ds_read_b128 v[158:161], v170
	ds_read_b128 v[162:165], v170 offset:1024
	ds_read_b128 v[166:169], v170 offset:2048
	ds_read_b128 v[170:173], v170 offset:3072
	v_lshl_add_u64 v[198:199], v[138:139], 0, s[24:25]
	s_add_i32 m0, s10, 0xc000
	ds_read_b128 v[174:177], v141
	ds_read_b128 v[178:181], v141 offset:1024
	ds_read_b128 v[182:185], v141 offset:2048
	ds_read_b128 v[186:189], v141 offset:3072
	ds_read_b128 v[190:193], v141 offset:4096
	ds_read_b128 v[194:197], v141 offset:5120
	ds_read_b128 v[204:207], v141 offset:6144
	ds_read_b128 v[208:211], v141 offset:7168
	global_load_lds_dwordx4 v[198:199], off
	v_lshl_add_u64 v[198:199], v[136:137], 0, s[24:25]
	s_add_i32 m0, s10, 0xe000
	s_nop 0
	global_load_lds_dwordx4 v[198:199], off
	s_waitcnt vmcnt(8)
	s_waitcnt lgkmcnt(0)
	s_barrier
	s_setprio 1
	v_mfma_f32_16x16x32_bf16 v[128:131], v[142:145], v[174:177], 0
	v_mfma_f32_16x16x32_bf16 v[124:127], v[150:153], v[174:177], 0
	v_mfma_f32_16x16x32_bf16 v[112:115], v[142:145], v[182:185], 0
	v_mfma_f32_16x16x32_bf16 v[108:111], v[150:153], v[182:185], 0
	v_mfma_f32_16x16x32_bf16 v[96:99], v[142:145], v[190:193], 0
	v_mfma_f32_16x16x32_bf16 v[92:95], v[150:153], v[190:193], 0
	v_mfma_f32_16x16x32_bf16 v[80:83], v[142:145], v[204:207], 0
	v_mfma_f32_16x16x32_bf16 v[76:79], v[150:153], v[204:207], 0
	v_mfma_f32_16x16x32_bf16 v[128:131], v[146:149], v[178:181], v[128:131]
	v_mfma_f32_16x16x32_bf16 v[124:127], v[154:157], v[178:181], v[124:127]
	v_mfma_f32_16x16x32_bf16 v[112:115], v[146:149], v[186:189], v[112:115]
	v_mfma_f32_16x16x32_bf16 v[108:111], v[154:157], v[186:189], v[108:111]
	v_mfma_f32_16x16x32_bf16 v[96:99], v[146:149], v[194:197], v[96:99]
	v_mfma_f32_16x16x32_bf16 v[92:95], v[154:157], v[194:197], v[92:95]
	v_mfma_f32_16x16x32_bf16 v[80:83], v[146:149], v[208:211], v[80:83]
	v_mfma_f32_16x16x32_bf16 v[76:79], v[154:157], v[208:211], v[76:79]
	s_setprio 0
	s_setprio 1
	v_mfma_f32_16x16x32_bf16 v[120:123], v[158:161], v[174:177], 0
	v_mfma_f32_16x16x32_bf16 v[116:119], v[166:169], v[174:177], 0
	v_mfma_f32_16x16x32_bf16 v[104:107], v[158:161], v[182:185], 0
	v_mfma_f32_16x16x32_bf16 v[100:103], v[166:169], v[182:185], 0
	v_mfma_f32_16x16x32_bf16 v[88:91], v[158:161], v[190:193], 0
	v_mfma_f32_16x16x32_bf16 v[84:87], v[166:169], v[190:193], 0
	v_mfma_f32_16x16x32_bf16 v[72:75], v[158:161], v[204:207], 0
	v_mfma_f32_16x16x32_bf16 v[68:71], v[166:169], v[204:207], 0
	v_mfma_f32_16x16x32_bf16 v[120:123], v[162:165], v[178:181], v[120:123]
	v_mfma_f32_16x16x32_bf16 v[116:119], v[170:173], v[178:181], v[116:119]
	v_mfma_f32_16x16x32_bf16 v[104:107], v[162:165], v[186:189], v[104:107]
	v_mfma_f32_16x16x32_bf16 v[100:103], v[170:173], v[186:189], v[100:103]
	v_mfma_f32_16x16x32_bf16 v[88:91], v[162:165], v[194:197], v[88:91]
	v_mfma_f32_16x16x32_bf16 v[84:87], v[170:173], v[194:197], v[84:87]
	v_mfma_f32_16x16x32_bf16 v[72:75], v[162:165], v[208:211], v[72:75]
	v_mfma_f32_16x16x32_bf16 v[68:71], v[170:173], v[208:211], v[68:71]
	s_setprio 0
	s_barrier
	s_add_i32 s30, s31, s9
	v_lshl_add_u64 v[198:199], s[26:27], 0, v[2:3]
	s_mov_b32 m0, s30
	ds_read_b128 v[174:177], v141 offset:16384
	ds_read_b128 v[178:181], v141 offset:17408
	ds_read_b128 v[182:185], v141 offset:18432
	ds_read_b128 v[186:189], v141 offset:19456
	ds_read_b128 v[190:193], v141 offset:20480
	ds_read_b128 v[194:197], v141 offset:21504
	ds_read_b128 v[204:207], v141 offset:22528
	ds_read_b128 v[208:211], v141 offset:23552
	global_load_lds_dwordx4 v[198:199], off
	s_add_i32 m0, s30, 0x2000
	s_add_u32 s30, s26, 0x80000
	v_lshl_add_u64 v[212:213], s[26:27], 0, v[134:135]
	s_addc_u32 s31, s27, 0
	s_add_i32 s29, s29, s9
	global_load_lds_dwordx4 v[212:213], off
	v_lshl_add_u64 v[214:215], s[30:31], 0, v[2:3]
	s_mov_b32 m0, s29
	v_lshl_add_u64 v[216:217], s[36:37], 0, v[132:133]
	global_load_lds_dwordx4 v[214:215], off
	v_lshl_add_u64 v[214:215], s[30:31], 0, v[134:135]
	s_add_i32 m0, s29, 0x2000
	s_nop 0
	global_load_lds_dwordx4 v[214:215], off
	v_lshl_add_u64 v[214:215], s[36:37], 0, v[0:1]
	s_mov_b32 m0, s10
	s_nop 0
	global_load_lds_dwordx4 v[214:215], off
	s_mov_b32 m0, s11
	s_nop 0
	global_load_lds_dwordx4 v[216:217], off
	s_waitcnt vmcnt(8)
	s_waitcnt lgkmcnt(0)
	s_barrier
	s_setprio 1
	v_mfma_f32_16x16x32_bf16 v[64:67], v[142:145], v[174:177], 0
	v_mfma_f32_16x16x32_bf16 v[60:63], v[150:153], v[174:177], 0
	v_mfma_f32_16x16x32_bf16 v[48:51], v[142:145], v[182:185], 0
	v_mfma_f32_16x16x32_bf16 v[44:47], v[150:153], v[182:185], 0
	v_mfma_f32_16x16x32_bf16 v[32:35], v[142:145], v[190:193], 0
	v_mfma_f32_16x16x32_bf16 v[28:31], v[150:153], v[190:193], 0
	v_mfma_f32_16x16x32_bf16 v[16:19], v[142:145], v[204:207], 0
	v_mfma_f32_16x16x32_bf16 v[12:15], v[150:153], v[204:207], 0
	v_mfma_f32_16x16x32_bf16 v[64:67], v[146:149], v[178:181], v[64:67]
	v_mfma_f32_16x16x32_bf16 v[60:63], v[154:157], v[178:181], v[60:63]
	v_mfma_f32_16x16x32_bf16 v[48:51], v[146:149], v[186:189], v[48:51]
	v_mfma_f32_16x16x32_bf16 v[44:47], v[154:157], v[186:189], v[44:47]
	v_mfma_f32_16x16x32_bf16 v[32:35], v[146:149], v[194:197], v[32:35]
	v_mfma_f32_16x16x32_bf16 v[28:31], v[154:157], v[194:197], v[28:31]
	v_mfma_f32_16x16x32_bf16 v[16:19], v[146:149], v[208:211], v[16:19]
	v_mfma_f32_16x16x32_bf16 v[12:15], v[154:157], v[208:211], v[12:15]
	s_setprio 0
	s_setprio 1
	v_mfma_f32_16x16x32_bf16 v[56:59], v[158:161], v[174:177], 0
	v_mfma_f32_16x16x32_bf16 v[52:55], v[166:169], v[174:177], 0
	v_mfma_f32_16x16x32_bf16 v[40:43], v[158:161], v[182:185], 0
	v_mfma_f32_16x16x32_bf16 v[36:39], v[166:169], v[182:185], 0
	v_mfma_f32_16x16x32_bf16 v[24:27], v[158:161], v[190:193], 0
	v_mfma_f32_16x16x32_bf16 v[20:23], v[166:169], v[190:193], 0
	v_mfma_f32_16x16x32_bf16 v[8:11], v[158:161], v[204:207], 0
	v_mfma_f32_16x16x32_bf16 v[4:7], v[166:169], v[204:207], 0
	v_mfma_f32_16x16x32_bf16 v[56:59], v[162:165], v[178:181], v[56:59]
	v_mfma_f32_16x16x32_bf16 v[52:55], v[170:173], v[178:181], v[52:55]
	v_mfma_f32_16x16x32_bf16 v[40:43], v[162:165], v[186:189], v[40:43]
	v_mfma_f32_16x16x32_bf16 v[36:39], v[170:173], v[186:189], v[36:39]
	v_mfma_f32_16x16x32_bf16 v[24:27], v[162:165], v[194:197], v[24:27]
	v_mfma_f32_16x16x32_bf16 v[20:23], v[170:173], v[194:197], v[20:23]
	v_mfma_f32_16x16x32_bf16 v[8:11], v[162:165], v[208:211], v[8:11]
	v_mfma_f32_16x16x32_bf16 v[4:7], v[170:173], v[208:211], v[4:7]
	s_setprio 0
	s_barrier
	s_add_i32 s29, 0, 0x18000
	s_add_i32 s33, 0, 0x1c000
	v_add_u32_e32 v154, s29, v140
	v_add_u32_e32 v170, s33, v140
	ds_read_b128 v[142:145], v154
	ds_read_b128 v[146:149], v154 offset:1024
	ds_read_b128 v[150:153], v154 offset:2048
	ds_read_b128 v[154:157], v154 offset:3072
	ds_read_b128 v[158:161], v170
	ds_read_b128 v[162:165], v170 offset:1024
	ds_read_b128 v[166:169], v170 offset:2048
	ds_read_b128 v[170:173], v170 offset:3072
	s_add_u32 s30, s36, 0x80000
	s_addc_u32 s31, s37, 0
	s_mov_b32 m0, s12
	v_lshl_add_u64 v[218:219], s[30:31], 0, v[0:1]
	ds_read_b128 v[174:177], v141 offset:32768
	ds_read_b128 v[178:181], v141 offset:33792
	ds_read_b128 v[182:185], v141 offset:34816
	ds_read_b128 v[186:189], v141 offset:35840
	ds_read_b128 v[190:193], v141 offset:36864
	ds_read_b128 v[194:197], v141 offset:37888
	ds_read_b128 v[204:207], v141 offset:38912
	ds_read_b128 v[208:211], v141 offset:39936
	global_load_lds_dwordx4 v[218:219], off
	v_lshl_add_u64 v[218:219], s[30:31], 0, v[132:133]
	s_mov_b32 m0, s13
	s_nop 0
	global_load_lds_dwordx4 v[218:219], off
	s_waitcnt vmcnt(8)
	s_waitcnt lgkmcnt(0)
	s_barrier
	s_setprio 1
	v_mfma_f32_16x16x32_bf16 v[128:131], v[142:145], v[174:177], v[128:131]
	v_mfma_f32_16x16x32_bf16 v[124:127], v[150:153], v[174:177], v[124:127]
	v_mfma_f32_16x16x32_bf16 v[112:115], v[142:145], v[182:185], v[112:115]
	v_mfma_f32_16x16x32_bf16 v[108:111], v[150:153], v[182:185], v[108:111]
	v_mfma_f32_16x16x32_bf16 v[96:99], v[142:145], v[190:193], v[96:99]
	v_mfma_f32_16x16x32_bf16 v[92:95], v[150:153], v[190:193], v[92:95]
	v_mfma_f32_16x16x32_bf16 v[80:83], v[142:145], v[204:207], v[80:83]
	v_mfma_f32_16x16x32_bf16 v[76:79], v[150:153], v[204:207], v[76:79]
	v_mfma_f32_16x16x32_bf16 v[128:131], v[146:149], v[178:181], v[128:131]
	v_mfma_f32_16x16x32_bf16 v[124:127], v[154:157], v[178:181], v[124:127]
	v_mfma_f32_16x16x32_bf16 v[112:115], v[146:149], v[186:189], v[112:115]
	v_mfma_f32_16x16x32_bf16 v[108:111], v[154:157], v[186:189], v[108:111]
	v_mfma_f32_16x16x32_bf16 v[96:99], v[146:149], v[194:197], v[96:99]
	v_mfma_f32_16x16x32_bf16 v[92:95], v[154:157], v[194:197], v[92:95]
	v_mfma_f32_16x16x32_bf16 v[80:83], v[146:149], v[208:211], v[80:83]
	v_mfma_f32_16x16x32_bf16 v[76:79], v[154:157], v[208:211], v[76:79]
	s_setprio 0
	s_setprio 1
	v_mfma_f32_16x16x32_bf16 v[120:123], v[158:161], v[174:177], v[120:123]
	v_mfma_f32_16x16x32_bf16 v[116:119], v[166:169], v[174:177], v[116:119]
	v_mfma_f32_16x16x32_bf16 v[104:107], v[158:161], v[182:185], v[104:107]
	v_mfma_f32_16x16x32_bf16 v[100:103], v[166:169], v[182:185], v[100:103]
	v_mfma_f32_16x16x32_bf16 v[88:91], v[158:161], v[190:193], v[88:91]
	v_mfma_f32_16x16x32_bf16 v[84:87], v[166:169], v[190:193], v[84:87]
	v_mfma_f32_16x16x32_bf16 v[72:75], v[158:161], v[204:207], v[72:75]
	v_mfma_f32_16x16x32_bf16 v[68:71], v[166:169], v[204:207], v[68:71]
	v_mfma_f32_16x16x32_bf16 v[120:123], v[162:165], v[178:181], v[120:123]
	v_mfma_f32_16x16x32_bf16 v[116:119], v[170:173], v[178:181], v[116:119]
	v_mfma_f32_16x16x32_bf16 v[104:107], v[162:165], v[186:189], v[104:107]
	v_mfma_f32_16x16x32_bf16 v[100:103], v[170:173], v[186:189], v[100:103]
	v_mfma_f32_16x16x32_bf16 v[88:91], v[162:165], v[194:197], v[88:91]
	v_mfma_f32_16x16x32_bf16 v[84:87], v[170:173], v[194:197], v[84:87]
	v_mfma_f32_16x16x32_bf16 v[72:75], v[162:165], v[208:211], v[72:75]
	v_mfma_f32_16x16x32_bf16 v[68:71], v[170:173], v[208:211], v[68:71]
	s_setprio 0
	s_barrier
	s_add_i32 s29, s29, s9
	v_lshl_add_u64 v[198:199], v[198:199], 0, s[68:69]
	s_mov_b32 m0, s29
	ds_read_b128 v[174:177], v141 offset:49152
	ds_read_b128 v[178:181], v141 offset:50176
	ds_read_b128 v[182:185], v141 offset:51200
	ds_read_b128 v[186:189], v141 offset:52224
	ds_read_b128 v[190:193], v141 offset:53248
	ds_read_b128 v[194:197], v141 offset:54272
	ds_read_b128 v[204:207], v141 offset:55296
	ds_read_b128 v[208:211], v141 offset:56320
	global_load_lds_dwordx4 v[198:199], off
	s_add_i32 m0, s29, 0x2000
	s_add_u32 s26, s26, 0x80080
	v_lshl_add_u64 v[198:199], v[212:213], 0, s[68:69]
	s_addc_u32 s27, s27, 0
	s_add_i32 s29, s33, s9
	global_load_lds_dwordx4 v[198:199], off
	v_lshl_add_u64 v[198:199], s[26:27], 0, v[2:3]
	s_mov_b32 m0, s29
	s_nop 0
	global_load_lds_dwordx4 v[198:199], off
	v_lshl_add_u64 v[198:199], s[26:27], 0, v[134:135]
	s_add_i32 m0, s29, 0x2000
	s_nop 0
	global_load_lds_dwordx4 v[198:199], off
	v_lshl_add_u64 v[198:199], v[214:215], 0, s[68:69]
	s_mov_b32 m0, s14
	s_nop 0
	global_load_lds_dwordx4 v[198:199], off
	v_lshl_add_u64 v[198:199], v[216:217], 0, s[68:69]
	s_mov_b32 m0, s15
	s_nop 0
	global_load_lds_dwordx4 v[198:199], off
	s_waitcnt vmcnt(8)
	s_waitcnt lgkmcnt(0)
	s_barrier
	s_setprio 1
	v_mfma_f32_16x16x32_bf16 v[64:67], v[142:145], v[174:177], v[64:67]
	v_mfma_f32_16x16x32_bf16 v[60:63], v[150:153], v[174:177], v[60:63]
	v_mfma_f32_16x16x32_bf16 v[48:51], v[142:145], v[182:185], v[48:51]
	v_mfma_f32_16x16x32_bf16 v[44:47], v[150:153], v[182:185], v[44:47]
	v_mfma_f32_16x16x32_bf16 v[32:35], v[142:145], v[190:193], v[32:35]
	v_mfma_f32_16x16x32_bf16 v[28:31], v[150:153], v[190:193], v[28:31]
	v_mfma_f32_16x16x32_bf16 v[16:19], v[142:145], v[204:207], v[16:19]
	v_mfma_f32_16x16x32_bf16 v[12:15], v[150:153], v[204:207], v[12:15]
	v_mfma_f32_16x16x32_bf16 v[64:67], v[146:149], v[178:181], v[64:67]
	v_mfma_f32_16x16x32_bf16 v[60:63], v[154:157], v[178:181], v[60:63]
	v_mfma_f32_16x16x32_bf16 v[48:51], v[146:149], v[186:189], v[48:51]
	v_mfma_f32_16x16x32_bf16 v[44:47], v[154:157], v[186:189], v[44:47]
	v_mfma_f32_16x16x32_bf16 v[32:35], v[146:149], v[194:197], v[32:35]
	v_mfma_f32_16x16x32_bf16 v[28:31], v[154:157], v[194:197], v[28:31]
	v_mfma_f32_16x16x32_bf16 v[16:19], v[146:149], v[208:211], v[16:19]
	v_mfma_f32_16x16x32_bf16 v[12:15], v[154:157], v[208:211], v[12:15]
	s_setprio 0
	s_setprio 1
	v_mfma_f32_16x16x32_bf16 v[56:59], v[158:161], v[174:177], v[56:59]
	v_mfma_f32_16x16x32_bf16 v[52:55], v[166:169], v[174:177], v[52:55]
	v_mfma_f32_16x16x32_bf16 v[40:43], v[158:161], v[182:185], v[40:43]
	v_mfma_f32_16x16x32_bf16 v[36:39], v[166:169], v[182:185], v[36:39]
	v_mfma_f32_16x16x32_bf16 v[24:27], v[158:161], v[190:193], v[24:27]
	v_mfma_f32_16x16x32_bf16 v[20:23], v[166:169], v[190:193], v[20:23]
	v_mfma_f32_16x16x32_bf16 v[8:11], v[158:161], v[204:207], v[8:11]
	v_mfma_f32_16x16x32_bf16 v[4:7], v[166:169], v[204:207], v[4:7]
	v_mfma_f32_16x16x32_bf16 v[56:59], v[162:165], v[178:181], v[56:59]
	v_mfma_f32_16x16x32_bf16 v[52:55], v[170:173], v[178:181], v[52:55]
	v_mfma_f32_16x16x32_bf16 v[40:43], v[162:165], v[186:189], v[40:43]
	v_mfma_f32_16x16x32_bf16 v[36:39], v[170:173], v[186:189], v[36:39]
	v_mfma_f32_16x16x32_bf16 v[24:27], v[162:165], v[194:197], v[24:27]
	v_mfma_f32_16x16x32_bf16 v[20:23], v[170:173], v[194:197], v[20:23]
	v_mfma_f32_16x16x32_bf16 v[8:11], v[162:165], v[208:211], v[8:11]
	v_mfma_f32_16x16x32_bf16 v[4:7], v[170:173], v[208:211], v[4:7]
	s_setprio 0
	s_barrier
	s_add_i32 s28, s28, 2
	s_add_u32 s24, s24, 0x100
	s_addc_u32 s25, s25, 0
	s_cmp_lt_u32 s28, 30
.LBB0_854:
	s_add_u32 s26, s18, s24
	s_addc_u32 s27, s19, s25
	s_add_u32 s26, s26, 0x22100100
	s_addc_u32 s27, s27, 0
	s_add_u32 s29, s16, s24
	s_addc_u32 s30, s17, s25
	s_add_i32 s31, 0, 0x10000
	s_cmpk_eq_i32 s24, 0xf00
	s_cselect_b32 s37, s23, s27
	s_cselect_b32 s36, s22, s26
	s_cselect_b32 s27, s21, s30
	s_cselect_b32 s26, s20, s29
	s_add_i32 s29, 0, 0x14000
	v_add_u32_e32 v154, s31, v140
	v_add_u32_e32 v170, s29, v140
	ds_read_b128 v[142:145], v154
	ds_read_b128 v[146:149], v154 offset:1024
	ds_read_b128 v[150:153], v154 offset:2048
	ds_read_b128 v[154:157], v154 offset:3072
	ds_read_b128 v[158:161], v170
	ds_read_b128 v[162:165], v170 offset:1024
	ds_read_b128 v[166:169], v170 offset:2048
	ds_read_b128 v[170:173], v170 offset:3072
	v_lshl_add_u64 v[198:199], v[138:139], 0, s[24:25]
	s_add_i32 m0, s10, 0xc000
	ds_read_b128 v[174:177], v141
	ds_read_b128 v[178:181], v141 offset:1024
	ds_read_b128 v[182:185], v141 offset:2048
	ds_read_b128 v[186:189], v141 offset:3072
	ds_read_b128 v[190:193], v141 offset:4096
	ds_read_b128 v[194:197], v141 offset:5120
	ds_read_b128 v[204:207], v141 offset:6144
	ds_read_b128 v[208:211], v141 offset:7168
	global_load_lds_dwordx4 v[198:199], off
	v_lshl_add_u64 v[198:199], v[136:137], 0, s[24:25]
	s_add_i32 m0, s10, 0xe000
	s_nop 0
	global_load_lds_dwordx4 v[198:199], off
	s_waitcnt vmcnt(8)
	s_waitcnt lgkmcnt(0)
	s_barrier
	s_setprio 1
	v_mfma_f32_16x16x32_bf16 v[128:131], v[142:145], v[174:177], v[128:131]
	v_mfma_f32_16x16x32_bf16 v[124:127], v[150:153], v[174:177], v[124:127]
	v_mfma_f32_16x16x32_bf16 v[112:115], v[142:145], v[182:185], v[112:115]
	v_mfma_f32_16x16x32_bf16 v[108:111], v[150:153], v[182:185], v[108:111]
	v_mfma_f32_16x16x32_bf16 v[96:99], v[142:145], v[190:193], v[96:99]
	v_mfma_f32_16x16x32_bf16 v[92:95], v[150:153], v[190:193], v[92:95]
	v_mfma_f32_16x16x32_bf16 v[80:83], v[142:145], v[204:207], v[80:83]
	v_mfma_f32_16x16x32_bf16 v[76:79], v[150:153], v[204:207], v[76:79]
	v_mfma_f32_16x16x32_bf16 v[128:131], v[146:149], v[178:181], v[128:131]
	v_mfma_f32_16x16x32_bf16 v[124:127], v[154:157], v[178:181], v[124:127]
	v_mfma_f32_16x16x32_bf16 v[112:115], v[146:149], v[186:189], v[112:115]
	v_mfma_f32_16x16x32_bf16 v[108:111], v[154:157], v[186:189], v[108:111]
	v_mfma_f32_16x16x32_bf16 v[96:99], v[146:149], v[194:197], v[96:99]
	v_mfma_f32_16x16x32_bf16 v[92:95], v[154:157], v[194:197], v[92:95]
	v_mfma_f32_16x16x32_bf16 v[80:83], v[146:149], v[208:211], v[80:83]
	v_mfma_f32_16x16x32_bf16 v[76:79], v[154:157], v[208:211], v[76:79]
	s_setprio 0
	s_setprio 1
	v_mfma_f32_16x16x32_bf16 v[120:123], v[158:161], v[174:177], v[120:123]
	v_mfma_f32_16x16x32_bf16 v[116:119], v[166:169], v[174:177], v[116:119]
	v_mfma_f32_16x16x32_bf16 v[104:107], v[158:161], v[182:185], v[104:107]
	v_mfma_f32_16x16x32_bf16 v[100:103], v[166:169], v[182:185], v[100:103]
	v_mfma_f32_16x16x32_bf16 v[88:91], v[158:161], v[190:193], v[88:91]
	v_mfma_f32_16x16x32_bf16 v[84:87], v[166:169], v[190:193], v[84:87]
	v_mfma_f32_16x16x32_bf16 v[72:75], v[158:161], v[204:207], v[72:75]
	v_mfma_f32_16x16x32_bf16 v[68:71], v[166:169], v[204:207], v[68:71]
	v_mfma_f32_16x16x32_bf16 v[120:123], v[162:165], v[178:181], v[120:123]
	v_mfma_f32_16x16x32_bf16 v[116:119], v[170:173], v[178:181], v[116:119]
	v_mfma_f32_16x16x32_bf16 v[104:107], v[162:165], v[186:189], v[104:107]
	v_mfma_f32_16x16x32_bf16 v[100:103], v[170:173], v[186:189], v[100:103]
	v_mfma_f32_16x16x32_bf16 v[88:91], v[162:165], v[194:197], v[88:91]
	v_mfma_f32_16x16x32_bf16 v[84:87], v[170:173], v[194:197], v[84:87]
	v_mfma_f32_16x16x32_bf16 v[72:75], v[162:165], v[208:211], v[72:75]
	v_mfma_f32_16x16x32_bf16 v[68:71], v[170:173], v[208:211], v[68:71]
	s_setprio 0
	s_barrier
	s_add_i32 s30, s31, s9
	v_lshl_add_u64 v[198:199], s[26:27], 0, v[2:3]
	s_mov_b32 m0, s30
	ds_read_b128 v[174:177], v141 offset:16384
	ds_read_b128 v[178:181], v141 offset:17408
	ds_read_b128 v[182:185], v141 offset:18432
	ds_read_b128 v[186:189], v141 offset:19456
	ds_read_b128 v[190:193], v141 offset:20480
	ds_read_b128 v[194:197], v141 offset:21504
	ds_read_b128 v[204:207], v141 offset:22528
	ds_read_b128 v[208:211], v141 offset:23552
	global_load_lds_dwordx4 v[198:199], off
	s_add_i32 m0, s30, 0x2000
	s_add_u32 s30, s26, 0x80000
	v_lshl_add_u64 v[212:213], s[26:27], 0, v[134:135]
	s_addc_u32 s31, s27, 0
	s_add_i32 s29, s29, s9
	global_load_lds_dwordx4 v[212:213], off
	v_lshl_add_u64 v[214:215], s[30:31], 0, v[2:3]
	s_mov_b32 m0, s29
	v_lshl_add_u64 v[216:217], s[36:37], 0, v[132:133]
	global_load_lds_dwordx4 v[214:215], off
	v_lshl_add_u64 v[214:215], s[30:31], 0, v[134:135]
	s_add_i32 m0, s29, 0x2000
	s_nop 0
	global_load_lds_dwordx4 v[214:215], off
	v_lshl_add_u64 v[214:215], s[36:37], 0, v[0:1]
	s_mov_b32 m0, s10
	s_nop 0
	global_load_lds_dwordx4 v[214:215], off
	s_mov_b32 m0, s11
	s_nop 0
	global_load_lds_dwordx4 v[216:217], off
	s_waitcnt vmcnt(8)
	s_waitcnt lgkmcnt(0)
	s_barrier
	s_setprio 1
	v_mfma_f32_16x16x32_bf16 v[64:67], v[142:145], v[174:177], v[64:67]
	v_mfma_f32_16x16x32_bf16 v[60:63], v[150:153], v[174:177], v[60:63]
	v_mfma_f32_16x16x32_bf16 v[48:51], v[142:145], v[182:185], v[48:51]
	v_mfma_f32_16x16x32_bf16 v[44:47], v[150:153], v[182:185], v[44:47]
	v_mfma_f32_16x16x32_bf16 v[32:35], v[142:145], v[190:193], v[32:35]
	v_mfma_f32_16x16x32_bf16 v[28:31], v[150:153], v[190:193], v[28:31]
	v_mfma_f32_16x16x32_bf16 v[16:19], v[142:145], v[204:207], v[16:19]
	v_mfma_f32_16x16x32_bf16 v[12:15], v[150:153], v[204:207], v[12:15]
	v_mfma_f32_16x16x32_bf16 v[64:67], v[146:149], v[178:181], v[64:67]
	v_mfma_f32_16x16x32_bf16 v[60:63], v[154:157], v[178:181], v[60:63]
	v_mfma_f32_16x16x32_bf16 v[48:51], v[146:149], v[186:189], v[48:51]
	v_mfma_f32_16x16x32_bf16 v[44:47], v[154:157], v[186:189], v[44:47]
	v_mfma_f32_16x16x32_bf16 v[32:35], v[146:149], v[194:197], v[32:35]
	v_mfma_f32_16x16x32_bf16 v[28:31], v[154:157], v[194:197], v[28:31]
	v_mfma_f32_16x16x32_bf16 v[16:19], v[146:149], v[208:211], v[16:19]
	v_mfma_f32_16x16x32_bf16 v[12:15], v[154:157], v[208:211], v[12:15]
	s_setprio 0
	s_setprio 1
	v_mfma_f32_16x16x32_bf16 v[56:59], v[158:161], v[174:177], v[56:59]
	v_mfma_f32_16x16x32_bf16 v[52:55], v[166:169], v[174:177], v[52:55]
	v_mfma_f32_16x16x32_bf16 v[40:43], v[158:161], v[182:185], v[40:43]
	v_mfma_f32_16x16x32_bf16 v[36:39], v[166:169], v[182:185], v[36:39]
	v_mfma_f32_16x16x32_bf16 v[24:27], v[158:161], v[190:193], v[24:27]
	v_mfma_f32_16x16x32_bf16 v[20:23], v[166:169], v[190:193], v[20:23]
	v_mfma_f32_16x16x32_bf16 v[8:11], v[158:161], v[204:207], v[8:11]
	v_mfma_f32_16x16x32_bf16 v[4:7], v[166:169], v[204:207], v[4:7]
	v_mfma_f32_16x16x32_bf16 v[56:59], v[162:165], v[178:181], v[56:59]
	v_mfma_f32_16x16x32_bf16 v[52:55], v[170:173], v[178:181], v[52:55]
	v_mfma_f32_16x16x32_bf16 v[40:43], v[162:165], v[186:189], v[40:43]
	v_mfma_f32_16x16x32_bf16 v[36:39], v[170:173], v[186:189], v[36:39]
	v_mfma_f32_16x16x32_bf16 v[24:27], v[162:165], v[194:197], v[24:27]
	v_mfma_f32_16x16x32_bf16 v[20:23], v[170:173], v[194:197], v[20:23]
	v_mfma_f32_16x16x32_bf16 v[8:11], v[162:165], v[208:211], v[8:11]
	v_mfma_f32_16x16x32_bf16 v[4:7], v[170:173], v[208:211], v[4:7]
	s_setprio 0
	s_barrier
	s_add_i32 s29, 0, 0x18000
	s_add_i32 s33, 0, 0x1c000
	v_add_u32_e32 v154, s29, v140
	v_add_u32_e32 v170, s33, v140
	ds_read_b128 v[142:145], v154
	ds_read_b128 v[146:149], v154 offset:1024
	ds_read_b128 v[150:153], v154 offset:2048
	ds_read_b128 v[154:157], v154 offset:3072
	ds_read_b128 v[158:161], v170
	ds_read_b128 v[162:165], v170 offset:1024
	ds_read_b128 v[166:169], v170 offset:2048
	ds_read_b128 v[170:173], v170 offset:3072
	s_add_u32 s30, s36, 0x80000
	s_addc_u32 s31, s37, 0
	s_mov_b32 m0, s12
	v_lshl_add_u64 v[218:219], s[30:31], 0, v[0:1]
	ds_read_b128 v[174:177], v141 offset:32768
	ds_read_b128 v[178:181], v141 offset:33792
	ds_read_b128 v[182:185], v141 offset:34816
	ds_read_b128 v[186:189], v141 offset:35840
	ds_read_b128 v[190:193], v141 offset:36864
	ds_read_b128 v[194:197], v141 offset:37888
	ds_read_b128 v[204:207], v141 offset:38912
	ds_read_b128 v[208:211], v141 offset:39936
	global_load_lds_dwordx4 v[218:219], off
	v_lshl_add_u64 v[218:219], s[30:31], 0, v[132:133]
	s_mov_b32 m0, s13
	s_nop 0
	global_load_lds_dwordx4 v[218:219], off
	s_waitcnt vmcnt(8)
	s_waitcnt lgkmcnt(0)
	s_barrier
	s_setprio 1
	v_mfma_f32_16x16x32_bf16 v[128:131], v[142:145], v[174:177], v[128:131]
	v_mfma_f32_16x16x32_bf16 v[124:127], v[150:153], v[174:177], v[124:127]
	v_mfma_f32_16x16x32_bf16 v[112:115], v[142:145], v[182:185], v[112:115]
	v_mfma_f32_16x16x32_bf16 v[108:111], v[150:153], v[182:185], v[108:111]
	v_mfma_f32_16x16x32_bf16 v[96:99], v[142:145], v[190:193], v[96:99]
	v_mfma_f32_16x16x32_bf16 v[92:95], v[150:153], v[190:193], v[92:95]
	v_mfma_f32_16x16x32_bf16 v[80:83], v[142:145], v[204:207], v[80:83]
	v_mfma_f32_16x16x32_bf16 v[76:79], v[150:153], v[204:207], v[76:79]
	v_mfma_f32_16x16x32_bf16 v[128:131], v[146:149], v[178:181], v[128:131]
	v_mfma_f32_16x16x32_bf16 v[124:127], v[154:157], v[178:181], v[124:127]
	v_mfma_f32_16x16x32_bf16 v[112:115], v[146:149], v[186:189], v[112:115]
	v_mfma_f32_16x16x32_bf16 v[108:111], v[154:157], v[186:189], v[108:111]
	v_mfma_f32_16x16x32_bf16 v[96:99], v[146:149], v[194:197], v[96:99]
	v_mfma_f32_16x16x32_bf16 v[92:95], v[154:157], v[194:197], v[92:95]
	v_mfma_f32_16x16x32_bf16 v[80:83], v[146:149], v[208:211], v[80:83]
	v_mfma_f32_16x16x32_bf16 v[76:79], v[154:157], v[208:211], v[76:79]
	s_setprio 0
	s_setprio 1
	v_mfma_f32_16x16x32_bf16 v[120:123], v[158:161], v[174:177], v[120:123]
	v_mfma_f32_16x16x32_bf16 v[116:119], v[166:169], v[174:177], v[116:119]
	v_mfma_f32_16x16x32_bf16 v[104:107], v[158:161], v[182:185], v[104:107]
	v_mfma_f32_16x16x32_bf16 v[100:103], v[166:169], v[182:185], v[100:103]
	v_mfma_f32_16x16x32_bf16 v[88:91], v[158:161], v[190:193], v[88:91]
	v_mfma_f32_16x16x32_bf16 v[84:87], v[166:169], v[190:193], v[84:87]
	v_mfma_f32_16x16x32_bf16 v[72:75], v[158:161], v[204:207], v[72:75]
	v_mfma_f32_16x16x32_bf16 v[68:71], v[166:169], v[204:207], v[68:71]
	v_mfma_f32_16x16x32_bf16 v[120:123], v[162:165], v[178:181], v[120:123]
	v_mfma_f32_16x16x32_bf16 v[116:119], v[170:173], v[178:181], v[116:119]
	v_mfma_f32_16x16x32_bf16 v[104:107], v[162:165], v[186:189], v[104:107]
	v_mfma_f32_16x16x32_bf16 v[100:103], v[170:173], v[186:189], v[100:103]
	v_mfma_f32_16x16x32_bf16 v[88:91], v[162:165], v[194:197], v[88:91]
	v_mfma_f32_16x16x32_bf16 v[84:87], v[170:173], v[194:197], v[84:87]
	v_mfma_f32_16x16x32_bf16 v[72:75], v[162:165], v[208:211], v[72:75]
	v_mfma_f32_16x16x32_bf16 v[68:71], v[170:173], v[208:211], v[68:71]
	s_setprio 0
	s_barrier
	s_add_i32 s29, s29, s9
	v_lshl_add_u64 v[198:199], v[198:199], 0, s[68:69]
	s_mov_b32 m0, s29
	ds_read_b128 v[174:177], v141 offset:49152
	ds_read_b128 v[178:181], v141 offset:50176
	ds_read_b128 v[182:185], v141 offset:51200
	ds_read_b128 v[186:189], v141 offset:52224
	ds_read_b128 v[190:193], v141 offset:53248
	ds_read_b128 v[194:197], v141 offset:54272
	ds_read_b128 v[204:207], v141 offset:55296
	ds_read_b128 v[208:211], v141 offset:56320
	global_load_lds_dwordx4 v[198:199], off
	s_add_i32 m0, s29, 0x2000
	s_add_u32 s26, s26, 0x80080
	v_lshl_add_u64 v[198:199], v[212:213], 0, s[68:69]
	s_addc_u32 s27, s27, 0
	s_add_i32 s29, s33, s9
	global_load_lds_dwordx4 v[198:199], off
	v_lshl_add_u64 v[198:199], s[26:27], 0, v[2:3]
	s_mov_b32 m0, s29
	s_nop 0
	global_load_lds_dwordx4 v[198:199], off
	v_lshl_add_u64 v[198:199], s[26:27], 0, v[134:135]
	s_add_i32 m0, s29, 0x2000
	s_nop 0
	global_load_lds_dwordx4 v[198:199], off
	v_lshl_add_u64 v[198:199], v[214:215], 0, s[68:69]
	s_mov_b32 m0, s14
	s_nop 0
	global_load_lds_dwordx4 v[198:199], off
	v_lshl_add_u64 v[198:199], v[216:217], 0, s[68:69]
	s_mov_b32 m0, s15
	s_nop 0
	global_load_lds_dwordx4 v[198:199], off
	s_waitcnt vmcnt(8)
	s_waitcnt lgkmcnt(0)
	s_barrier
	s_setprio 1
	v_mfma_f32_16x16x32_bf16 v[64:67], v[142:145], v[174:177], v[64:67]
	v_mfma_f32_16x16x32_bf16 v[60:63], v[150:153], v[174:177], v[60:63]
	v_mfma_f32_16x16x32_bf16 v[48:51], v[142:145], v[182:185], v[48:51]
	v_mfma_f32_16x16x32_bf16 v[44:47], v[150:153], v[182:185], v[44:47]
	v_mfma_f32_16x16x32_bf16 v[32:35], v[142:145], v[190:193], v[32:35]
	v_mfma_f32_16x16x32_bf16 v[28:31], v[150:153], v[190:193], v[28:31]
	v_mfma_f32_16x16x32_bf16 v[16:19], v[142:145], v[204:207], v[16:19]
	v_mfma_f32_16x16x32_bf16 v[12:15], v[150:153], v[204:207], v[12:15]
	v_mfma_f32_16x16x32_bf16 v[64:67], v[146:149], v[178:181], v[64:67]
	v_mfma_f32_16x16x32_bf16 v[60:63], v[154:157], v[178:181], v[60:63]
	v_mfma_f32_16x16x32_bf16 v[48:51], v[146:149], v[186:189], v[48:51]
	v_mfma_f32_16x16x32_bf16 v[44:47], v[154:157], v[186:189], v[44:47]
	v_mfma_f32_16x16x32_bf16 v[32:35], v[146:149], v[194:197], v[32:35]
	v_mfma_f32_16x16x32_bf16 v[28:31], v[154:157], v[194:197], v[28:31]
	v_mfma_f32_16x16x32_bf16 v[16:19], v[146:149], v[208:211], v[16:19]
	v_mfma_f32_16x16x32_bf16 v[12:15], v[154:157], v[208:211], v[12:15]
	s_setprio 0
	s_setprio 1
	v_mfma_f32_16x16x32_bf16 v[56:59], v[158:161], v[174:177], v[56:59]
	v_mfma_f32_16x16x32_bf16 v[52:55], v[166:169], v[174:177], v[52:55]
	v_mfma_f32_16x16x32_bf16 v[40:43], v[158:161], v[182:185], v[40:43]
	v_mfma_f32_16x16x32_bf16 v[36:39], v[166:169], v[182:185], v[36:39]
	v_mfma_f32_16x16x32_bf16 v[24:27], v[158:161], v[190:193], v[24:27]
	v_mfma_f32_16x16x32_bf16 v[20:23], v[166:169], v[190:193], v[20:23]
	v_mfma_f32_16x16x32_bf16 v[8:11], v[158:161], v[204:207], v[8:11]
	v_mfma_f32_16x16x32_bf16 v[4:7], v[166:169], v[204:207], v[4:7]
	v_mfma_f32_16x16x32_bf16 v[56:59], v[162:165], v[178:181], v[56:59]
	v_mfma_f32_16x16x32_bf16 v[52:55], v[170:173], v[178:181], v[52:55]
	v_mfma_f32_16x16x32_bf16 v[40:43], v[162:165], v[186:189], v[40:43]
	v_mfma_f32_16x16x32_bf16 v[36:39], v[170:173], v[186:189], v[36:39]
	v_mfma_f32_16x16x32_bf16 v[24:27], v[162:165], v[194:197], v[24:27]
	v_mfma_f32_16x16x32_bf16 v[20:23], v[170:173], v[194:197], v[20:23]
	v_mfma_f32_16x16x32_bf16 v[8:11], v[162:165], v[208:211], v[8:11]
	v_mfma_f32_16x16x32_bf16 v[4:7], v[170:173], v[208:211], v[4:7]
	s_setprio 0
	s_barrier
	s_add_i32 s28, s28, 2
	s_add_u32 s24, s24, 0x100
	s_addc_u32 s25, s25, 0
	s_cmp_lt_u32 s28, 30
	s_cbranch_scc1 .LBB0_854
	s_waitcnt vmcnt(0)
	s_cmpk_gt_u32 s6, 0xff
	s_cbranch_scc1 .LBB0_857
	s_barrier

.LBB0_946:
	s_ashr_i32 s49, s48, 31
	s_andn2_b64 vcc, exec, s[56:57]
	s_lshl_b64 s[6:7], s[48:49], 19
	s_add_u32 s52, s62, s6
	s_addc_u32 s53, s63, s7
	s_and_b64 s[6:7], s[56:57], exec
	s_cselect_b32 s5, s53, s41
	s_cselect_b32 s6, s52, s40
	s_ashr_i32 s51, s50, 31
	s_lshl_b64 s[8:9], s[50:51], 19
	s_add_u32 s54, s64, s8
	s_addc_u32 s55, s65, s9
	s_and_b64 s[8:9], s[56:57], exec
	s_cselect_b32 s7, s55, s39
	s_cselect_b32 s8, s54, s38
	s_add_u32 s9, s38, 0x100
	v_cndmask_b32_e64 v4, 0, 1, s[56:57]
	s_addc_u32 s10, s39, 0
	v_cmp_ne_u32_e64 s[36:37], 1, v4
	s_add_u32 s38, s40, 0x40080
	s_addc_u32 s39, s41, 0
	s_mov_b32 s11, -2
	s_waitcnt lgkmcnt(0)
	s_add_u32 s12, s38, 0xfffc0080
	s_addc_u32 s13, s39, -1
	s_add_i32 s14, 0, 0x10000
	s_cmp_eq_u32 s11, 12
	s_cselect_b32 s57, s5, s13
	s_cselect_b32 s56, s6, s12
	s_cselect_b32 s41, s7, s10
	s_cselect_b32 s40, s8, s9
	s_add_i32 s15, 0, 0x14000
	v_add_u32_e32 v144, s14, v230
	v_add_u32_e32 v160, s15, v230
	ds_read_b128 v[124:127], v144
	ds_read_b128 v[128:131], v144 offset:1024
	ds_read_b128 v[136:139], v144 offset:2048
	ds_read_b128 v[144:147], v144 offset:3072
	ds_read_b128 v[148:151], v160
	ds_read_b128 v[152:155], v160 offset:1024
	ds_read_b128 v[156:159], v160 offset:2048
	ds_read_b128 v[160:163], v160 offset:3072
	v_lshl_add_u64 v[196:197], s[38:39], 0, v[222:223]
	s_add_i32 m0, s71, 0xc000
	ds_read_b128 v[164:167], v243
	ds_read_b128 v[168:171], v243 offset:1024
	ds_read_b128 v[172:175], v243 offset:2048
	ds_read_b128 v[176:179], v243 offset:3072
	ds_read_b128 v[180:183], v243 offset:4096
	ds_read_b128 v[184:187], v243 offset:5120
	ds_read_b128 v[188:191], v243 offset:6144
	ds_read_b128 v[192:195], v243 offset:7168
	global_load_lds_dwordx4 v[196:197], off
	v_lshl_add_u64 v[196:197], s[38:39], 0, v[220:221]
	s_add_i32 m0, s71, 0xe000
	s_nop 0
	global_load_lds_dwordx4 v[196:197], off
	s_waitcnt vmcnt(8)
	s_waitcnt lgkmcnt(0)
	s_barrier
	s_setprio 1
	v_mfma_f32_16x16x32_bf16 v[140:143], v[124:127], v[164:167], 0
	v_mfma_f32_16x16x32_bf16 v[132:135], v[136:139], v[164:167], 0
	v_mfma_f32_16x16x32_bf16 v[112:115], v[124:127], v[172:175], 0
	v_mfma_f32_16x16x32_bf16 v[108:111], v[136:139], v[172:175], 0
	v_mfma_f32_16x16x32_bf16 v[96:99], v[124:127], v[180:183], 0
	v_mfma_f32_16x16x32_bf16 v[92:95], v[136:139], v[180:183], 0
	v_mfma_f32_16x16x32_bf16 v[80:83], v[124:127], v[188:191], 0
	v_mfma_f32_16x16x32_bf16 v[76:79], v[136:139], v[188:191], 0
	v_mfma_f32_16x16x32_bf16 v[140:143], v[128:131], v[168:171], v[140:143]
	v_mfma_f32_16x16x32_bf16 v[132:135], v[144:147], v[168:171], v[132:135]
	v_mfma_f32_16x16x32_bf16 v[112:115], v[128:131], v[176:179], v[112:115]
	v_mfma_f32_16x16x32_bf16 v[108:111], v[144:147], v[176:179], v[108:111]
	v_mfma_f32_16x16x32_bf16 v[96:99], v[128:131], v[184:187], v[96:99]
	v_mfma_f32_16x16x32_bf16 v[92:95], v[144:147], v[184:187], v[92:95]
	v_mfma_f32_16x16x32_bf16 v[80:83], v[128:131], v[192:195], v[80:83]
	v_mfma_f32_16x16x32_bf16 v[76:79], v[144:147], v[192:195], v[76:79]
	s_setprio 0
	s_setprio 1
	v_mfma_f32_16x16x32_bf16 v[120:123], v[148:151], v[164:167], 0
	v_mfma_f32_16x16x32_bf16 v[116:119], v[156:159], v[164:167], 0
	v_mfma_f32_16x16x32_bf16 v[104:107], v[148:151], v[172:175], 0
	v_mfma_f32_16x16x32_bf16 v[100:103], v[156:159], v[172:175], 0
	v_mfma_f32_16x16x32_bf16 v[88:91], v[148:151], v[180:183], 0
	v_mfma_f32_16x16x32_bf16 v[84:87], v[156:159], v[180:183], 0
	v_mfma_f32_16x16x32_bf16 v[72:75], v[148:151], v[188:191], 0
	v_mfma_f32_16x16x32_bf16 v[68:71], v[156:159], v[188:191], 0
	v_mfma_f32_16x16x32_bf16 v[120:123], v[152:155], v[168:171], v[120:123]
	v_mfma_f32_16x16x32_bf16 v[116:119], v[160:163], v[168:171], v[116:119]
	v_mfma_f32_16x16x32_bf16 v[104:107], v[152:155], v[176:179], v[104:107]
	v_mfma_f32_16x16x32_bf16 v[100:103], v[160:163], v[176:179], v[100:103]
	v_mfma_f32_16x16x32_bf16 v[88:91], v[152:155], v[184:187], v[88:91]
	v_mfma_f32_16x16x32_bf16 v[84:87], v[160:163], v[184:187], v[84:87]
	v_mfma_f32_16x16x32_bf16 v[72:75], v[152:155], v[192:195], v[72:75]
	v_mfma_f32_16x16x32_bf16 v[68:71], v[160:163], v[192:195], v[68:71]
	s_setprio 0
	s_barrier
	s_add_i32 s12, s14, s70
	v_lshl_add_u64 v[196:197], s[40:41], 0, v[2:3]
	s_mov_b32 m0, s12
	ds_read_b128 v[164:167], v243 offset:16384
	ds_read_b128 v[168:171], v243 offset:17408
	ds_read_b128 v[172:175], v243 offset:18432
	ds_read_b128 v[176:179], v243 offset:19456
	ds_read_b128 v[180:183], v243 offset:20480
	ds_read_b128 v[184:187], v243 offset:21504
	ds_read_b128 v[188:191], v243 offset:22528
	ds_read_b128 v[192:195], v243 offset:23552
	global_load_lds_dwordx4 v[196:197], off
	s_add_i32 m0, s12, 0x2000
	s_add_u32 s12, s40, 0x40000
	v_lshl_add_u64 v[198:199], s[40:41], 0, v[218:219]
	s_addc_u32 s13, s41, 0
	s_add_i32 s14, s15, s70
	global_load_lds_dwordx4 v[198:199], off
	v_lshl_add_u64 v[200:201], s[12:13], 0, v[2:3]
	s_mov_b32 m0, s14
	v_lshl_add_u64 v[202:203], s[56:57], 0, v[216:217]
	global_load_lds_dwordx4 v[200:201], off
	v_lshl_add_u64 v[200:201], s[12:13], 0, v[218:219]
	s_add_i32 m0, s14, 0x2000
	s_nop 0
	global_load_lds_dwordx4 v[200:201], off
	v_lshl_add_u64 v[200:201], s[56:57], 0, v[0:1]
	s_mov_b32 m0, s71
	s_nop 0
	global_load_lds_dwordx4 v[200:201], off
	s_mov_b32 m0, s80
	s_nop 0
	global_load_lds_dwordx4 v[202:203], off
	s_waitcnt vmcnt(8)
	s_waitcnt lgkmcnt(0)
	s_barrier
	s_setprio 1
	v_mfma_f32_16x16x32_bf16 v[64:67], v[124:127], v[164:167], 0
	v_mfma_f32_16x16x32_bf16 v[60:63], v[136:139], v[164:167], 0
	v_mfma_f32_16x16x32_bf16 v[48:51], v[124:127], v[172:175], 0
	v_mfma_f32_16x16x32_bf16 v[44:47], v[136:139], v[172:175], 0
	v_mfma_f32_16x16x32_bf16 v[32:35], v[124:127], v[180:183], 0
	v_mfma_f32_16x16x32_bf16 v[28:31], v[136:139], v[180:183], 0
	v_mfma_f32_16x16x32_bf16 v[16:19], v[124:127], v[188:191], 0
	v_mfma_f32_16x16x32_bf16 v[12:15], v[136:139], v[188:191], 0
	v_mfma_f32_16x16x32_bf16 v[64:67], v[128:131], v[168:171], v[64:67]
	v_mfma_f32_16x16x32_bf16 v[60:63], v[144:147], v[168:171], v[60:63]
	v_mfma_f32_16x16x32_bf16 v[48:51], v[128:131], v[176:179], v[48:51]
	v_mfma_f32_16x16x32_bf16 v[44:47], v[144:147], v[176:179], v[44:47]
	v_mfma_f32_16x16x32_bf16 v[32:35], v[128:131], v[184:187], v[32:35]
	v_mfma_f32_16x16x32_bf16 v[28:31], v[144:147], v[184:187], v[28:31]
	v_mfma_f32_16x16x32_bf16 v[16:19], v[128:131], v[192:195], v[16:19]
	v_mfma_f32_16x16x32_bf16 v[12:15], v[144:147], v[192:195], v[12:15]
	s_setprio 0
	s_setprio 1
	v_mfma_f32_16x16x32_bf16 v[56:59], v[148:151], v[164:167], 0
	v_mfma_f32_16x16x32_bf16 v[52:55], v[156:159], v[164:167], 0
	v_mfma_f32_16x16x32_bf16 v[40:43], v[148:151], v[172:175], 0
	v_mfma_f32_16x16x32_bf16 v[36:39], v[156:159], v[172:175], 0
	v_mfma_f32_16x16x32_bf16 v[24:27], v[148:151], v[180:183], 0
	v_mfma_f32_16x16x32_bf16 v[20:23], v[156:159], v[180:183], 0
	v_mfma_f32_16x16x32_bf16 v[8:11], v[148:151], v[188:191], 0
	v_mfma_f32_16x16x32_bf16 v[4:7], v[156:159], v[188:191], 0
	v_mfma_f32_16x16x32_bf16 v[56:59], v[152:155], v[168:171], v[56:59]
	v_mfma_f32_16x16x32_bf16 v[52:55], v[160:163], v[168:171], v[52:55]
	v_mfma_f32_16x16x32_bf16 v[40:43], v[152:155], v[176:179], v[40:43]
	v_mfma_f32_16x16x32_bf16 v[36:39], v[160:163], v[176:179], v[36:39]
	v_mfma_f32_16x16x32_bf16 v[24:27], v[152:155], v[184:187], v[24:27]
	v_mfma_f32_16x16x32_bf16 v[20:23], v[160:163], v[184:187], v[20:23]
	v_mfma_f32_16x16x32_bf16 v[8:11], v[152:155], v[192:195], v[8:11]
	v_mfma_f32_16x16x32_bf16 v[4:7], v[160:163], v[192:195], v[4:7]
	s_setprio 0
	s_barrier
	s_add_i32 s14, 0, 0x18000
	s_add_i32 s15, 0, 0x1c000
	v_add_u32_e32 v144, s14, v230
	v_add_u32_e32 v160, s15, v230
	ds_read_b128 v[124:127], v144
	ds_read_b128 v[128:131], v144 offset:1024
	ds_read_b128 v[136:139], v144 offset:2048
	ds_read_b128 v[144:147], v144 offset:3072
	ds_read_b128 v[148:151], v160
	ds_read_b128 v[152:155], v160 offset:1024
	ds_read_b128 v[156:159], v160 offset:2048
	ds_read_b128 v[160:163], v160 offset:3072
	s_add_u32 s12, s56, 0x40000
	s_addc_u32 s13, s57, 0
	s_mov_b32 m0, s81
	v_lshl_add_u64 v[204:205], s[12:13], 0, v[0:1]
	ds_read_b128 v[164:167], v243 offset:32768
	ds_read_b128 v[168:171], v243 offset:33792
	ds_read_b128 v[172:175], v243 offset:34816
	ds_read_b128 v[176:179], v243 offset:35840
	ds_read_b128 v[180:183], v243 offset:36864
	ds_read_b128 v[184:187], v243 offset:37888
	ds_read_b128 v[188:191], v243 offset:38912
	ds_read_b128 v[192:195], v243 offset:39936
	global_load_lds_dwordx4 v[204:205], off
	v_lshl_add_u64 v[204:205], s[12:13], 0, v[216:217]
	s_mov_b32 m0, s82
	s_nop 0
	global_load_lds_dwordx4 v[204:205], off
	s_waitcnt vmcnt(8)
	s_waitcnt lgkmcnt(0)
	s_barrier
	s_setprio 1
	v_mfma_f32_16x16x32_bf16 v[140:143], v[124:127], v[164:167], v[140:143]
	v_mfma_f32_16x16x32_bf16 v[132:135], v[136:139], v[164:167], v[132:135]
	v_mfma_f32_16x16x32_bf16 v[112:115], v[124:127], v[172:175], v[112:115]
	v_mfma_f32_16x16x32_bf16 v[108:111], v[136:139], v[172:175], v[108:111]
	v_mfma_f32_16x16x32_bf16 v[96:99], v[124:127], v[180:183], v[96:99]
	v_mfma_f32_16x16x32_bf16 v[92:95], v[136:139], v[180:183], v[92:95]
	v_mfma_f32_16x16x32_bf16 v[80:83], v[124:127], v[188:191], v[80:83]
	v_mfma_f32_16x16x32_bf16 v[76:79], v[136:139], v[188:191], v[76:79]
	v_mfma_f32_16x16x32_bf16 v[140:143], v[128:131], v[168:171], v[140:143]
	v_mfma_f32_16x16x32_bf16 v[132:135], v[144:147], v[168:171], v[132:135]
	v_mfma_f32_16x16x32_bf16 v[112:115], v[128:131], v[176:179], v[112:115]
	v_mfma_f32_16x16x32_bf16 v[108:111], v[144:147], v[176:179], v[108:111]
	v_mfma_f32_16x16x32_bf16 v[96:99], v[128:131], v[184:187], v[96:99]
	v_mfma_f32_16x16x32_bf16 v[92:95], v[144:147], v[184:187], v[92:95]
	v_mfma_f32_16x16x32_bf16 v[80:83], v[128:131], v[192:195], v[80:83]
	v_mfma_f32_16x16x32_bf16 v[76:79], v[144:147], v[192:195], v[76:79]
	s_setprio 0
	s_setprio 1
	v_mfma_f32_16x16x32_bf16 v[120:123], v[148:151], v[164:167], v[120:123]
	v_mfma_f32_16x16x32_bf16 v[116:119], v[156:159], v[164:167], v[116:119]
	v_mfma_f32_16x16x32_bf16 v[104:107], v[148:151], v[172:175], v[104:107]
	v_mfma_f32_16x16x32_bf16 v[100:103], v[156:159], v[172:175], v[100:103]
	v_mfma_f32_16x16x32_bf16 v[88:91], v[148:151], v[180:183], v[88:91]
	v_mfma_f32_16x16x32_bf16 v[84:87], v[156:159], v[180:183], v[84:87]
	v_mfma_f32_16x16x32_bf16 v[72:75], v[148:151], v[188:191], v[72:75]
	v_mfma_f32_16x16x32_bf16 v[68:71], v[156:159], v[188:191], v[68:71]
	v_mfma_f32_16x16x32_bf16 v[120:123], v[152:155], v[168:171], v[120:123]
	v_mfma_f32_16x16x32_bf16 v[116:119], v[160:163], v[168:171], v[116:119]
	v_mfma_f32_16x16x32_bf16 v[104:107], v[152:155], v[176:179], v[104:107]
	v_mfma_f32_16x16x32_bf16 v[100:103], v[160:163], v[176:179], v[100:103]
	v_mfma_f32_16x16x32_bf16 v[88:91], v[152:155], v[184:187], v[88:91]
	v_mfma_f32_16x16x32_bf16 v[84:87], v[160:163], v[184:187], v[84:87]
	v_mfma_f32_16x16x32_bf16 v[72:75], v[152:155], v[192:195], v[72:75]
	v_mfma_f32_16x16x32_bf16 v[68:71], v[160:163], v[192:195], v[68:71]
	s_setprio 0
	s_barrier
	s_add_i32 s12, s14, s70
	v_lshl_add_u64 v[196:197], v[196:197], 0, s[68:69]
	s_mov_b32 m0, s12
	ds_read_b128 v[164:167], v243 offset:49152
	ds_read_b128 v[168:171], v243 offset:50176
	ds_read_b128 v[172:175], v243 offset:51200
	ds_read_b128 v[176:179], v243 offset:52224
	ds_read_b128 v[180:183], v243 offset:53248
	ds_read_b128 v[184:187], v243 offset:54272
	ds_read_b128 v[188:191], v243 offset:55296
	ds_read_b128 v[192:195], v243 offset:56320
	global_load_lds_dwordx4 v[196:197], off
	s_add_i32 m0, s12, 0x2000
	s_add_u32 s12, s40, 0x40080
	v_lshl_add_u64 v[196:197], v[198:199], 0, s[68:69]
	s_addc_u32 s13, s41, 0
	s_add_i32 s14, s15, s70
	global_load_lds_dwordx4 v[196:197], off
	v_lshl_add_u64 v[196:197], s[12:13], 0, v[2:3]
	s_mov_b32 m0, s14
	s_nop 0
	global_load_lds_dwordx4 v[196:197], off
	v_lshl_add_u64 v[196:197], s[12:13], 0, v[218:219]
	s_add_i32 m0, s14, 0x2000
	s_nop 0
	global_load_lds_dwordx4 v[196:197], off
	v_lshl_add_u64 v[196:197], v[200:201], 0, s[68:69]
	s_mov_b32 m0, s85
	s_nop 0
	global_load_lds_dwordx4 v[196:197], off
	v_lshl_add_u64 v[196:197], v[202:203], 0, s[68:69]
	s_mov_b32 m0, s87
	s_nop 0
	global_load_lds_dwordx4 v[196:197], off
	s_waitcnt vmcnt(8)
	s_waitcnt lgkmcnt(0)
	s_barrier
	s_setprio 1
	v_mfma_f32_16x16x32_bf16 v[64:67], v[124:127], v[164:167], v[64:67]
	v_mfma_f32_16x16x32_bf16 v[60:63], v[136:139], v[164:167], v[60:63]
	v_mfma_f32_16x16x32_bf16 v[48:51], v[124:127], v[172:175], v[48:51]
	v_mfma_f32_16x16x32_bf16 v[44:47], v[136:139], v[172:175], v[44:47]
	v_mfma_f32_16x16x32_bf16 v[32:35], v[124:127], v[180:183], v[32:35]
	v_mfma_f32_16x16x32_bf16 v[28:31], v[136:139], v[180:183], v[28:31]
	v_mfma_f32_16x16x32_bf16 v[16:19], v[124:127], v[188:191], v[16:19]
	v_mfma_f32_16x16x32_bf16 v[12:15], v[136:139], v[188:191], v[12:15]
	v_mfma_f32_16x16x32_bf16 v[64:67], v[128:131], v[168:171], v[64:67]
	v_mfma_f32_16x16x32_bf16 v[60:63], v[144:147], v[168:171], v[60:63]
	v_mfma_f32_16x16x32_bf16 v[48:51], v[128:131], v[176:179], v[48:51]
	v_mfma_f32_16x16x32_bf16 v[44:47], v[144:147], v[176:179], v[44:47]
	v_mfma_f32_16x16x32_bf16 v[32:35], v[128:131], v[184:187], v[32:35]
	v_mfma_f32_16x16x32_bf16 v[28:31], v[144:147], v[184:187], v[28:31]
	v_mfma_f32_16x16x32_bf16 v[16:19], v[128:131], v[192:195], v[16:19]
	v_mfma_f32_16x16x32_bf16 v[12:15], v[144:147], v[192:195], v[12:15]
	s_setprio 0
	s_setprio 1
	v_mfma_f32_16x16x32_bf16 v[56:59], v[148:151], v[164:167], v[56:59]
	v_mfma_f32_16x16x32_bf16 v[52:55], v[156:159], v[164:167], v[52:55]
	v_mfma_f32_16x16x32_bf16 v[40:43], v[148:151], v[172:175], v[40:43]
	v_mfma_f32_16x16x32_bf16 v[36:39], v[156:159], v[172:175], v[36:39]
	v_mfma_f32_16x16x32_bf16 v[24:27], v[148:151], v[180:183], v[24:27]
	v_mfma_f32_16x16x32_bf16 v[20:23], v[156:159], v[180:183], v[20:23]
	v_mfma_f32_16x16x32_bf16 v[8:11], v[148:151], v[188:191], v[8:11]
	v_mfma_f32_16x16x32_bf16 v[4:7], v[156:159], v[188:191], v[4:7]
	v_mfma_f32_16x16x32_bf16 v[56:59], v[152:155], v[168:171], v[56:59]
	v_mfma_f32_16x16x32_bf16 v[52:55], v[160:163], v[168:171], v[52:55]
	v_mfma_f32_16x16x32_bf16 v[40:43], v[152:155], v[176:179], v[40:43]
	v_mfma_f32_16x16x32_bf16 v[36:39], v[160:163], v[176:179], v[36:39]
	v_mfma_f32_16x16x32_bf16 v[24:27], v[152:155], v[184:187], v[24:27]
	v_mfma_f32_16x16x32_bf16 v[20:23], v[160:163], v[184:187], v[20:23]
	v_mfma_f32_16x16x32_bf16 v[8:11], v[152:155], v[192:195], v[8:11]
	v_mfma_f32_16x16x32_bf16 v[4:7], v[160:163], v[192:195], v[4:7]
	s_setprio 0
	s_barrier
	s_add_i32 s11, s11, 2
	s_add_u32 s9, s9, 0x100
	s_addc_u32 s10, s10, 0
	s_add_u32 s38, s38, 0x100
	s_addc_u32 s39, s39, 0
	s_cmp_gt_u32 s11, 13
.LBB0_947:
	s_add_u32 s12, s38, 0xfffc0080
	s_addc_u32 s13, s39, -1
	s_add_i32 s14, 0, 0x10000
	s_cmp_eq_u32 s11, 12
	s_cselect_b32 s57, s5, s13
	s_cselect_b32 s56, s6, s12
	s_cselect_b32 s41, s7, s10
	s_cselect_b32 s40, s8, s9
	s_add_i32 s15, 0, 0x14000
	v_add_u32_e32 v144, s14, v230
	v_add_u32_e32 v160, s15, v230
	ds_read_b128 v[124:127], v144
	ds_read_b128 v[128:131], v144 offset:1024
	ds_read_b128 v[136:139], v144 offset:2048
	ds_read_b128 v[144:147], v144 offset:3072
	ds_read_b128 v[148:151], v160
	ds_read_b128 v[152:155], v160 offset:1024
	ds_read_b128 v[156:159], v160 offset:2048
	ds_read_b128 v[160:163], v160 offset:3072
	v_lshl_add_u64 v[196:197], s[38:39], 0, v[222:223]
	s_add_i32 m0, s71, 0xc000
	ds_read_b128 v[164:167], v243
	ds_read_b128 v[168:171], v243 offset:1024
	ds_read_b128 v[172:175], v243 offset:2048
	ds_read_b128 v[176:179], v243 offset:3072
	ds_read_b128 v[180:183], v243 offset:4096
	ds_read_b128 v[184:187], v243 offset:5120
	ds_read_b128 v[188:191], v243 offset:6144
	ds_read_b128 v[192:195], v243 offset:7168
	global_load_lds_dwordx4 v[196:197], off
	v_lshl_add_u64 v[196:197], s[38:39], 0, v[220:221]
	s_add_i32 m0, s71, 0xe000
	s_nop 0
	global_load_lds_dwordx4 v[196:197], off
	s_waitcnt vmcnt(8)
	s_waitcnt lgkmcnt(0)
	s_barrier
	s_setprio 1
	v_mfma_f32_16x16x32_bf16 v[140:143], v[124:127], v[164:167], v[140:143]
	v_mfma_f32_16x16x32_bf16 v[132:135], v[136:139], v[164:167], v[132:135]
	v_mfma_f32_16x16x32_bf16 v[112:115], v[124:127], v[172:175], v[112:115]
	v_mfma_f32_16x16x32_bf16 v[108:111], v[136:139], v[172:175], v[108:111]
	v_mfma_f32_16x16x32_bf16 v[96:99], v[124:127], v[180:183], v[96:99]
	v_mfma_f32_16x16x32_bf16 v[92:95], v[136:139], v[180:183], v[92:95]
	v_mfma_f32_16x16x32_bf16 v[80:83], v[124:127], v[188:191], v[80:83]
	v_mfma_f32_16x16x32_bf16 v[76:79], v[136:139], v[188:191], v[76:79]
	v_mfma_f32_16x16x32_bf16 v[140:143], v[128:131], v[168:171], v[140:143]
	v_mfma_f32_16x16x32_bf16 v[132:135], v[144:147], v[168:171], v[132:135]
	v_mfma_f32_16x16x32_bf16 v[112:115], v[128:131], v[176:179], v[112:115]
	v_mfma_f32_16x16x32_bf16 v[108:111], v[144:147], v[176:179], v[108:111]
	v_mfma_f32_16x16x32_bf16 v[96:99], v[128:131], v[184:187], v[96:99]
	v_mfma_f32_16x16x32_bf16 v[92:95], v[144:147], v[184:187], v[92:95]
	v_mfma_f32_16x16x32_bf16 v[80:83], v[128:131], v[192:195], v[80:83]
	v_mfma_f32_16x16x32_bf16 v[76:79], v[144:147], v[192:195], v[76:79]
	s_setprio 0
	s_setprio 1
	v_mfma_f32_16x16x32_bf16 v[120:123], v[148:151], v[164:167], v[120:123]
	v_mfma_f32_16x16x32_bf16 v[116:119], v[156:159], v[164:167], v[116:119]
	v_mfma_f32_16x16x32_bf16 v[104:107], v[148:151], v[172:175], v[104:107]
	v_mfma_f32_16x16x32_bf16 v[100:103], v[156:159], v[172:175], v[100:103]
	v_mfma_f32_16x16x32_bf16 v[88:91], v[148:151], v[180:183], v[88:91]
	v_mfma_f32_16x16x32_bf16 v[84:87], v[156:159], v[180:183], v[84:87]
	v_mfma_f32_16x16x32_bf16 v[72:75], v[148:151], v[188:191], v[72:75]
	v_mfma_f32_16x16x32_bf16 v[68:71], v[156:159], v[188:191], v[68:71]
	v_mfma_f32_16x16x32_bf16 v[120:123], v[152:155], v[168:171], v[120:123]
	v_mfma_f32_16x16x32_bf16 v[116:119], v[160:163], v[168:171], v[116:119]
	v_mfma_f32_16x16x32_bf16 v[104:107], v[152:155], v[176:179], v[104:107]
	v_mfma_f32_16x16x32_bf16 v[100:103], v[160:163], v[176:179], v[100:103]
	v_mfma_f32_16x16x32_bf16 v[88:91], v[152:155], v[184:187], v[88:91]
	v_mfma_f32_16x16x32_bf16 v[84:87], v[160:163], v[184:187], v[84:87]
	v_mfma_f32_16x16x32_bf16 v[72:75], v[152:155], v[192:195], v[72:75]
	v_mfma_f32_16x16x32_bf16 v[68:71], v[160:163], v[192:195], v[68:71]
	s_setprio 0
	s_barrier
	s_add_i32 s12, s14, s70
	v_lshl_add_u64 v[196:197], s[40:41], 0, v[2:3]
	s_mov_b32 m0, s12
	ds_read_b128 v[164:167], v243 offset:16384
	ds_read_b128 v[168:171], v243 offset:17408
	ds_read_b128 v[172:175], v243 offset:18432
	ds_read_b128 v[176:179], v243 offset:19456
	ds_read_b128 v[180:183], v243 offset:20480
	ds_read_b128 v[184:187], v243 offset:21504
	ds_read_b128 v[188:191], v243 offset:22528
	ds_read_b128 v[192:195], v243 offset:23552
	global_load_lds_dwordx4 v[196:197], off
	s_add_i32 m0, s12, 0x2000
	s_add_u32 s12, s40, 0x40000
	v_lshl_add_u64 v[198:199], s[40:41], 0, v[218:219]
	s_addc_u32 s13, s41, 0
	s_add_i32 s14, s15, s70
	global_load_lds_dwordx4 v[198:199], off
	v_lshl_add_u64 v[200:201], s[12:13], 0, v[2:3]
	s_mov_b32 m0, s14
	v_lshl_add_u64 v[202:203], s[56:57], 0, v[216:217]
	global_load_lds_dwordx4 v[200:201], off
	v_lshl_add_u64 v[200:201], s[12:13], 0, v[218:219]
	s_add_i32 m0, s14, 0x2000
	s_nop 0
	global_load_lds_dwordx4 v[200:201], off
	v_lshl_add_u64 v[200:201], s[56:57], 0, v[0:1]
	s_mov_b32 m0, s71
	s_nop 0
	global_load_lds_dwordx4 v[200:201], off
	s_mov_b32 m0, s80
	s_nop 0
	global_load_lds_dwordx4 v[202:203], off
	s_waitcnt vmcnt(8)
	s_waitcnt lgkmcnt(0)
	s_barrier
	s_setprio 1
	v_mfma_f32_16x16x32_bf16 v[64:67], v[124:127], v[164:167], v[64:67]
	v_mfma_f32_16x16x32_bf16 v[60:63], v[136:139], v[164:167], v[60:63]
	v_mfma_f32_16x16x32_bf16 v[48:51], v[124:127], v[172:175], v[48:51]
	v_mfma_f32_16x16x32_bf16 v[44:47], v[136:139], v[172:175], v[44:47]
	v_mfma_f32_16x16x32_bf16 v[32:35], v[124:127], v[180:183], v[32:35]
	v_mfma_f32_16x16x32_bf16 v[28:31], v[136:139], v[180:183], v[28:31]
	v_mfma_f32_16x16x32_bf16 v[16:19], v[124:127], v[188:191], v[16:19]
	v_mfma_f32_16x16x32_bf16 v[12:15], v[136:139], v[188:191], v[12:15]
	v_mfma_f32_16x16x32_bf16 v[64:67], v[128:131], v[168:171], v[64:67]
	v_mfma_f32_16x16x32_bf16 v[60:63], v[144:147], v[168:171], v[60:63]
	v_mfma_f32_16x16x32_bf16 v[48:51], v[128:131], v[176:179], v[48:51]
	v_mfma_f32_16x16x32_bf16 v[44:47], v[144:147], v[176:179], v[44:47]
	v_mfma_f32_16x16x32_bf16 v[32:35], v[128:131], v[184:187], v[32:35]
	v_mfma_f32_16x16x32_bf16 v[28:31], v[144:147], v[184:187], v[28:31]
	v_mfma_f32_16x16x32_bf16 v[16:19], v[128:131], v[192:195], v[16:19]
	v_mfma_f32_16x16x32_bf16 v[12:15], v[144:147], v[192:195], v[12:15]
	s_setprio 0
	s_setprio 1
	v_mfma_f32_16x16x32_bf16 v[56:59], v[148:151], v[164:167], v[56:59]
	v_mfma_f32_16x16x32_bf16 v[52:55], v[156:159], v[164:167], v[52:55]
	v_mfma_f32_16x16x32_bf16 v[40:43], v[148:151], v[172:175], v[40:43]
	v_mfma_f32_16x16x32_bf16 v[36:39], v[156:159], v[172:175], v[36:39]
	v_mfma_f32_16x16x32_bf16 v[24:27], v[148:151], v[180:183], v[24:27]
	v_mfma_f32_16x16x32_bf16 v[20:23], v[156:159], v[180:183], v[20:23]
	v_mfma_f32_16x16x32_bf16 v[8:11], v[148:151], v[188:191], v[8:11]
	v_mfma_f32_16x16x32_bf16 v[4:7], v[156:159], v[188:191], v[4:7]
	v_mfma_f32_16x16x32_bf16 v[56:59], v[152:155], v[168:171], v[56:59]
	v_mfma_f32_16x16x32_bf16 v[52:55], v[160:163], v[168:171], v[52:55]
	v_mfma_f32_16x16x32_bf16 v[40:43], v[152:155], v[176:179], v[40:43]
	v_mfma_f32_16x16x32_bf16 v[36:39], v[160:163], v[176:179], v[36:39]
	v_mfma_f32_16x16x32_bf16 v[24:27], v[152:155], v[184:187], v[24:27]
	v_mfma_f32_16x16x32_bf16 v[20:23], v[160:163], v[184:187], v[20:23]
	v_mfma_f32_16x16x32_bf16 v[8:11], v[152:155], v[192:195], v[8:11]
	v_mfma_f32_16x16x32_bf16 v[4:7], v[160:163], v[192:195], v[4:7]
	s_setprio 0
	s_barrier
	s_add_i32 s14, 0, 0x18000
	s_add_i32 s15, 0, 0x1c000
	v_add_u32_e32 v144, s14, v230
	v_add_u32_e32 v160, s15, v230
	ds_read_b128 v[124:127], v144
	ds_read_b128 v[128:131], v144 offset:1024
	ds_read_b128 v[136:139], v144 offset:2048
	ds_read_b128 v[144:147], v144 offset:3072
	ds_read_b128 v[148:151], v160
	ds_read_b128 v[152:155], v160 offset:1024
	ds_read_b128 v[156:159], v160 offset:2048
	ds_read_b128 v[160:163], v160 offset:3072
	s_add_u32 s12, s56, 0x40000
	s_addc_u32 s13, s57, 0
	s_mov_b32 m0, s81
	v_lshl_add_u64 v[204:205], s[12:13], 0, v[0:1]
	ds_read_b128 v[164:167], v243 offset:32768
	ds_read_b128 v[168:171], v243 offset:33792
	ds_read_b128 v[172:175], v243 offset:34816
	ds_read_b128 v[176:179], v243 offset:35840
	ds_read_b128 v[180:183], v243 offset:36864
	ds_read_b128 v[184:187], v243 offset:37888
	ds_read_b128 v[188:191], v243 offset:38912
	ds_read_b128 v[192:195], v243 offset:39936
	global_load_lds_dwordx4 v[204:205], off
	v_lshl_add_u64 v[204:205], s[12:13], 0, v[216:217]
	s_mov_b32 m0, s82
	s_nop 0
	global_load_lds_dwordx4 v[204:205], off
	s_waitcnt vmcnt(8)
	s_waitcnt lgkmcnt(0)
	s_barrier
	s_setprio 1
	v_mfma_f32_16x16x32_bf16 v[140:143], v[124:127], v[164:167], v[140:143]
	v_mfma_f32_16x16x32_bf16 v[132:135], v[136:139], v[164:167], v[132:135]
	v_mfma_f32_16x16x32_bf16 v[112:115], v[124:127], v[172:175], v[112:115]
	v_mfma_f32_16x16x32_bf16 v[108:111], v[136:139], v[172:175], v[108:111]
	v_mfma_f32_16x16x32_bf16 v[96:99], v[124:127], v[180:183], v[96:99]
	v_mfma_f32_16x16x32_bf16 v[92:95], v[136:139], v[180:183], v[92:95]
	v_mfma_f32_16x16x32_bf16 v[80:83], v[124:127], v[188:191], v[80:83]
	v_mfma_f32_16x16x32_bf16 v[76:79], v[136:139], v[188:191], v[76:79]
	v_mfma_f32_16x16x32_bf16 v[140:143], v[128:131], v[168:171], v[140:143]
	v_mfma_f32_16x16x32_bf16 v[132:135], v[144:147], v[168:171], v[132:135]
	v_mfma_f32_16x16x32_bf16 v[112:115], v[128:131], v[176:179], v[112:115]
	v_mfma_f32_16x16x32_bf16 v[108:111], v[144:147], v[176:179], v[108:111]
	v_mfma_f32_16x16x32_bf16 v[96:99], v[128:131], v[184:187], v[96:99]
	v_mfma_f32_16x16x32_bf16 v[92:95], v[144:147], v[184:187], v[92:95]
	v_mfma_f32_16x16x32_bf16 v[80:83], v[128:131], v[192:195], v[80:83]
	v_mfma_f32_16x16x32_bf16 v[76:79], v[144:147], v[192:195], v[76:79]
	s_setprio 0
	s_setprio 1
	v_mfma_f32_16x16x32_bf16 v[120:123], v[148:151], v[164:167], v[120:123]
	v_mfma_f32_16x16x32_bf16 v[116:119], v[156:159], v[164:167], v[116:119]
	v_mfma_f32_16x16x32_bf16 v[104:107], v[148:151], v[172:175], v[104:107]
	v_mfma_f32_16x16x32_bf16 v[100:103], v[156:159], v[172:175], v[100:103]
	v_mfma_f32_16x16x32_bf16 v[88:91], v[148:151], v[180:183], v[88:91]
	v_mfma_f32_16x16x32_bf16 v[84:87], v[156:159], v[180:183], v[84:87]
	v_mfma_f32_16x16x32_bf16 v[72:75], v[148:151], v[188:191], v[72:75]
	v_mfma_f32_16x16x32_bf16 v[68:71], v[156:159], v[188:191], v[68:71]
	v_mfma_f32_16x16x32_bf16 v[120:123], v[152:155], v[168:171], v[120:123]
	v_mfma_f32_16x16x32_bf16 v[116:119], v[160:163], v[168:171], v[116:119]
	v_mfma_f32_16x16x32_bf16 v[104:107], v[152:155], v[176:179], v[104:107]
	v_mfma_f32_16x16x32_bf16 v[100:103], v[160:163], v[176:179], v[100:103]
	v_mfma_f32_16x16x32_bf16 v[88:91], v[152:155], v[184:187], v[88:91]
	v_mfma_f32_16x16x32_bf16 v[84:87], v[160:163], v[184:187], v[84:87]
	v_mfma_f32_16x16x32_bf16 v[72:75], v[152:155], v[192:195], v[72:75]
	v_mfma_f32_16x16x32_bf16 v[68:71], v[160:163], v[192:195], v[68:71]
	s_setprio 0
	s_barrier
	s_add_i32 s12, s14, s70
	v_lshl_add_u64 v[196:197], v[196:197], 0, s[68:69]
	s_mov_b32 m0, s12
	ds_read_b128 v[164:167], v243 offset:49152
	ds_read_b128 v[168:171], v243 offset:50176
	ds_read_b128 v[172:175], v243 offset:51200
	ds_read_b128 v[176:179], v243 offset:52224
	ds_read_b128 v[180:183], v243 offset:53248
	ds_read_b128 v[184:187], v243 offset:54272
	ds_read_b128 v[188:191], v243 offset:55296
	ds_read_b128 v[192:195], v243 offset:56320
	global_load_lds_dwordx4 v[196:197], off
	s_add_i32 m0, s12, 0x2000
	s_add_u32 s12, s40, 0x40080
	v_lshl_add_u64 v[196:197], v[198:199], 0, s[68:69]
	s_addc_u32 s13, s41, 0
	s_add_i32 s14, s15, s70
	global_load_lds_dwordx4 v[196:197], off
	v_lshl_add_u64 v[196:197], s[12:13], 0, v[2:3]
	s_mov_b32 m0, s14
	s_nop 0
	global_load_lds_dwordx4 v[196:197], off
	v_lshl_add_u64 v[196:197], s[12:13], 0, v[218:219]
	s_add_i32 m0, s14, 0x2000
	s_nop 0
	global_load_lds_dwordx4 v[196:197], off
	v_lshl_add_u64 v[196:197], v[200:201], 0, s[68:69]
	s_mov_b32 m0, s85
	s_nop 0
	global_load_lds_dwordx4 v[196:197], off
	v_lshl_add_u64 v[196:197], v[202:203], 0, s[68:69]
	s_mov_b32 m0, s87
	s_nop 0
	global_load_lds_dwordx4 v[196:197], off
	s_waitcnt vmcnt(8)
	s_waitcnt lgkmcnt(0)
	s_barrier
	s_setprio 1
	v_mfma_f32_16x16x32_bf16 v[64:67], v[124:127], v[164:167], v[64:67]
	v_mfma_f32_16x16x32_bf16 v[60:63], v[136:139], v[164:167], v[60:63]
	v_mfma_f32_16x16x32_bf16 v[48:51], v[124:127], v[172:175], v[48:51]
	v_mfma_f32_16x16x32_bf16 v[44:47], v[136:139], v[172:175], v[44:47]
	v_mfma_f32_16x16x32_bf16 v[32:35], v[124:127], v[180:183], v[32:35]
	v_mfma_f32_16x16x32_bf16 v[28:31], v[136:139], v[180:183], v[28:31]
	v_mfma_f32_16x16x32_bf16 v[16:19], v[124:127], v[188:191], v[16:19]
	v_mfma_f32_16x16x32_bf16 v[12:15], v[136:139], v[188:191], v[12:15]
	v_mfma_f32_16x16x32_bf16 v[64:67], v[128:131], v[168:171], v[64:67]
	v_mfma_f32_16x16x32_bf16 v[60:63], v[144:147], v[168:171], v[60:63]
	v_mfma_f32_16x16x32_bf16 v[48:51], v[128:131], v[176:179], v[48:51]
	v_mfma_f32_16x16x32_bf16 v[44:47], v[144:147], v[176:179], v[44:47]
	v_mfma_f32_16x16x32_bf16 v[32:35], v[128:131], v[184:187], v[32:35]
	v_mfma_f32_16x16x32_bf16 v[28:31], v[144:147], v[184:187], v[28:31]
	v_mfma_f32_16x16x32_bf16 v[16:19], v[128:131], v[192:195], v[16:19]
	v_mfma_f32_16x16x32_bf16 v[12:15], v[144:147], v[192:195], v[12:15]
	s_setprio 0
	s_setprio 1
	v_mfma_f32_16x16x32_bf16 v[56:59], v[148:151], v[164:167], v[56:59]
	v_mfma_f32_16x16x32_bf16 v[52:55], v[156:159], v[164:167], v[52:55]
	v_mfma_f32_16x16x32_bf16 v[40:43], v[148:151], v[172:175], v[40:43]
	v_mfma_f32_16x16x32_bf16 v[36:39], v[156:159], v[172:175], v[36:39]
	v_mfma_f32_16x16x32_bf16 v[24:27], v[148:151], v[180:183], v[24:27]
	v_mfma_f32_16x16x32_bf16 v[20:23], v[156:159], v[180:183], v[20:23]
	v_mfma_f32_16x16x32_bf16 v[8:11], v[148:151], v[188:191], v[8:11]
	v_mfma_f32_16x16x32_bf16 v[4:7], v[156:159], v[188:191], v[4:7]
	v_mfma_f32_16x16x32_bf16 v[56:59], v[152:155], v[168:171], v[56:59]
	v_mfma_f32_16x16x32_bf16 v[52:55], v[160:163], v[168:171], v[52:55]
	v_mfma_f32_16x16x32_bf16 v[40:43], v[152:155], v[176:179], v[40:43]
	v_mfma_f32_16x16x32_bf16 v[36:39], v[160:163], v[176:179], v[36:39]
	v_mfma_f32_16x16x32_bf16 v[24:27], v[152:155], v[184:187], v[24:27]
	v_mfma_f32_16x16x32_bf16 v[20:23], v[160:163], v[184:187], v[20:23]
	v_mfma_f32_16x16x32_bf16 v[8:11], v[152:155], v[192:195], v[8:11]
	v_mfma_f32_16x16x32_bf16 v[4:7], v[160:163], v[192:195], v[4:7]
	s_setprio 0
	s_barrier
	s_add_i32 s11, s11, 2
	s_add_u32 s9, s9, 0x100
	s_addc_u32 s10, s10, 0
	s_add_u32 s38, s38, 0x100
	s_addc_u32 s39, s39, 0
	s_cmp_gt_u32 s11, 13
	s_cbranch_scc0 .LBB0_947
	s_and_b64 vcc, exec, s[46:47]
	s_cbranch_vccz .LBB0_950
	s_barrier

.Lgu_skip1_p:
	s_waitcnt lgkmcnt(0)
	s_barrier
	s_setprio 1
	v_mfma_f32_16x16x32_bf16 v[124:127], v[142:145], v[184:187], 0
	v_mfma_f32_16x16x32_bf16 v[120:123], v[150:153], v[184:187], 0
	v_mfma_f32_16x16x32_bf16 v[112:115], v[142:145], v[192:195], 0
	v_mfma_f32_16x16x32_bf16 v[104:107], v[150:153], v[192:195], 0
	v_mfma_f32_16x16x32_bf16 v[96:99], v[142:145], v[200:203], 0
	v_mfma_f32_16x16x32_bf16 v[88:91], v[150:153], v[200:203], 0
	v_mfma_f32_16x16x32_bf16 v[80:83], v[142:145], v[208:211], 0
	v_mfma_f32_16x16x32_bf16 v[72:75], v[150:153], v[208:211], 0
	v_mfma_f32_16x16x32_bf16 v[124:127], v[146:149], v[188:191], v[124:127]
	v_mfma_f32_16x16x32_bf16 v[120:123], v[154:157], v[188:191], v[120:123]
	v_mfma_f32_16x16x32_bf16 v[112:115], v[146:149], v[196:199], v[112:115]
	v_mfma_f32_16x16x32_bf16 v[104:107], v[154:157], v[196:199], v[104:107]
	v_mfma_f32_16x16x32_bf16 v[96:99], v[146:149], v[204:207], v[96:99]
	v_mfma_f32_16x16x32_bf16 v[88:91], v[154:157], v[204:207], v[88:91]
	v_mfma_f32_16x16x32_bf16 v[80:83], v[146:149], v[212:215], v[80:83]
	v_mfma_f32_16x16x32_bf16 v[72:75], v[154:157], v[212:215], v[72:75]
	v_mfma_f32_16x16x32_bf16 v[128:131], v[168:171], v[184:187], 0
	v_mfma_f32_16x16x32_bf16 v[116:119], v[176:179], v[184:187], 0
	v_mfma_f32_16x16x32_bf16 v[108:111], v[168:171], v[192:195], 0
	v_mfma_f32_16x16x32_bf16 v[100:103], v[176:179], v[192:195], 0
	v_mfma_f32_16x16x32_bf16 v[92:95], v[168:171], v[200:203], 0
	v_mfma_f32_16x16x32_bf16 v[84:87], v[176:179], v[200:203], 0
	v_mfma_f32_16x16x32_bf16 v[76:79], v[168:171], v[208:211], 0
	v_mfma_f32_16x16x32_bf16 v[68:71], v[176:179], v[208:211], 0
	v_mfma_f32_16x16x32_bf16 v[128:131], v[172:175], v[188:191], v[128:131]
	v_mfma_f32_16x16x32_bf16 v[116:119], v[180:183], v[188:191], v[116:119]
	v_mfma_f32_16x16x32_bf16 v[108:111], v[172:175], v[196:199], v[108:111]
	v_mfma_f32_16x16x32_bf16 v[100:103], v[180:183], v[196:199], v[100:103]
	v_mfma_f32_16x16x32_bf16 v[92:95], v[172:175], v[204:207], v[92:95]
	v_mfma_f32_16x16x32_bf16 v[84:87], v[180:183], v[204:207], v[84:87]
	v_mfma_f32_16x16x32_bf16 v[76:79], v[172:175], v[212:215], v[76:79]
	v_mfma_f32_16x16x32_bf16 v[68:71], v[180:183], v[212:215], v[68:71]
	s_setprio 0
	s_barrier
	s_add_i32 s12, s14, s56
	s_mov_b32 m0, s12
	ds_read_b128 v[184:187], v167 offset:16384
	ds_read_b128 v[188:191], v167 offset:17408
	ds_read_b128 v[192:195], v167 offset:18432
	ds_read_b128 v[196:199], v167 offset:19456
	ds_read_b128 v[200:203], v167 offset:20480
	ds_read_b128 v[204:207], v167 offset:21504
	ds_read_b128 v[208:211], v167 offset:22528
	ds_read_b128 v[212:215], v167 offset:23552
	global_load_lds_dwordx4 v2, s[46:47]
	s_add_i32 m0, s12, 0x2000
	s_add_u32 s12, s46, 0x80000
	s_addc_u32 s13, s47, 0
	s_add_i32 s14, s15, s56
	global_load_lds_dwordx4 v0, s[46:47]
	s_mov_b32 m0, s14
	s_nop 0
	global_load_lds_dwordx4 v2, s[12:13]
	s_add_i32 m0, s14, 0x2000
	s_nop 0
	global_load_lds_dwordx4 v0, s[12:13]
	s_mov_b32 m0, s60
	s_nop 0
	global_load_lds_dwordx4 v134, s[48:49]
	s_mov_b32 m0, s61
	s_nop 0
	global_load_lds_dwordx4 v132, s[48:49]
	s_cmp_lg_u32 s32, 0
	s_cbranch_scc1 .Lgu_skip2_p
	s_waitcnt vmcnt(8)
.Lgu_skip2_p:
	s_mov_b32 s32, 0
	s_waitcnt lgkmcnt(0)
	s_barrier
	s_setprio 1
	v_mfma_f32_16x16x32_bf16 v[64:67], v[142:145], v[184:187], 0
	v_mfma_f32_16x16x32_bf16 v[56:59], v[150:153], v[184:187], 0
	v_mfma_f32_16x16x32_bf16 v[48:51], v[142:145], v[192:195], 0
	v_mfma_f32_16x16x32_bf16 v[40:43], v[150:153], v[192:195], 0
	v_mfma_f32_16x16x32_bf16 v[32:35], v[142:145], v[200:203], 0
	v_mfma_f32_16x16x32_bf16 v[24:27], v[150:153], v[200:203], 0
	v_mfma_f32_16x16x32_bf16 v[16:19], v[142:145], v[208:211], 0
	v_mfma_f32_16x16x32_bf16 v[8:11], v[150:153], v[208:211], 0
	v_mfma_f32_16x16x32_bf16 v[64:67], v[146:149], v[188:191], v[64:67]
	v_mfma_f32_16x16x32_bf16 v[56:59], v[154:157], v[188:191], v[56:59]
	v_mfma_f32_16x16x32_bf16 v[48:51], v[146:149], v[196:199], v[48:51]
	v_mfma_f32_16x16x32_bf16 v[40:43], v[154:157], v[196:199], v[40:43]
	v_mfma_f32_16x16x32_bf16 v[32:35], v[146:149], v[204:207], v[32:35]
	v_mfma_f32_16x16x32_bf16 v[24:27], v[154:157], v[204:207], v[24:27]
	v_mfma_f32_16x16x32_bf16 v[16:19], v[146:149], v[212:215], v[16:19]
	v_mfma_f32_16x16x32_bf16 v[8:11], v[154:157], v[212:215], v[8:11]
	v_mfma_f32_16x16x32_bf16 v[60:63], v[168:171], v[184:187], 0
	v_mfma_f32_16x16x32_bf16 v[52:55], v[176:179], v[184:187], 0
	v_mfma_f32_16x16x32_bf16 v[44:47], v[168:171], v[192:195], 0
	v_mfma_f32_16x16x32_bf16 v[36:39], v[176:179], v[192:195], 0
	v_mfma_f32_16x16x32_bf16 v[28:31], v[168:171], v[200:203], 0
	v_mfma_f32_16x16x32_bf16 v[20:23], v[176:179], v[200:203], 0
	v_mfma_f32_16x16x32_bf16 v[12:15], v[168:171], v[208:211], 0
	v_mfma_f32_16x16x32_bf16 v[4:7], v[176:179], v[208:211], 0
	v_mfma_f32_16x16x32_bf16 v[60:63], v[172:175], v[188:191], v[60:63]
	v_mfma_f32_16x16x32_bf16 v[52:55], v[180:183], v[188:191], v[52:55]
	v_mfma_f32_16x16x32_bf16 v[44:47], v[172:175], v[196:199], v[44:47]
	v_mfma_f32_16x16x32_bf16 v[36:39], v[180:183], v[196:199], v[36:39]
	v_mfma_f32_16x16x32_bf16 v[28:31], v[172:175], v[204:207], v[28:31]
	v_mfma_f32_16x16x32_bf16 v[20:23], v[180:183], v[204:207], v[20:23]
	v_mfma_f32_16x16x32_bf16 v[12:15], v[172:175], v[212:215], v[12:15]
	v_mfma_f32_16x16x32_bf16 v[4:7], v[180:183], v[212:215], v[4:7]
	s_setprio 0
	s_barrier
	s_add_i32 s14, 0, 0x18000
	s_add_i32 s15, 0, 0x1c000
	v_add_u32_e32 v154, s14, v163
	v_add_u32_e32 v160, s15, v163
	ds_read_b128 v[142:145], v154
	ds_read_b128 v[146:149], v154 offset:1024
	ds_read_b128 v[150:153], v154 offset:2048
	ds_read_b128 v[154:157], v154 offset:3072
	ds_read_b128 v[168:171], v160
	ds_read_b128 v[172:175], v160 offset:1024
	ds_read_b128 v[176:179], v160 offset:2048
	ds_read_b128 v[180:183], v160 offset:3072
	s_add_u32 s12, s48, 0x80000
	s_addc_u32 s13, s49, 0
	s_mov_b32 m0, s62
	ds_read_b128 v[184:187], v167 offset:32768
	ds_read_b128 v[188:191], v167 offset:33792
	ds_read_b128 v[192:195], v167 offset:34816
	ds_read_b128 v[196:199], v167 offset:35840
	ds_read_b128 v[200:203], v167 offset:36864
	ds_read_b128 v[204:207], v167 offset:37888
	ds_read_b128 v[208:211], v167 offset:38912
	ds_read_b128 v[212:215], v167 offset:39936
	global_load_lds_dwordx4 v134, s[12:13]
	s_mov_b32 m0, s63
	s_nop 0
	global_load_lds_dwordx4 v132, s[12:13]
	s_waitcnt vmcnt(8)
	s_waitcnt lgkmcnt(0)
	s_barrier
	s_setprio 1
	v_mfma_f32_16x16x32_bf16 v[124:127], v[142:145], v[184:187], v[124:127]
	v_mfma_f32_16x16x32_bf16 v[120:123], v[150:153], v[184:187], v[120:123]
	v_mfma_f32_16x16x32_bf16 v[112:115], v[142:145], v[192:195], v[112:115]
	v_mfma_f32_16x16x32_bf16 v[104:107], v[150:153], v[192:195], v[104:107]
	v_mfma_f32_16x16x32_bf16 v[96:99], v[142:145], v[200:203], v[96:99]
	v_mfma_f32_16x16x32_bf16 v[88:91], v[150:153], v[200:203], v[88:91]
	v_mfma_f32_16x16x32_bf16 v[80:83], v[142:145], v[208:211], v[80:83]
	v_mfma_f32_16x16x32_bf16 v[72:75], v[150:153], v[208:211], v[72:75]
	v_mfma_f32_16x16x32_bf16 v[124:127], v[146:149], v[188:191], v[124:127]
	v_mfma_f32_16x16x32_bf16 v[120:123], v[154:157], v[188:191], v[120:123]
	v_mfma_f32_16x16x32_bf16 v[112:115], v[146:149], v[196:199], v[112:115]
	v_mfma_f32_16x16x32_bf16 v[104:107], v[154:157], v[196:199], v[104:107]
	v_mfma_f32_16x16x32_bf16 v[96:99], v[146:149], v[204:207], v[96:99]
	v_mfma_f32_16x16x32_bf16 v[88:91], v[154:157], v[204:207], v[88:91]
	v_mfma_f32_16x16x32_bf16 v[80:83], v[146:149], v[212:215], v[80:83]
	v_mfma_f32_16x16x32_bf16 v[72:75], v[154:157], v[212:215], v[72:75]
	v_mfma_f32_16x16x32_bf16 v[128:131], v[168:171], v[184:187], v[128:131]
	v_mfma_f32_16x16x32_bf16 v[116:119], v[176:179], v[184:187], v[116:119]
	v_mfma_f32_16x16x32_bf16 v[108:111], v[168:171], v[192:195], v[108:111]
	v_mfma_f32_16x16x32_bf16 v[100:103], v[176:179], v[192:195], v[100:103]
	v_mfma_f32_16x16x32_bf16 v[92:95], v[168:171], v[200:203], v[92:95]
	v_mfma_f32_16x16x32_bf16 v[84:87], v[176:179], v[200:203], v[84:87]
	v_mfma_f32_16x16x32_bf16 v[76:79], v[168:171], v[208:211], v[76:79]
	v_mfma_f32_16x16x32_bf16 v[68:71], v[176:179], v[208:211], v[68:71]
	v_mfma_f32_16x16x32_bf16 v[128:131], v[172:175], v[188:191], v[128:131]
	v_mfma_f32_16x16x32_bf16 v[116:119], v[180:183], v[188:191], v[116:119]
	v_mfma_f32_16x16x32_bf16 v[108:111], v[172:175], v[196:199], v[108:111]
	v_mfma_f32_16x16x32_bf16 v[100:103], v[180:183], v[196:199], v[100:103]
	v_mfma_f32_16x16x32_bf16 v[92:95], v[172:175], v[204:207], v[92:95]
	v_mfma_f32_16x16x32_bf16 v[84:87], v[180:183], v[204:207], v[84:87]
	v_mfma_f32_16x16x32_bf16 v[76:79], v[172:175], v[212:215], v[76:79]
	v_mfma_f32_16x16x32_bf16 v[68:71], v[180:183], v[212:215], v[68:71]
	s_setprio 0
	s_barrier
	s_add_i32 s12, s14, s56
	s_mov_b32 m0, s12
	ds_read_b128 v[184:187], v167 offset:49152
	ds_read_b128 v[188:191], v167 offset:50176
	ds_read_b128 v[192:195], v167 offset:51200
	ds_read_b128 v[196:199], v167 offset:52224
	ds_read_b128 v[200:203], v167 offset:53248
	ds_read_b128 v[204:207], v167 offset:54272
	ds_read_b128 v[208:211], v167 offset:55296
	ds_read_b128 v[212:215], v167 offset:56320
	s_add_u32 s100, s46, 0x80
	s_addc_u32 s101, s47, 0
	global_load_lds_dwordx4 v2, s[100:101]
	s_add_i32 m0, s12, 0x2000
	s_add_u32 s12, s46, 0x80080
	s_addc_u32 s13, s47, 0
	s_add_i32 s14, s15, s56
	s_add_u32 s100, s46, 0x80
	s_addc_u32 s101, s47, 0
	global_load_lds_dwordx4 v0, s[100:101]
	s_mov_b32 m0, s14
	s_nop 0
	global_load_lds_dwordx4 v2, s[12:13]
	s_add_i32 m0, s14, 0x2000
	s_nop 0
	global_load_lds_dwordx4 v0, s[12:13]
	s_mov_b32 m0, s64
	s_nop 0
	s_add_u32 s100, s48, 0x80
	s_addc_u32 s101, s49, 0
	global_load_lds_dwordx4 v134, s[100:101]
	s_mov_b32 m0, s65
	s_nop 0
	s_add_u32 s100, s48, 0x80
	s_addc_u32 s101, s49, 0
	global_load_lds_dwordx4 v132, s[100:101]
	s_waitcnt vmcnt(8)
	s_waitcnt lgkmcnt(0)
	s_barrier
	s_setprio 1
	v_mfma_f32_16x16x32_bf16 v[64:67], v[142:145], v[184:187], v[64:67]
	v_mfma_f32_16x16x32_bf16 v[56:59], v[150:153], v[184:187], v[56:59]
	v_mfma_f32_16x16x32_bf16 v[48:51], v[142:145], v[192:195], v[48:51]
	v_mfma_f32_16x16x32_bf16 v[40:43], v[150:153], v[192:195], v[40:43]
	v_mfma_f32_16x16x32_bf16 v[32:35], v[142:145], v[200:203], v[32:35]
	v_mfma_f32_16x16x32_bf16 v[24:27], v[150:153], v[200:203], v[24:27]
	v_mfma_f32_16x16x32_bf16 v[16:19], v[142:145], v[208:211], v[16:19]
	v_mfma_f32_16x16x32_bf16 v[8:11], v[150:153], v[208:211], v[8:11]
	v_mfma_f32_16x16x32_bf16 v[64:67], v[146:149], v[188:191], v[64:67]
	v_mfma_f32_16x16x32_bf16 v[56:59], v[154:157], v[188:191], v[56:59]
	v_mfma_f32_16x16x32_bf16 v[48:51], v[146:149], v[196:199], v[48:51]
	v_mfma_f32_16x16x32_bf16 v[40:43], v[154:157], v[196:199], v[40:43]
	v_mfma_f32_16x16x32_bf16 v[32:35], v[146:149], v[204:207], v[32:35]
	v_mfma_f32_16x16x32_bf16 v[24:27], v[154:157], v[204:207], v[24:27]
	v_mfma_f32_16x16x32_bf16 v[16:19], v[146:149], v[212:215], v[16:19]
	v_mfma_f32_16x16x32_bf16 v[8:11], v[154:157], v[212:215], v[8:11]
	v_mfma_f32_16x16x32_bf16 v[60:63], v[168:171], v[184:187], v[60:63]
	v_mfma_f32_16x16x32_bf16 v[52:55], v[176:179], v[184:187], v[52:55]
	v_mfma_f32_16x16x32_bf16 v[44:47], v[168:171], v[192:195], v[44:47]
	v_mfma_f32_16x16x32_bf16 v[36:39], v[176:179], v[192:195], v[36:39]
	v_mfma_f32_16x16x32_bf16 v[28:31], v[168:171], v[200:203], v[28:31]
	v_mfma_f32_16x16x32_bf16 v[20:23], v[176:179], v[200:203], v[20:23]
	v_mfma_f32_16x16x32_bf16 v[12:15], v[168:171], v[208:211], v[12:15]
	v_mfma_f32_16x16x32_bf16 v[4:7], v[176:179], v[208:211], v[4:7]
	v_mfma_f32_16x16x32_bf16 v[60:63], v[172:175], v[188:191], v[60:63]
	v_mfma_f32_16x16x32_bf16 v[52:55], v[180:183], v[188:191], v[52:55]
	v_mfma_f32_16x16x32_bf16 v[44:47], v[172:175], v[196:199], v[44:47]
	v_mfma_f32_16x16x32_bf16 v[36:39], v[180:183], v[196:199], v[36:39]
	v_mfma_f32_16x16x32_bf16 v[28:31], v[172:175], v[204:207], v[28:31]
	v_mfma_f32_16x16x32_bf16 v[20:23], v[180:183], v[204:207], v[20:23]
	v_mfma_f32_16x16x32_bf16 v[12:15], v[172:175], v[212:215], v[12:15]
	v_mfma_f32_16x16x32_bf16 v[4:7], v[180:183], v[212:215], v[4:7]
	s_setprio 0
	s_barrier
	s_add_i32 s11, s11, 2
	s_add_u32 s9, s9, 0x100
	s_addc_u32 s10, s10, 0
	s_add_u32 s44, s44, 0x100
	s_addc_u32 s45, s45, 0
	s_cmp_gt_u32 s11, 29
.LBB0_1066:
	s_add_u32 s12, s44, 0xfff80080
	s_addc_u32 s13, s45, -1
	s_add_i32 s14, 0, 0x10000
	s_cmp_eq_u32 s11, 28
	s_cselect_b32 s49, s5, s13
	s_cselect_b32 s48, s6, s12
	s_cselect_b32 s47, s7, s10
	s_cselect_b32 s46, s8, s9
	s_add_i32 s15, 0, 0x14000
	v_add_u32_e32 v154, s14, v163
	v_add_u32_e32 v158, s15, v163
	ds_read_b128 v[142:145], v154
	ds_read_b128 v[146:149], v154 offset:1024
	ds_read_b128 v[150:153], v154 offset:2048
	ds_read_b128 v[154:157], v154 offset:3072
	ds_read_b128 v[168:171], v158
	ds_read_b128 v[172:175], v158 offset:1024
	ds_read_b128 v[176:179], v158 offset:2048
	ds_read_b128 v[180:183], v158 offset:3072
	s_add_i32 m0, s60, 0xc000
	ds_read_b128 v[184:187], v167
	ds_read_b128 v[188:191], v167 offset:1024
	ds_read_b128 v[192:195], v167 offset:2048
	ds_read_b128 v[196:199], v167 offset:3072
	ds_read_b128 v[200:203], v167 offset:4096
	ds_read_b128 v[204:207], v167 offset:5120
	ds_read_b128 v[208:211], v167 offset:6144
	ds_read_b128 v[212:215], v167 offset:7168
	global_load_lds_dwordx4 v140, s[44:45]
	s_add_i32 m0, s60, 0xe000
	s_nop 0
	global_load_lds_dwordx4 v138, s[44:45]
	s_waitcnt vmcnt(8)
	s_waitcnt lgkmcnt(0)
	s_barrier
	s_setprio 1
	v_mfma_f32_16x16x32_bf16 v[124:127], v[142:145], v[184:187], v[124:127]
	v_mfma_f32_16x16x32_bf16 v[120:123], v[150:153], v[184:187], v[120:123]
	v_mfma_f32_16x16x32_bf16 v[112:115], v[142:145], v[192:195], v[112:115]
	v_mfma_f32_16x16x32_bf16 v[104:107], v[150:153], v[192:195], v[104:107]
	v_mfma_f32_16x16x32_bf16 v[96:99], v[142:145], v[200:203], v[96:99]
	v_mfma_f32_16x16x32_bf16 v[88:91], v[150:153], v[200:203], v[88:91]
	v_mfma_f32_16x16x32_bf16 v[80:83], v[142:145], v[208:211], v[80:83]
	v_mfma_f32_16x16x32_bf16 v[72:75], v[150:153], v[208:211], v[72:75]
	v_mfma_f32_16x16x32_bf16 v[124:127], v[146:149], v[188:191], v[124:127]
	v_mfma_f32_16x16x32_bf16 v[120:123], v[154:157], v[188:191], v[120:123]
	v_mfma_f32_16x16x32_bf16 v[112:115], v[146:149], v[196:199], v[112:115]
	v_mfma_f32_16x16x32_bf16 v[104:107], v[154:157], v[196:199], v[104:107]
	v_mfma_f32_16x16x32_bf16 v[96:99], v[146:149], v[204:207], v[96:99]
	v_mfma_f32_16x16x32_bf16 v[88:91], v[154:157], v[204:207], v[88:91]
	v_mfma_f32_16x16x32_bf16 v[80:83], v[146:149], v[212:215], v[80:83]
	v_mfma_f32_16x16x32_bf16 v[72:75], v[154:157], v[212:215], v[72:75]
	v_mfma_f32_16x16x32_bf16 v[128:131], v[168:171], v[184:187], v[128:131]
	v_mfma_f32_16x16x32_bf16 v[116:119], v[176:179], v[184:187], v[116:119]
	v_mfma_f32_16x16x32_bf16 v[108:111], v[168:171], v[192:195], v[108:111]
	v_mfma_f32_16x16x32_bf16 v[100:103], v[176:179], v[192:195], v[100:103]
	v_mfma_f32_16x16x32_bf16 v[92:95], v[168:171], v[200:203], v[92:95]
	v_mfma_f32_16x16x32_bf16 v[84:87], v[176:179], v[200:203], v[84:87]
	v_mfma_f32_16x16x32_bf16 v[76:79], v[168:171], v[208:211], v[76:79]
	v_mfma_f32_16x16x32_bf16 v[68:71], v[176:179], v[208:211], v[68:71]
	v_mfma_f32_16x16x32_bf16 v[128:131], v[172:175], v[188:191], v[128:131]
	v_mfma_f32_16x16x32_bf16 v[116:119], v[180:183], v[188:191], v[116:119]
	v_mfma_f32_16x16x32_bf16 v[108:111], v[172:175], v[196:199], v[108:111]
	v_mfma_f32_16x16x32_bf16 v[100:103], v[180:183], v[196:199], v[100:103]
	v_mfma_f32_16x16x32_bf16 v[92:95], v[172:175], v[204:207], v[92:95]
	v_mfma_f32_16x16x32_bf16 v[84:87], v[180:183], v[204:207], v[84:87]
	v_mfma_f32_16x16x32_bf16 v[76:79], v[172:175], v[212:215], v[76:79]
	v_mfma_f32_16x16x32_bf16 v[68:71], v[180:183], v[212:215], v[68:71]
	s_setprio 0
	s_barrier
	s_add_i32 s12, s14, s56
	s_mov_b32 m0, s12
	ds_read_b128 v[184:187], v167 offset:16384
	ds_read_b128 v[188:191], v167 offset:17408
	ds_read_b128 v[192:195], v167 offset:18432
	ds_read_b128 v[196:199], v167 offset:19456
	ds_read_b128 v[200:203], v167 offset:20480
	ds_read_b128 v[204:207], v167 offset:21504
	ds_read_b128 v[208:211], v167 offset:22528
	ds_read_b128 v[212:215], v167 offset:23552
	global_load_lds_dwordx4 v2, s[46:47]
	s_add_i32 m0, s12, 0x2000
	s_add_u32 s12, s46, 0x80000
	s_addc_u32 s13, s47, 0
	s_add_i32 s14, s15, s56
	global_load_lds_dwordx4 v0, s[46:47]
	s_mov_b32 m0, s14
	s_nop 0
	global_load_lds_dwordx4 v2, s[12:13]
	s_add_i32 m0, s14, 0x2000
	s_nop 0
	global_load_lds_dwordx4 v0, s[12:13]
	s_mov_b32 m0, s60
	s_nop 0
	global_load_lds_dwordx4 v134, s[48:49]
	s_mov_b32 m0, s61
	s_nop 0
	global_load_lds_dwordx4 v132, s[48:49]
	s_waitcnt vmcnt(8)
	s_waitcnt lgkmcnt(0)
	s_barrier
	s_setprio 1
	v_mfma_f32_16x16x32_bf16 v[64:67], v[142:145], v[184:187], v[64:67]
	v_mfma_f32_16x16x32_bf16 v[56:59], v[150:153], v[184:187], v[56:59]
	v_mfma_f32_16x16x32_bf16 v[48:51], v[142:145], v[192:195], v[48:51]
	v_mfma_f32_16x16x32_bf16 v[40:43], v[150:153], v[192:195], v[40:43]
	v_mfma_f32_16x16x32_bf16 v[32:35], v[142:145], v[200:203], v[32:35]
	v_mfma_f32_16x16x32_bf16 v[24:27], v[150:153], v[200:203], v[24:27]
	v_mfma_f32_16x16x32_bf16 v[16:19], v[142:145], v[208:211], v[16:19]
	v_mfma_f32_16x16x32_bf16 v[8:11], v[150:153], v[208:211], v[8:11]
	v_mfma_f32_16x16x32_bf16 v[64:67], v[146:149], v[188:191], v[64:67]
	v_mfma_f32_16x16x32_bf16 v[56:59], v[154:157], v[188:191], v[56:59]
	v_mfma_f32_16x16x32_bf16 v[48:51], v[146:149], v[196:199], v[48:51]
	v_mfma_f32_16x16x32_bf16 v[40:43], v[154:157], v[196:199], v[40:43]
	v_mfma_f32_16x16x32_bf16 v[32:35], v[146:149], v[204:207], v[32:35]
	v_mfma_f32_16x16x32_bf16 v[24:27], v[154:157], v[204:207], v[24:27]
	v_mfma_f32_16x16x32_bf16 v[16:19], v[146:149], v[212:215], v[16:19]
	v_mfma_f32_16x16x32_bf16 v[8:11], v[154:157], v[212:215], v[8:11]
	v_mfma_f32_16x16x32_bf16 v[60:63], v[168:171], v[184:187], v[60:63]
	v_mfma_f32_16x16x32_bf16 v[52:55], v[176:179], v[184:187], v[52:55]
	v_mfma_f32_16x16x32_bf16 v[44:47], v[168:171], v[192:195], v[44:47]
	v_mfma_f32_16x16x32_bf16 v[36:39], v[176:179], v[192:195], v[36:39]
	v_mfma_f32_16x16x32_bf16 v[28:31], v[168:171], v[200:203], v[28:31]
	v_mfma_f32_16x16x32_bf16 v[20:23], v[176:179], v[200:203], v[20:23]
	v_mfma_f32_16x16x32_bf16 v[12:15], v[168:171], v[208:211], v[12:15]
	v_mfma_f32_16x16x32_bf16 v[4:7], v[176:179], v[208:211], v[4:7]
	v_mfma_f32_16x16x32_bf16 v[60:63], v[172:175], v[188:191], v[60:63]
	v_mfma_f32_16x16x32_bf16 v[52:55], v[180:183], v[188:191], v[52:55]
	v_mfma_f32_16x16x32_bf16 v[44:47], v[172:175], v[196:199], v[44:47]
	v_mfma_f32_16x16x32_bf16 v[36:39], v[180:183], v[196:199], v[36:39]
	v_mfma_f32_16x16x32_bf16 v[28:31], v[172:175], v[204:207], v[28:31]
	v_mfma_f32_16x16x32_bf16 v[20:23], v[180:183], v[204:207], v[20:23]
	v_mfma_f32_16x16x32_bf16 v[12:15], v[172:175], v[212:215], v[12:15]
	v_mfma_f32_16x16x32_bf16 v[4:7], v[180:183], v[212:215], v[4:7]
	s_setprio 0
	s_barrier
	s_add_i32 s14, 0, 0x18000
	s_add_i32 s15, 0, 0x1c000
	v_add_u32_e32 v154, s14, v163
	v_add_u32_e32 v160, s15, v163
	ds_read_b128 v[142:145], v154
	ds_read_b128 v[146:149], v154 offset:1024
	ds_read_b128 v[150:153], v154 offset:2048
	ds_read_b128 v[154:157], v154 offset:3072
	ds_read_b128 v[168:171], v160
	ds_read_b128 v[172:175], v160 offset:1024
	ds_read_b128 v[176:179], v160 offset:2048
	ds_read_b128 v[180:183], v160 offset:3072
	s_add_u32 s12, s48, 0x80000
	s_addc_u32 s13, s49, 0
	s_mov_b32 m0, s62
	ds_read_b128 v[184:187], v167 offset:32768
	ds_read_b128 v[188:191], v167 offset:33792
	ds_read_b128 v[192:195], v167 offset:34816
	ds_read_b128 v[196:199], v167 offset:35840
	ds_read_b128 v[200:203], v167 offset:36864
	ds_read_b128 v[204:207], v167 offset:37888
	ds_read_b128 v[208:211], v167 offset:38912
	ds_read_b128 v[212:215], v167 offset:39936
	global_load_lds_dwordx4 v134, s[12:13]
	s_mov_b32 m0, s63
	s_nop 0
	global_load_lds_dwordx4 v132, s[12:13]
	s_waitcnt vmcnt(8)
	s_waitcnt lgkmcnt(0)
	s_barrier
	s_setprio 1
	v_mfma_f32_16x16x32_bf16 v[124:127], v[142:145], v[184:187], v[124:127]
	v_mfma_f32_16x16x32_bf16 v[120:123], v[150:153], v[184:187], v[120:123]
	v_mfma_f32_16x16x32_bf16 v[112:115], v[142:145], v[192:195], v[112:115]
	v_mfma_f32_16x16x32_bf16 v[104:107], v[150:153], v[192:195], v[104:107]
	v_mfma_f32_16x16x32_bf16 v[96:99], v[142:145], v[200:203], v[96:99]
	v_mfma_f32_16x16x32_bf16 v[88:91], v[150:153], v[200:203], v[88:91]
	v_mfma_f32_16x16x32_bf16 v[80:83], v[142:145], v[208:211], v[80:83]
	v_mfma_f32_16x16x32_bf16 v[72:75], v[150:153], v[208:211], v[72:75]
	v_mfma_f32_16x16x32_bf16 v[124:127], v[146:149], v[188:191], v[124:127]
	v_mfma_f32_16x16x32_bf16 v[120:123], v[154:157], v[188:191], v[120:123]
	v_mfma_f32_16x16x32_bf16 v[112:115], v[146:149], v[196:199], v[112:115]
	v_mfma_f32_16x16x32_bf16 v[104:107], v[154:157], v[196:199], v[104:107]
	v_mfma_f32_16x16x32_bf16 v[96:99], v[146:149], v[204:207], v[96:99]
	v_mfma_f32_16x16x32_bf16 v[88:91], v[154:157], v[204:207], v[88:91]
	v_mfma_f32_16x16x32_bf16 v[80:83], v[146:149], v[212:215], v[80:83]
	v_mfma_f32_16x16x32_bf16 v[72:75], v[154:157], v[212:215], v[72:75]
	v_mfma_f32_16x16x32_bf16 v[128:131], v[168:171], v[184:187], v[128:131]
	v_mfma_f32_16x16x32_bf16 v[116:119], v[176:179], v[184:187], v[116:119]
	v_mfma_f32_16x16x32_bf16 v[108:111], v[168:171], v[192:195], v[108:111]
	v_mfma_f32_16x16x32_bf16 v[100:103], v[176:179], v[192:195], v[100:103]
	v_mfma_f32_16x16x32_bf16 v[92:95], v[168:171], v[200:203], v[92:95]
	v_mfma_f32_16x16x32_bf16 v[84:87], v[176:179], v[200:203], v[84:87]
	v_mfma_f32_16x16x32_bf16 v[76:79], v[168:171], v[208:211], v[76:79]
	v_mfma_f32_16x16x32_bf16 v[68:71], v[176:179], v[208:211], v[68:71]
	v_mfma_f32_16x16x32_bf16 v[128:131], v[172:175], v[188:191], v[128:131]
	v_mfma_f32_16x16x32_bf16 v[116:119], v[180:183], v[188:191], v[116:119]
	v_mfma_f32_16x16x32_bf16 v[108:111], v[172:175], v[196:199], v[108:111]
	v_mfma_f32_16x16x32_bf16 v[100:103], v[180:183], v[196:199], v[100:103]
	v_mfma_f32_16x16x32_bf16 v[92:95], v[172:175], v[204:207], v[92:95]
	v_mfma_f32_16x16x32_bf16 v[84:87], v[180:183], v[204:207], v[84:87]
	v_mfma_f32_16x16x32_bf16 v[76:79], v[172:175], v[212:215], v[76:79]
	v_mfma_f32_16x16x32_bf16 v[68:71], v[180:183], v[212:215], v[68:71]
	s_setprio 0
	s_barrier
	s_add_i32 s12, s14, s56
	s_mov_b32 m0, s12
	ds_read_b128 v[184:187], v167 offset:49152
	ds_read_b128 v[188:191], v167 offset:50176
	ds_read_b128 v[192:195], v167 offset:51200
	ds_read_b128 v[196:199], v167 offset:52224
	ds_read_b128 v[200:203], v167 offset:53248
	ds_read_b128 v[204:207], v167 offset:54272
	ds_read_b128 v[208:211], v167 offset:55296
	ds_read_b128 v[212:215], v167 offset:56320
	s_add_u32 s100, s46, 0x80
	s_addc_u32 s101, s47, 0
	global_load_lds_dwordx4 v2, s[100:101]
	s_add_i32 m0, s12, 0x2000
	s_add_u32 s12, s46, 0x80080
	s_addc_u32 s13, s47, 0
	s_add_i32 s14, s15, s56
	s_add_u32 s100, s46, 0x80
	s_addc_u32 s101, s47, 0
	global_load_lds_dwordx4 v0, s[100:101]
	s_mov_b32 m0, s14
	s_nop 0
	global_load_lds_dwordx4 v2, s[12:13]
	s_add_i32 m0, s14, 0x2000
	s_nop 0
	global_load_lds_dwordx4 v0, s[12:13]
	s_mov_b32 m0, s64
	s_nop 0
	s_add_u32 s100, s48, 0x80
	s_addc_u32 s101, s49, 0
	global_load_lds_dwordx4 v134, s[100:101]
	s_mov_b32 m0, s65
	s_nop 0
	s_add_u32 s100, s48, 0x80
	s_addc_u32 s101, s49, 0
	global_load_lds_dwordx4 v132, s[100:101]
	s_waitcnt vmcnt(8)
	s_waitcnt lgkmcnt(0)
	s_barrier
	s_setprio 1
	v_mfma_f32_16x16x32_bf16 v[64:67], v[142:145], v[184:187], v[64:67]
	v_mfma_f32_16x16x32_bf16 v[56:59], v[150:153], v[184:187], v[56:59]
	v_mfma_f32_16x16x32_bf16 v[48:51], v[142:145], v[192:195], v[48:51]
	v_mfma_f32_16x16x32_bf16 v[40:43], v[150:153], v[192:195], v[40:43]
	v_mfma_f32_16x16x32_bf16 v[32:35], v[142:145], v[200:203], v[32:35]
	v_mfma_f32_16x16x32_bf16 v[24:27], v[150:153], v[200:203], v[24:27]
	v_mfma_f32_16x16x32_bf16 v[16:19], v[142:145], v[208:211], v[16:19]
	v_mfma_f32_16x16x32_bf16 v[8:11], v[150:153], v[208:211], v[8:11]
	v_mfma_f32_16x16x32_bf16 v[64:67], v[146:149], v[188:191], v[64:67]
	v_mfma_f32_16x16x32_bf16 v[56:59], v[154:157], v[188:191], v[56:59]
	v_mfma_f32_16x16x32_bf16 v[48:51], v[146:149], v[196:199], v[48:51]
	v_mfma_f32_16x16x32_bf16 v[40:43], v[154:157], v[196:199], v[40:43]
	v_mfma_f32_16x16x32_bf16 v[32:35], v[146:149], v[204:207], v[32:35]
	v_mfma_f32_16x16x32_bf16 v[24:27], v[154:157], v[204:207], v[24:27]
	v_mfma_f32_16x16x32_bf16 v[16:19], v[146:149], v[212:215], v[16:19]
	v_mfma_f32_16x16x32_bf16 v[8:11], v[154:157], v[212:215], v[8:11]
	v_mfma_f32_16x16x32_bf16 v[60:63], v[168:171], v[184:187], v[60:63]
	v_mfma_f32_16x16x32_bf16 v[52:55], v[176:179], v[184:187], v[52:55]
	v_mfma_f32_16x16x32_bf16 v[44:47], v[168:171], v[192:195], v[44:47]
	v_mfma_f32_16x16x32_bf16 v[36:39], v[176:179], v[192:195], v[36:39]
	v_mfma_f32_16x16x32_bf16 v[28:31], v[168:171], v[200:203], v[28:31]
	v_mfma_f32_16x16x32_bf16 v[20:23], v[176:179], v[200:203], v[20:23]
	v_mfma_f32_16x16x32_bf16 v[12:15], v[168:171], v[208:211], v[12:15]
	v_mfma_f32_16x16x32_bf16 v[4:7], v[176:179], v[208:211], v[4:7]
	v_mfma_f32_16x16x32_bf16 v[60:63], v[172:175], v[188:191], v[60:63]
	v_mfma_f32_16x16x32_bf16 v[52:55], v[180:183], v[188:191], v[52:55]
	v_mfma_f32_16x16x32_bf16 v[44:47], v[172:175], v[196:199], v[44:47]
	v_mfma_f32_16x16x32_bf16 v[36:39], v[180:183], v[196:199], v[36:39]
	v_mfma_f32_16x16x32_bf16 v[28:31], v[172:175], v[204:207], v[28:31]
	v_mfma_f32_16x16x32_bf16 v[20:23], v[180:183], v[204:207], v[20:23]
	v_mfma_f32_16x16x32_bf16 v[12:15], v[172:175], v[212:215], v[12:15]
	v_mfma_f32_16x16x32_bf16 v[4:7], v[180:183], v[212:215], v[4:7]
	s_setprio 0
	s_barrier
	s_add_i32 s11, s11, 2
	s_add_u32 s9, s9, 0x100
	s_addc_u32 s10, s10, 0
	s_add_u32 s44, s44, 0x100
	s_addc_u32 s45, s45, 0
	s_cmp_gt_u32 s11, 29
	s_cbranch_scc0 .LBB0_1066
	s_and_b64 vcc, exec, s[22:23]
	s_cbranch_vccz .LBB0_1069
	s_nop 0

.LBB0_1133:
	s_add_u32 s5, s40, 0x100
	s_addc_u32 s6, s41, 0
	s_mov_b32 s7, -2
	s_waitcnt lgkmcnt(0)
	s_add_u32 s40, s38, 0x100
	s_addc_u32 s41, s39, 0
	s_add_i32 s8, 0, 0x10000
	s_cmpk_eq_i32 s7, 0x54
	s_cselect_b32 s45, s61, s41
	s_cselect_b32 s44, s60, s40
	s_cselect_b32 s43, s63, s6
	s_cselect_b32 s42, s62, s5
	s_add_i32 s10, 0, 0x14000
	v_add_u32_e32 v112, s8, v242
	v_add_u32_e32 v148, s10, v242
	ds_read_b128 v[92:95], v112
	ds_read_b128 v[100:103], v112 offset:1024
	ds_read_b128 v[108:111], v112 offset:2048
	ds_read_b128 v[112:115], v112 offset:3072
	ds_read_b128 v[116:119], v148
	ds_read_b128 v[128:131], v148 offset:1024
	ds_read_b128 v[140:143], v148 offset:2048
	ds_read_b128 v[148:151], v148 offset:3072
	v_lshl_add_u64 v[196:197], s[38:39], 0, v[222:223]
	s_add_i32 m0, s83, 0xc000
	ds_read_b128 v[160:163], v245
	ds_read_b128 v[168:171], v245 offset:1024
	ds_read_b128 v[172:175], v245 offset:2048
	ds_read_b128 v[176:179], v245 offset:3072
	ds_read_b128 v[180:183], v245 offset:4096
	ds_read_b128 v[184:187], v245 offset:5120
	ds_read_b128 v[188:191], v245 offset:6144
	ds_read_b128 v[192:195], v245 offset:7168
	global_load_lds_dwordx4 v[196:197], off
	v_lshl_add_u64 v[196:197], s[38:39], 0, v[220:221]
	s_add_i32 m0, s83, 0xe000
	s_nop 0
	global_load_lds_dwordx4 v[196:197], off
	s_waitcnt vmcnt(8)
	s_waitcnt lgkmcnt(0)
	s_barrier
	s_setprio 1
	v_mfma_f32_16x16x32_bf16 v[164:167], v[92:95], v[160:163], 0
	v_mfma_f32_16x16x32_bf16 v[156:159], v[108:111], v[160:163], 0
	v_mfma_f32_16x16x32_bf16 v[136:139], v[92:95], v[172:175], 0
	v_mfma_f32_16x16x32_bf16 v[132:135], v[108:111], v[172:175], 0
	v_mfma_f32_16x16x32_bf16 v[104:107], v[92:95], v[180:183], 0
	v_mfma_f32_16x16x32_bf16 v[96:99], v[108:111], v[180:183], 0
	v_mfma_f32_16x16x32_bf16 v[80:83], v[92:95], v[188:191], 0
	v_mfma_f32_16x16x32_bf16 v[76:79], v[108:111], v[188:191], 0
	v_mfma_f32_16x16x32_bf16 v[164:167], v[100:103], v[168:171], v[164:167]
	v_mfma_f32_16x16x32_bf16 v[156:159], v[112:115], v[168:171], v[156:159]
	v_mfma_f32_16x16x32_bf16 v[136:139], v[100:103], v[176:179], v[136:139]
	v_mfma_f32_16x16x32_bf16 v[132:135], v[112:115], v[176:179], v[132:135]
	v_mfma_f32_16x16x32_bf16 v[104:107], v[100:103], v[184:187], v[104:107]
	v_mfma_f32_16x16x32_bf16 v[96:99], v[112:115], v[184:187], v[96:99]
	v_mfma_f32_16x16x32_bf16 v[80:83], v[100:103], v[192:195], v[80:83]
	v_mfma_f32_16x16x32_bf16 v[76:79], v[112:115], v[192:195], v[76:79]
	s_setprio 0
	s_setprio 1
	v_mfma_f32_16x16x32_bf16 v[152:155], v[116:119], v[160:163], 0
	v_mfma_f32_16x16x32_bf16 v[144:147], v[140:143], v[160:163], 0
	v_mfma_f32_16x16x32_bf16 v[124:127], v[116:119], v[172:175], 0
	v_mfma_f32_16x16x32_bf16 v[120:123], v[140:143], v[172:175], 0
	v_mfma_f32_16x16x32_bf16 v[88:91], v[116:119], v[180:183], 0
	v_mfma_f32_16x16x32_bf16 v[84:87], v[140:143], v[180:183], 0
	v_mfma_f32_16x16x32_bf16 v[72:75], v[116:119], v[188:191], 0
	v_mfma_f32_16x16x32_bf16 v[68:71], v[140:143], v[188:191], 0
	v_mfma_f32_16x16x32_bf16 v[152:155], v[128:131], v[168:171], v[152:155]
	v_mfma_f32_16x16x32_bf16 v[144:147], v[148:151], v[168:171], v[144:147]
	v_mfma_f32_16x16x32_bf16 v[124:127], v[128:131], v[176:179], v[124:127]
	v_mfma_f32_16x16x32_bf16 v[120:123], v[148:151], v[176:179], v[120:123]
	v_mfma_f32_16x16x32_bf16 v[88:91], v[128:131], v[184:187], v[88:91]
	v_mfma_f32_16x16x32_bf16 v[84:87], v[148:151], v[184:187], v[84:87]
	v_mfma_f32_16x16x32_bf16 v[72:75], v[128:131], v[192:195], v[72:75]
	v_mfma_f32_16x16x32_bf16 v[68:71], v[148:151], v[192:195], v[68:71]
	s_setprio 0
	s_barrier
	s_add_i32 s8, s8, s82
	v_lshl_add_u64 v[196:197], s[42:43], 0, v[2:3]
	s_mov_b32 m0, s8
	ds_read_b128 v[160:163], v245 offset:16384
	ds_read_b128 v[168:171], v245 offset:17408
	ds_read_b128 v[172:175], v245 offset:18432
	ds_read_b128 v[176:179], v245 offset:19456
	ds_read_b128 v[180:183], v245 offset:20480
	ds_read_b128 v[184:187], v245 offset:21504
	ds_read_b128 v[188:191], v245 offset:22528
	ds_read_b128 v[192:195], v245 offset:23552
	global_load_lds_dwordx4 v[196:197], off
	s_add_i32 m0, s8, 0x2000
	s_add_u32 s8, s42, 0x160000
	v_lshl_add_u64 v[198:199], s[42:43], 0, v[218:219]
	s_addc_u32 s9, s43, 0
	s_add_i32 s10, s10, s82
	global_load_lds_dwordx4 v[198:199], off
	v_lshl_add_u64 v[200:201], s[8:9], 0, v[2:3]
	s_mov_b32 m0, s10
	v_lshl_add_u64 v[202:203], s[44:45], 0, v[216:217]
	global_load_lds_dwordx4 v[200:201], off
	v_lshl_add_u64 v[200:201], s[8:9], 0, v[218:219]
	s_add_i32 m0, s10, 0x2000
	s_nop 0
	global_load_lds_dwordx4 v[200:201], off
	v_lshl_add_u64 v[200:201], s[44:45], 0, v[0:1]
	s_mov_b32 m0, s83
	s_nop 0
	global_load_lds_dwordx4 v[200:201], off
	s_mov_b32 m0, s84
	s_nop 0
	global_load_lds_dwordx4 v[202:203], off
	s_waitcnt vmcnt(8)
	s_waitcnt lgkmcnt(0)
	s_barrier
	s_setprio 1
	v_mfma_f32_16x16x32_bf16 v[64:67], v[92:95], v[160:163], 0
	v_mfma_f32_16x16x32_bf16 v[60:63], v[108:111], v[160:163], 0
	v_mfma_f32_16x16x32_bf16 v[48:51], v[92:95], v[172:175], 0
	v_mfma_f32_16x16x32_bf16 v[44:47], v[108:111], v[172:175], 0
	v_mfma_f32_16x16x32_bf16 v[32:35], v[92:95], v[180:183], 0
	v_mfma_f32_16x16x32_bf16 v[28:31], v[108:111], v[180:183], 0
	v_mfma_f32_16x16x32_bf16 v[16:19], v[92:95], v[188:191], 0
	v_mfma_f32_16x16x32_bf16 v[12:15], v[108:111], v[188:191], 0
	v_mfma_f32_16x16x32_bf16 v[64:67], v[100:103], v[168:171], v[64:67]
	v_mfma_f32_16x16x32_bf16 v[60:63], v[112:115], v[168:171], v[60:63]
	v_mfma_f32_16x16x32_bf16 v[48:51], v[100:103], v[176:179], v[48:51]
	v_mfma_f32_16x16x32_bf16 v[44:47], v[112:115], v[176:179], v[44:47]
	v_mfma_f32_16x16x32_bf16 v[32:35], v[100:103], v[184:187], v[32:35]
	v_mfma_f32_16x16x32_bf16 v[28:31], v[112:115], v[184:187], v[28:31]
	v_mfma_f32_16x16x32_bf16 v[16:19], v[100:103], v[192:195], v[16:19]
	v_mfma_f32_16x16x32_bf16 v[12:15], v[112:115], v[192:195], v[12:15]
	s_setprio 0
	s_setprio 1
	v_mfma_f32_16x16x32_bf16 v[56:59], v[116:119], v[160:163], 0
	v_mfma_f32_16x16x32_bf16 v[52:55], v[140:143], v[160:163], 0
	v_mfma_f32_16x16x32_bf16 v[40:43], v[116:119], v[172:175], 0
	v_mfma_f32_16x16x32_bf16 v[36:39], v[140:143], v[172:175], 0
	v_mfma_f32_16x16x32_bf16 v[24:27], v[116:119], v[180:183], 0
	v_mfma_f32_16x16x32_bf16 v[20:23], v[140:143], v[180:183], 0
	v_mfma_f32_16x16x32_bf16 v[8:11], v[116:119], v[188:191], 0
	v_mfma_f32_16x16x32_bf16 v[4:7], v[140:143], v[188:191], 0
	v_mfma_f32_16x16x32_bf16 v[56:59], v[128:131], v[168:171], v[56:59]
	v_mfma_f32_16x16x32_bf16 v[52:55], v[148:151], v[168:171], v[52:55]
	v_mfma_f32_16x16x32_bf16 v[40:43], v[128:131], v[176:179], v[40:43]
	v_mfma_f32_16x16x32_bf16 v[36:39], v[148:151], v[176:179], v[36:39]
	v_mfma_f32_16x16x32_bf16 v[24:27], v[128:131], v[184:187], v[24:27]
	v_mfma_f32_16x16x32_bf16 v[20:23], v[148:151], v[184:187], v[20:23]
	v_mfma_f32_16x16x32_bf16 v[8:11], v[128:131], v[192:195], v[8:11]
	v_mfma_f32_16x16x32_bf16 v[4:7], v[148:151], v[192:195], v[4:7]
	s_setprio 0
	s_barrier
	s_add_i32 s10, 0, 0x18000
	s_add_i32 s11, 0, 0x1c000
	v_add_u32_e32 v112, s10, v242
	v_add_u32_e32 v148, s11, v242
	ds_read_b128 v[92:95], v112
	ds_read_b128 v[100:103], v112 offset:1024
	ds_read_b128 v[108:111], v112 offset:2048
	ds_read_b128 v[112:115], v112 offset:3072
	ds_read_b128 v[116:119], v148
	ds_read_b128 v[128:131], v148 offset:1024
	ds_read_b128 v[140:143], v148 offset:2048
	ds_read_b128 v[148:151], v148 offset:3072
	s_add_u32 s8, s44, 0x160000
	s_addc_u32 s9, s45, 0
	s_mov_b32 m0, s85
	v_lshl_add_u64 v[204:205], s[8:9], 0, v[0:1]
	ds_read_b128 v[160:163], v245 offset:32768
	ds_read_b128 v[168:171], v245 offset:33792
	ds_read_b128 v[172:175], v245 offset:34816
	ds_read_b128 v[176:179], v245 offset:35840
	ds_read_b128 v[180:183], v245 offset:36864
	ds_read_b128 v[184:187], v245 offset:37888
	ds_read_b128 v[188:191], v245 offset:38912
	ds_read_b128 v[192:195], v245 offset:39936
	global_load_lds_dwordx4 v[204:205], off
	v_lshl_add_u64 v[204:205], s[8:9], 0, v[216:217]
	s_mov_b32 m0, s87
	s_nop 0
	global_load_lds_dwordx4 v[204:205], off
	s_waitcnt vmcnt(8)
	s_waitcnt lgkmcnt(0)
	s_barrier
	s_setprio 1
	v_mfma_f32_16x16x32_bf16 v[164:167], v[92:95], v[160:163], v[164:167]
	v_mfma_f32_16x16x32_bf16 v[156:159], v[108:111], v[160:163], v[156:159]
	v_mfma_f32_16x16x32_bf16 v[136:139], v[92:95], v[172:175], v[136:139]
	v_mfma_f32_16x16x32_bf16 v[132:135], v[108:111], v[172:175], v[132:135]
	v_mfma_f32_16x16x32_bf16 v[104:107], v[92:95], v[180:183], v[104:107]
	v_mfma_f32_16x16x32_bf16 v[96:99], v[108:111], v[180:183], v[96:99]
	v_mfma_f32_16x16x32_bf16 v[80:83], v[92:95], v[188:191], v[80:83]
	v_mfma_f32_16x16x32_bf16 v[76:79], v[108:111], v[188:191], v[76:79]
	v_mfma_f32_16x16x32_bf16 v[164:167], v[100:103], v[168:171], v[164:167]
	v_mfma_f32_16x16x32_bf16 v[156:159], v[112:115], v[168:171], v[156:159]
	v_mfma_f32_16x16x32_bf16 v[136:139], v[100:103], v[176:179], v[136:139]
	v_mfma_f32_16x16x32_bf16 v[132:135], v[112:115], v[176:179], v[132:135]
	v_mfma_f32_16x16x32_bf16 v[104:107], v[100:103], v[184:187], v[104:107]
	v_mfma_f32_16x16x32_bf16 v[96:99], v[112:115], v[184:187], v[96:99]
	v_mfma_f32_16x16x32_bf16 v[80:83], v[100:103], v[192:195], v[80:83]
	v_mfma_f32_16x16x32_bf16 v[76:79], v[112:115], v[192:195], v[76:79]
	s_setprio 0
	s_setprio 1
	v_mfma_f32_16x16x32_bf16 v[152:155], v[116:119], v[160:163], v[152:155]
	v_mfma_f32_16x16x32_bf16 v[144:147], v[140:143], v[160:163], v[144:147]
	v_mfma_f32_16x16x32_bf16 v[124:127], v[116:119], v[172:175], v[124:127]
	v_mfma_f32_16x16x32_bf16 v[120:123], v[140:143], v[172:175], v[120:123]
	v_mfma_f32_16x16x32_bf16 v[88:91], v[116:119], v[180:183], v[88:91]
	v_mfma_f32_16x16x32_bf16 v[84:87], v[140:143], v[180:183], v[84:87]
	v_mfma_f32_16x16x32_bf16 v[72:75], v[116:119], v[188:191], v[72:75]
	v_mfma_f32_16x16x32_bf16 v[68:71], v[140:143], v[188:191], v[68:71]
	v_mfma_f32_16x16x32_bf16 v[152:155], v[128:131], v[168:171], v[152:155]
	v_mfma_f32_16x16x32_bf16 v[144:147], v[148:151], v[168:171], v[144:147]
	v_mfma_f32_16x16x32_bf16 v[124:127], v[128:131], v[176:179], v[124:127]
	v_mfma_f32_16x16x32_bf16 v[120:123], v[148:151], v[176:179], v[120:123]
	v_mfma_f32_16x16x32_bf16 v[88:91], v[128:131], v[184:187], v[88:91]
	v_mfma_f32_16x16x32_bf16 v[84:87], v[148:151], v[184:187], v[84:87]
	v_mfma_f32_16x16x32_bf16 v[72:75], v[128:131], v[192:195], v[72:75]
	v_mfma_f32_16x16x32_bf16 v[68:71], v[148:151], v[192:195], v[68:71]
	s_setprio 0
	s_barrier
	s_add_i32 s8, s10, s82
	v_lshl_add_u64 v[196:197], v[196:197], 0, s[68:69]
	s_mov_b32 m0, s8
	ds_read_b128 v[160:163], v245 offset:49152
	ds_read_b128 v[168:171], v245 offset:50176
	ds_read_b128 v[172:175], v245 offset:51200
	ds_read_b128 v[176:179], v245 offset:52224
	ds_read_b128 v[180:183], v245 offset:53248
	ds_read_b128 v[184:187], v245 offset:54272
	ds_read_b128 v[188:191], v245 offset:55296
	ds_read_b128 v[192:195], v245 offset:56320
	global_load_lds_dwordx4 v[196:197], off
	s_add_i32 m0, s8, 0x2000
	s_add_u32 s8, s42, 0x160080
	v_lshl_add_u64 v[196:197], v[198:199], 0, s[68:69]
	s_addc_u32 s9, s43, 0
	s_add_i32 s10, s11, s82
	global_load_lds_dwordx4 v[196:197], off
	v_lshl_add_u64 v[196:197], s[8:9], 0, v[2:3]
	s_mov_b32 m0, s10
	s_nop 0
	global_load_lds_dwordx4 v[196:197], off
	v_lshl_add_u64 v[196:197], s[8:9], 0, v[218:219]
	s_add_i32 m0, s10, 0x2000
	s_nop 0
	global_load_lds_dwordx4 v[196:197], off
	v_lshl_add_u64 v[196:197], v[200:201], 0, s[68:69]
	s_mov_b32 m0, s72
	s_nop 0
	global_load_lds_dwordx4 v[196:197], off
	v_lshl_add_u64 v[196:197], v[202:203], 0, s[68:69]
	s_mov_b32 m0, s88
	s_nop 0
	global_load_lds_dwordx4 v[196:197], off
	s_waitcnt vmcnt(8)
	s_waitcnt lgkmcnt(0)
	s_barrier
	s_setprio 1
	v_mfma_f32_16x16x32_bf16 v[64:67], v[92:95], v[160:163], v[64:67]
	v_mfma_f32_16x16x32_bf16 v[60:63], v[108:111], v[160:163], v[60:63]
	v_mfma_f32_16x16x32_bf16 v[48:51], v[92:95], v[172:175], v[48:51]
	v_mfma_f32_16x16x32_bf16 v[44:47], v[108:111], v[172:175], v[44:47]
	v_mfma_f32_16x16x32_bf16 v[32:35], v[92:95], v[180:183], v[32:35]
	v_mfma_f32_16x16x32_bf16 v[28:31], v[108:111], v[180:183], v[28:31]
	v_mfma_f32_16x16x32_bf16 v[16:19], v[92:95], v[188:191], v[16:19]
	v_mfma_f32_16x16x32_bf16 v[12:15], v[108:111], v[188:191], v[12:15]
	v_mfma_f32_16x16x32_bf16 v[64:67], v[100:103], v[168:171], v[64:67]
	v_mfma_f32_16x16x32_bf16 v[60:63], v[112:115], v[168:171], v[60:63]
	v_mfma_f32_16x16x32_bf16 v[48:51], v[100:103], v[176:179], v[48:51]
	v_mfma_f32_16x16x32_bf16 v[44:47], v[112:115], v[176:179], v[44:47]
	v_mfma_f32_16x16x32_bf16 v[32:35], v[100:103], v[184:187], v[32:35]
	v_mfma_f32_16x16x32_bf16 v[28:31], v[112:115], v[184:187], v[28:31]
	v_mfma_f32_16x16x32_bf16 v[16:19], v[100:103], v[192:195], v[16:19]
	v_mfma_f32_16x16x32_bf16 v[12:15], v[112:115], v[192:195], v[12:15]
	s_setprio 0
	s_setprio 1
	v_mfma_f32_16x16x32_bf16 v[56:59], v[116:119], v[160:163], v[56:59]
	v_mfma_f32_16x16x32_bf16 v[52:55], v[140:143], v[160:163], v[52:55]
	v_mfma_f32_16x16x32_bf16 v[40:43], v[116:119], v[172:175], v[40:43]
	v_mfma_f32_16x16x32_bf16 v[36:39], v[140:143], v[172:175], v[36:39]
	v_mfma_f32_16x16x32_bf16 v[24:27], v[116:119], v[180:183], v[24:27]
	v_mfma_f32_16x16x32_bf16 v[20:23], v[140:143], v[180:183], v[20:23]
	v_mfma_f32_16x16x32_bf16 v[8:11], v[116:119], v[188:191], v[8:11]
	v_mfma_f32_16x16x32_bf16 v[4:7], v[140:143], v[188:191], v[4:7]
	v_mfma_f32_16x16x32_bf16 v[56:59], v[128:131], v[168:171], v[56:59]
	v_mfma_f32_16x16x32_bf16 v[52:55], v[148:151], v[168:171], v[52:55]
	v_mfma_f32_16x16x32_bf16 v[40:43], v[128:131], v[176:179], v[40:43]
	v_mfma_f32_16x16x32_bf16 v[36:39], v[148:151], v[176:179], v[36:39]
	v_mfma_f32_16x16x32_bf16 v[24:27], v[128:131], v[184:187], v[24:27]
	v_mfma_f32_16x16x32_bf16 v[20:23], v[148:151], v[184:187], v[20:23]
	v_mfma_f32_16x16x32_bf16 v[8:11], v[128:131], v[192:195], v[8:11]
	v_mfma_f32_16x16x32_bf16 v[4:7], v[148:151], v[192:195], v[4:7]
	s_setprio 0
	s_barrier
	s_add_i32 s7, s7, 2
	s_add_u32 s5, s5, 0x100
	s_addc_u32 s6, s6, 0
	s_cmpk_gt_u32 s7, 0x55
	s_mov_b64 s[38:39], s[40:41]
.LBB0_1134:
	s_add_u32 s40, s38, 0x100
	s_addc_u32 s41, s39, 0
	s_add_i32 s8, 0, 0x10000
	s_cmpk_eq_i32 s7, 0x54
	s_cselect_b32 s45, s61, s41
	s_cselect_b32 s44, s60, s40
	s_cselect_b32 s43, s63, s6
	s_cselect_b32 s42, s62, s5
	s_add_i32 s10, 0, 0x14000
	v_add_u32_e32 v112, s8, v242
	v_add_u32_e32 v148, s10, v242
	ds_read_b128 v[92:95], v112
	ds_read_b128 v[100:103], v112 offset:1024
	ds_read_b128 v[108:111], v112 offset:2048
	ds_read_b128 v[112:115], v112 offset:3072
	ds_read_b128 v[116:119], v148
	ds_read_b128 v[128:131], v148 offset:1024
	ds_read_b128 v[140:143], v148 offset:2048
	ds_read_b128 v[148:151], v148 offset:3072
	v_lshl_add_u64 v[196:197], s[38:39], 0, v[222:223]
	s_add_i32 m0, s83, 0xc000
	ds_read_b128 v[160:163], v245
	ds_read_b128 v[168:171], v245 offset:1024
	ds_read_b128 v[172:175], v245 offset:2048
	ds_read_b128 v[176:179], v245 offset:3072
	ds_read_b128 v[180:183], v245 offset:4096
	ds_read_b128 v[184:187], v245 offset:5120
	ds_read_b128 v[188:191], v245 offset:6144
	ds_read_b128 v[192:195], v245 offset:7168
	global_load_lds_dwordx4 v[196:197], off
	v_lshl_add_u64 v[196:197], s[38:39], 0, v[220:221]
	s_add_i32 m0, s83, 0xe000
	s_nop 0
	global_load_lds_dwordx4 v[196:197], off
	s_waitcnt vmcnt(8)
	s_waitcnt lgkmcnt(0)
	s_barrier
	s_setprio 1
	v_mfma_f32_16x16x32_bf16 v[164:167], v[92:95], v[160:163], v[164:167]
	v_mfma_f32_16x16x32_bf16 v[156:159], v[108:111], v[160:163], v[156:159]
	v_mfma_f32_16x16x32_bf16 v[136:139], v[92:95], v[172:175], v[136:139]
	v_mfma_f32_16x16x32_bf16 v[132:135], v[108:111], v[172:175], v[132:135]
	v_mfma_f32_16x16x32_bf16 v[104:107], v[92:95], v[180:183], v[104:107]
	v_mfma_f32_16x16x32_bf16 v[96:99], v[108:111], v[180:183], v[96:99]
	v_mfma_f32_16x16x32_bf16 v[80:83], v[92:95], v[188:191], v[80:83]
	v_mfma_f32_16x16x32_bf16 v[76:79], v[108:111], v[188:191], v[76:79]
	v_mfma_f32_16x16x32_bf16 v[164:167], v[100:103], v[168:171], v[164:167]
	v_mfma_f32_16x16x32_bf16 v[156:159], v[112:115], v[168:171], v[156:159]
	v_mfma_f32_16x16x32_bf16 v[136:139], v[100:103], v[176:179], v[136:139]
	v_mfma_f32_16x16x32_bf16 v[132:135], v[112:115], v[176:179], v[132:135]
	v_mfma_f32_16x16x32_bf16 v[104:107], v[100:103], v[184:187], v[104:107]
	v_mfma_f32_16x16x32_bf16 v[96:99], v[112:115], v[184:187], v[96:99]
	v_mfma_f32_16x16x32_bf16 v[80:83], v[100:103], v[192:195], v[80:83]
	v_mfma_f32_16x16x32_bf16 v[76:79], v[112:115], v[192:195], v[76:79]
	s_setprio 0
	s_setprio 1
	v_mfma_f32_16x16x32_bf16 v[152:155], v[116:119], v[160:163], v[152:155]
	v_mfma_f32_16x16x32_bf16 v[144:147], v[140:143], v[160:163], v[144:147]
	v_mfma_f32_16x16x32_bf16 v[124:127], v[116:119], v[172:175], v[124:127]
	v_mfma_f32_16x16x32_bf16 v[120:123], v[140:143], v[172:175], v[120:123]
	v_mfma_f32_16x16x32_bf16 v[88:91], v[116:119], v[180:183], v[88:91]
	v_mfma_f32_16x16x32_bf16 v[84:87], v[140:143], v[180:183], v[84:87]
	v_mfma_f32_16x16x32_bf16 v[72:75], v[116:119], v[188:191], v[72:75]
	v_mfma_f32_16x16x32_bf16 v[68:71], v[140:143], v[188:191], v[68:71]
	v_mfma_f32_16x16x32_bf16 v[152:155], v[128:131], v[168:171], v[152:155]
	v_mfma_f32_16x16x32_bf16 v[144:147], v[148:151], v[168:171], v[144:147]
	v_mfma_f32_16x16x32_bf16 v[124:127], v[128:131], v[176:179], v[124:127]
	v_mfma_f32_16x16x32_bf16 v[120:123], v[148:151], v[176:179], v[120:123]
	v_mfma_f32_16x16x32_bf16 v[88:91], v[128:131], v[184:187], v[88:91]
	v_mfma_f32_16x16x32_bf16 v[84:87], v[148:151], v[184:187], v[84:87]
	v_mfma_f32_16x16x32_bf16 v[72:75], v[128:131], v[192:195], v[72:75]
	v_mfma_f32_16x16x32_bf16 v[68:71], v[148:151], v[192:195], v[68:71]
	s_setprio 0
	s_barrier
	s_add_i32 s8, s8, s82
	v_lshl_add_u64 v[196:197], s[42:43], 0, v[2:3]
	s_mov_b32 m0, s8
	ds_read_b128 v[160:163], v245 offset:16384
	ds_read_b128 v[168:171], v245 offset:17408
	ds_read_b128 v[172:175], v245 offset:18432
	ds_read_b128 v[176:179], v245 offset:19456
	ds_read_b128 v[180:183], v245 offset:20480
	ds_read_b128 v[184:187], v245 offset:21504
	ds_read_b128 v[188:191], v245 offset:22528
	ds_read_b128 v[192:195], v245 offset:23552
	global_load_lds_dwordx4 v[196:197], off
	s_add_i32 m0, s8, 0x2000
	s_add_u32 s8, s42, 0x160000
	v_lshl_add_u64 v[198:199], s[42:43], 0, v[218:219]
	s_addc_u32 s9, s43, 0
	s_add_i32 s10, s10, s82
	global_load_lds_dwordx4 v[198:199], off
	v_lshl_add_u64 v[200:201], s[8:9], 0, v[2:3]
	s_mov_b32 m0, s10
	v_lshl_add_u64 v[202:203], s[44:45], 0, v[216:217]
	global_load_lds_dwordx4 v[200:201], off
	v_lshl_add_u64 v[200:201], s[8:9], 0, v[218:219]
	s_add_i32 m0, s10, 0x2000
	s_nop 0
	global_load_lds_dwordx4 v[200:201], off
	v_lshl_add_u64 v[200:201], s[44:45], 0, v[0:1]
	s_mov_b32 m0, s83
	s_nop 0
	global_load_lds_dwordx4 v[200:201], off
	s_mov_b32 m0, s84
	s_nop 0
	global_load_lds_dwordx4 v[202:203], off
	s_waitcnt vmcnt(8)
	s_waitcnt lgkmcnt(0)
	s_barrier
	s_setprio 1
	v_mfma_f32_16x16x32_bf16 v[64:67], v[92:95], v[160:163], v[64:67]
	v_mfma_f32_16x16x32_bf16 v[60:63], v[108:111], v[160:163], v[60:63]
	v_mfma_f32_16x16x32_bf16 v[48:51], v[92:95], v[172:175], v[48:51]
	v_mfma_f32_16x16x32_bf16 v[44:47], v[108:111], v[172:175], v[44:47]
	v_mfma_f32_16x16x32_bf16 v[32:35], v[92:95], v[180:183], v[32:35]
	v_mfma_f32_16x16x32_bf16 v[28:31], v[108:111], v[180:183], v[28:31]
	v_mfma_f32_16x16x32_bf16 v[16:19], v[92:95], v[188:191], v[16:19]
	v_mfma_f32_16x16x32_bf16 v[12:15], v[108:111], v[188:191], v[12:15]
	v_mfma_f32_16x16x32_bf16 v[64:67], v[100:103], v[168:171], v[64:67]
	v_mfma_f32_16x16x32_bf16 v[60:63], v[112:115], v[168:171], v[60:63]
	v_mfma_f32_16x16x32_bf16 v[48:51], v[100:103], v[176:179], v[48:51]
	v_mfma_f32_16x16x32_bf16 v[44:47], v[112:115], v[176:179], v[44:47]
	v_mfma_f32_16x16x32_bf16 v[32:35], v[100:103], v[184:187], v[32:35]
	v_mfma_f32_16x16x32_bf16 v[28:31], v[112:115], v[184:187], v[28:31]
	v_mfma_f32_16x16x32_bf16 v[16:19], v[100:103], v[192:195], v[16:19]
	v_mfma_f32_16x16x32_bf16 v[12:15], v[112:115], v[192:195], v[12:15]
	s_setprio 0
	s_setprio 1
	v_mfma_f32_16x16x32_bf16 v[56:59], v[116:119], v[160:163], v[56:59]
	v_mfma_f32_16x16x32_bf16 v[52:55], v[140:143], v[160:163], v[52:55]
	v_mfma_f32_16x16x32_bf16 v[40:43], v[116:119], v[172:175], v[40:43]
	v_mfma_f32_16x16x32_bf16 v[36:39], v[140:143], v[172:175], v[36:39]
	v_mfma_f32_16x16x32_bf16 v[24:27], v[116:119], v[180:183], v[24:27]
	v_mfma_f32_16x16x32_bf16 v[20:23], v[140:143], v[180:183], v[20:23]
	v_mfma_f32_16x16x32_bf16 v[8:11], v[116:119], v[188:191], v[8:11]
	v_mfma_f32_16x16x32_bf16 v[4:7], v[140:143], v[188:191], v[4:7]
	v_mfma_f32_16x16x32_bf16 v[56:59], v[128:131], v[168:171], v[56:59]
	v_mfma_f32_16x16x32_bf16 v[52:55], v[148:151], v[168:171], v[52:55]
	v_mfma_f32_16x16x32_bf16 v[40:43], v[128:131], v[176:179], v[40:43]
	v_mfma_f32_16x16x32_bf16 v[36:39], v[148:151], v[176:179], v[36:39]
	v_mfma_f32_16x16x32_bf16 v[24:27], v[128:131], v[184:187], v[24:27]
	v_mfma_f32_16x16x32_bf16 v[20:23], v[148:151], v[184:187], v[20:23]
	v_mfma_f32_16x16x32_bf16 v[8:11], v[128:131], v[192:195], v[8:11]
	v_mfma_f32_16x16x32_bf16 v[4:7], v[148:151], v[192:195], v[4:7]
	s_setprio 0
	s_barrier
	s_add_i32 s10, 0, 0x18000
	s_add_i32 s11, 0, 0x1c000
	v_add_u32_e32 v112, s10, v242
	v_add_u32_e32 v148, s11, v242
	ds_read_b128 v[92:95], v112
	ds_read_b128 v[100:103], v112 offset:1024
	ds_read_b128 v[108:111], v112 offset:2048
	ds_read_b128 v[112:115], v112 offset:3072
	ds_read_b128 v[116:119], v148
	ds_read_b128 v[128:131], v148 offset:1024
	ds_read_b128 v[140:143], v148 offset:2048
	ds_read_b128 v[148:151], v148 offset:3072
	s_add_u32 s8, s44, 0x160000
	s_addc_u32 s9, s45, 0
	s_mov_b32 m0, s85
	v_lshl_add_u64 v[204:205], s[8:9], 0, v[0:1]
	ds_read_b128 v[160:163], v245 offset:32768
	ds_read_b128 v[168:171], v245 offset:33792
	ds_read_b128 v[172:175], v245 offset:34816
	ds_read_b128 v[176:179], v245 offset:35840
	ds_read_b128 v[180:183], v245 offset:36864
	ds_read_b128 v[184:187], v245 offset:37888
	ds_read_b128 v[188:191], v245 offset:38912
	ds_read_b128 v[192:195], v245 offset:39936
	global_load_lds_dwordx4 v[204:205], off
	v_lshl_add_u64 v[204:205], s[8:9], 0, v[216:217]
	s_mov_b32 m0, s87
	s_nop 0
	global_load_lds_dwordx4 v[204:205], off
	s_waitcnt vmcnt(8)
	s_waitcnt lgkmcnt(0)
	s_barrier
	s_setprio 1
	v_mfma_f32_16x16x32_bf16 v[164:167], v[92:95], v[160:163], v[164:167]
	v_mfma_f32_16x16x32_bf16 v[156:159], v[108:111], v[160:163], v[156:159]
	v_mfma_f32_16x16x32_bf16 v[136:139], v[92:95], v[172:175], v[136:139]
	v_mfma_f32_16x16x32_bf16 v[132:135], v[108:111], v[172:175], v[132:135]
	v_mfma_f32_16x16x32_bf16 v[104:107], v[92:95], v[180:183], v[104:107]
	v_mfma_f32_16x16x32_bf16 v[96:99], v[108:111], v[180:183], v[96:99]
	v_mfma_f32_16x16x32_bf16 v[80:83], v[92:95], v[188:191], v[80:83]
	v_mfma_f32_16x16x32_bf16 v[76:79], v[108:111], v[188:191], v[76:79]
	v_mfma_f32_16x16x32_bf16 v[164:167], v[100:103], v[168:171], v[164:167]
	v_mfma_f32_16x16x32_bf16 v[156:159], v[112:115], v[168:171], v[156:159]
	v_mfma_f32_16x16x32_bf16 v[136:139], v[100:103], v[176:179], v[136:139]
	v_mfma_f32_16x16x32_bf16 v[132:135], v[112:115], v[176:179], v[132:135]
	v_mfma_f32_16x16x32_bf16 v[104:107], v[100:103], v[184:187], v[104:107]
	v_mfma_f32_16x16x32_bf16 v[96:99], v[112:115], v[184:187], v[96:99]
	v_mfma_f32_16x16x32_bf16 v[80:83], v[100:103], v[192:195], v[80:83]
	v_mfma_f32_16x16x32_bf16 v[76:79], v[112:115], v[192:195], v[76:79]
	s_setprio 0
	s_setprio 1
	v_mfma_f32_16x16x32_bf16 v[152:155], v[116:119], v[160:163], v[152:155]
	v_mfma_f32_16x16x32_bf16 v[144:147], v[140:143], v[160:163], v[144:147]
	v_mfma_f32_16x16x32_bf16 v[124:127], v[116:119], v[172:175], v[124:127]
	v_mfma_f32_16x16x32_bf16 v[120:123], v[140:143], v[172:175], v[120:123]
	v_mfma_f32_16x16x32_bf16 v[88:91], v[116:119], v[180:183], v[88:91]
	v_mfma_f32_16x16x32_bf16 v[84:87], v[140:143], v[180:183], v[84:87]
	v_mfma_f32_16x16x32_bf16 v[72:75], v[116:119], v[188:191], v[72:75]
	v_mfma_f32_16x16x32_bf16 v[68:71], v[140:143], v[188:191], v[68:71]
	v_mfma_f32_16x16x32_bf16 v[152:155], v[128:131], v[168:171], v[152:155]
	v_mfma_f32_16x16x32_bf16 v[144:147], v[148:151], v[168:171], v[144:147]
	v_mfma_f32_16x16x32_bf16 v[124:127], v[128:131], v[176:179], v[124:127]
	v_mfma_f32_16x16x32_bf16 v[120:123], v[148:151], v[176:179], v[120:123]
	v_mfma_f32_16x16x32_bf16 v[88:91], v[128:131], v[184:187], v[88:91]
	v_mfma_f32_16x16x32_bf16 v[84:87], v[148:151], v[184:187], v[84:87]
	v_mfma_f32_16x16x32_bf16 v[72:75], v[128:131], v[192:195], v[72:75]
	v_mfma_f32_16x16x32_bf16 v[68:71], v[148:151], v[192:195], v[68:71]
	s_setprio 0
	s_barrier
	s_add_i32 s8, s10, s82
	v_lshl_add_u64 v[196:197], v[196:197], 0, s[68:69]
	s_mov_b32 m0, s8
	ds_read_b128 v[160:163], v245 offset:49152
	ds_read_b128 v[168:171], v245 offset:50176
	ds_read_b128 v[172:175], v245 offset:51200
	ds_read_b128 v[176:179], v245 offset:52224
	ds_read_b128 v[180:183], v245 offset:53248
	ds_read_b128 v[184:187], v245 offset:54272
	ds_read_b128 v[188:191], v245 offset:55296
	ds_read_b128 v[192:195], v245 offset:56320
	global_load_lds_dwordx4 v[196:197], off
	s_add_i32 m0, s8, 0x2000
	s_add_u32 s8, s42, 0x160080
	v_lshl_add_u64 v[196:197], v[198:199], 0, s[68:69]
	s_addc_u32 s9, s43, 0
	s_add_i32 s10, s11, s82
	global_load_lds_dwordx4 v[196:197], off
	v_lshl_add_u64 v[196:197], s[8:9], 0, v[2:3]
	s_mov_b32 m0, s10
	s_nop 0
	global_load_lds_dwordx4 v[196:197], off
	v_lshl_add_u64 v[196:197], s[8:9], 0, v[218:219]
	s_add_i32 m0, s10, 0x2000
	s_nop 0
	global_load_lds_dwordx4 v[196:197], off
	v_lshl_add_u64 v[196:197], v[200:201], 0, s[68:69]
	s_mov_b32 m0, s72
	s_nop 0
	global_load_lds_dwordx4 v[196:197], off
	v_lshl_add_u64 v[196:197], v[202:203], 0, s[68:69]
	s_mov_b32 m0, s88
	s_nop 0
	global_load_lds_dwordx4 v[196:197], off
	s_waitcnt vmcnt(8)
	s_waitcnt lgkmcnt(0)
	s_barrier
	s_setprio 1
	v_mfma_f32_16x16x32_bf16 v[64:67], v[92:95], v[160:163], v[64:67]
	v_mfma_f32_16x16x32_bf16 v[60:63], v[108:111], v[160:163], v[60:63]
	v_mfma_f32_16x16x32_bf16 v[48:51], v[92:95], v[172:175], v[48:51]
	v_mfma_f32_16x16x32_bf16 v[44:47], v[108:111], v[172:175], v[44:47]
	v_mfma_f32_16x16x32_bf16 v[32:35], v[92:95], v[180:183], v[32:35]
	v_mfma_f32_16x16x32_bf16 v[28:31], v[108:111], v[180:183], v[28:31]
	v_mfma_f32_16x16x32_bf16 v[16:19], v[92:95], v[188:191], v[16:19]
	v_mfma_f32_16x16x32_bf16 v[12:15], v[108:111], v[188:191], v[12:15]
	v_mfma_f32_16x16x32_bf16 v[64:67], v[100:103], v[168:171], v[64:67]
	v_mfma_f32_16x16x32_bf16 v[60:63], v[112:115], v[168:171], v[60:63]
	v_mfma_f32_16x16x32_bf16 v[48:51], v[100:103], v[176:179], v[48:51]
	v_mfma_f32_16x16x32_bf16 v[44:47], v[112:115], v[176:179], v[44:47]
	v_mfma_f32_16x16x32_bf16 v[32:35], v[100:103], v[184:187], v[32:35]
	v_mfma_f32_16x16x32_bf16 v[28:31], v[112:115], v[184:187], v[28:31]
	v_mfma_f32_16x16x32_bf16 v[16:19], v[100:103], v[192:195], v[16:19]
	v_mfma_f32_16x16x32_bf16 v[12:15], v[112:115], v[192:195], v[12:15]
	s_setprio 0
	s_setprio 1
	v_mfma_f32_16x16x32_bf16 v[56:59], v[116:119], v[160:163], v[56:59]
	v_mfma_f32_16x16x32_bf16 v[52:55], v[140:143], v[160:163], v[52:55]
	v_mfma_f32_16x16x32_bf16 v[40:43], v[116:119], v[172:175], v[40:43]
	v_mfma_f32_16x16x32_bf16 v[36:39], v[140:143], v[172:175], v[36:39]
	v_mfma_f32_16x16x32_bf16 v[24:27], v[116:119], v[180:183], v[24:27]
	v_mfma_f32_16x16x32_bf16 v[20:23], v[140:143], v[180:183], v[20:23]
	v_mfma_f32_16x16x32_bf16 v[8:11], v[116:119], v[188:191], v[8:11]
	v_mfma_f32_16x16x32_bf16 v[4:7], v[140:143], v[188:191], v[4:7]
	v_mfma_f32_16x16x32_bf16 v[56:59], v[128:131], v[168:171], v[56:59]
	v_mfma_f32_16x16x32_bf16 v[52:55], v[148:151], v[168:171], v[52:55]
	v_mfma_f32_16x16x32_bf16 v[40:43], v[128:131], v[176:179], v[40:43]
	v_mfma_f32_16x16x32_bf16 v[36:39], v[148:151], v[176:179], v[36:39]
	v_mfma_f32_16x16x32_bf16 v[24:27], v[128:131], v[184:187], v[24:27]
	v_mfma_f32_16x16x32_bf16 v[20:23], v[148:151], v[184:187], v[20:23]
	v_mfma_f32_16x16x32_bf16 v[8:11], v[128:131], v[192:195], v[8:11]
	v_mfma_f32_16x16x32_bf16 v[4:7], v[148:151], v[192:195], v[4:7]
	s_setprio 0
	s_barrier
	s_add_i32 s7, s7, 2
	s_add_u32 s5, s5, 0x100
	s_addc_u32 s6, s6, 0
	s_cmpk_gt_u32 s7, 0x55
	s_mov_b64 s[38:39], s[40:41]
	s_cbranch_scc0 .LBB0_1134
	s_and_b64 vcc, exec, s[52:53]
	s_cbranch_vccz .LBB0_1137
	s_barrier
